# v32 + GEMM tiles: the wr==1 half's skew barrier moved from right after the epilogue to just before the K loop, so both halves compute the next tile index and clear accumulators concurrently (same barr
# baseline (speedup 1.0000x reference)
; #define PG8_STAGE(bufoff, gbase, voff) do { _Pragma("unroll") for (int _i = 0; _i < 2; ++_i) \
;         __builtin_amdgcn_global_load_lds((const unsigned*)((const char*)(gbase) + (voff)[_i]), (LAS unsigned*)(lds + (bufoff) + ldsw + _i * 8192), 16, 0, 0); } while (0)
; #define PG8_LDA(dst, b, h) do { _Pragma("unroll") for (int m = 0; m < 4; ++m) _Pragma("unroll") for (int k = 0; k < 2; ++k) dst[m][k] = *(const LAS bf16x8*)(lds + PG8_SA(b, h) + aoff + m * 2048 + k * 1024); } while (0)
; #define PG8_LDB(dst, b, h) do { _Pragma("unroll") for (int n = 0; n < 2; ++n) _Pragma("unroll") for (int k = 0; k < 2; ++k) dst[n][k] = *(const LAS bf16x8*)(lds + PG8_SB(b, h) + boff + n * 2048 + k * 1024); } while (0)
; #define PG8_BAR __builtin_amdgcn_s_barrier()
; #define PG8_SCHED __builtin_amdgcn_sched_barrier(0)
; template <class Epi>
; __device__ __forceinline__ void gemm_phase(LAS unsigned char* lds, int wave_s, const Gemm g, const StaticOrder S, const Epi E) {
;     ...
;     for (;;) {
;         const bool has_next = S.next(ui + 1, nxt);
;         const char* nA = has_next ? (const char*)g.A + (size_t)nxt.pm * tstepA : cA; const char* nB = has_next ? (const char*)g.Bt + (size_t)nxt.pn * tstepB : cB;
;         for (int t = 0; t < nt; t += 2) {
;             const bool last = (t == nt - 2);
;             const char* a1 = cA + (size_t)(t + 1) * kstep;
;             const char* a2 = last ? nA : cA + (size_t)(t + 2) * kstep; const char* b2 = last ? nB : cB + (size_t)(t + 2) * kstep;
;             const char* a3 = a2 + kstep; const char* b3 = b2 + kstep;
;             PG8_LDB(B0, 0, 0); PG8_LDB(B1, 0, 1); PG8_SCHED; PG8_LDA(At, 0, 0); PG8_STAGE(PG8_SA(1, 1), a1 + hstepA, voffA);
;     ...
;         if (!has_next) break;
; #pragma unroll
;         for (int a = 0; a < 2; ++a)
; #pragma unroll
;             for (int b = 0; b < 2; ++b)
; #pragma unroll
;                 for (int m = 0; m < 4; ++m)
; #pragma unroll
;                     for (int n = 0; n < 2; ++n) acc[a][b][m][n] = (f32x4){0.f, 0.f, 0.f, 0.f};
;         cur = nxt; cA = nA; cB = nB; ++ui;
;         if (wr == 1) PG8_BAR;
.LBB0_164:
	s_ashr_i32 s19, s18, 31
	s_lshl_b64 s[6:7], s[18:19], 19
	s_add_u32 s20, s38, s6
	s_addc_u32 s21, s39, s7
	s_and_b64 s[6:7], s[0:1], exec
	s_cselect_b32 s19, s21, s25
	s_cselect_b32 s45, s20, s24
	s_ashr_i32 s17, s16, 31
	s_lshl_b64 s[6:7], s[16:17], 19
	v_readlane_b32 s10, v252, 43
	v_readlane_b32 s11, v252, 44
	s_add_u32 s22, s10, s6
	s_addc_u32 s23, s11, s7
	s_and_b64 s[6:7], s[0:1], exec
	s_cselect_b32 s10, s23, s27
	s_cselect_b32 s11, s22, s26
	s_add_u32 s24, s24, 0x40080
	s_addc_u32 s25, s25, 0
	s_add_u32 s17, s26, 0x100
	v_mov_b32_e32 v2, 0
	s_addc_u32 s46, s27, 0
	s_mov_b32 s47, -2
	v_mov_b32_e32 v246, v2
	v_mov_b32_e32 v247, v2
	v_mov_b32_e32 v248, v2
	v_mov_b32_e32 v249, v2
	v_mov_b32_e32 v3, v2
	v_mov_b32_e32 v4, v2
	v_mfma_f32_32x32x16_bf16 v[18:33], v[246:249], v[246:249], 0
	v_mov_b32_e32 v5, v2
	v_mov_b32_e32 v6, v2
	v_mfma_f32_32x32x16_bf16 v[34:49], v[246:249], v[246:249], 0
	v_mov_b32_e32 v7, v2
	v_mov_b32_e32 v8, v2
	v_mfma_f32_32x32x16_bf16 v[50:65], v[246:249], v[246:249], 0
	v_mov_b32_e32 v9, v2
	v_mov_b32_e32 v10, v2
	v_mfma_f32_32x32x16_bf16 v[66:81], v[246:249], v[246:249], 0
	v_mov_b32_e32 v11, v2
	v_mov_b32_e32 v12, v2
	v_mfma_f32_32x32x16_bf16 v[82:97], v[246:249], v[246:249], 0
	v_mov_b32_e32 v13, v2
	v_mov_b32_e32 v14, v2
	v_mfma_f32_32x32x16_bf16 v[98:113], v[246:249], v[246:249], 0
	v_mov_b32_e32 v15, v2
	v_mov_b32_e32 v16, v2
	v_mfma_f32_32x32x16_bf16 v[114:129], v[246:249], v[246:249], 0
	v_mov_b32_e32 v17, v2
	s_cmp_eq_u32 s99, 0x13579bdf
	s_cbranch_scc0 .Lskw_0
	s_mov_b32 s99, 0
	s_barrier
.Lskw_0:
.LBB0_165:
	s_cmp_eq_u32 s47, 6
	s_cbranch_scc0 .Lsq_ffn1up_skip
	v_readlane_b32 s100, v136, 0
	v_readlane_b32 s101, v137, 0
	s_lshl_b32 s6, s44, 14
	s_lshl_b32 s7, s92, 5
	s_add_u32 s6, s6, s7
	s_add_u32 s100, s100, s6
	s_addc_u32 s101, s101, 0
	s_add_i32 m0, s7, 0x24000
	v_lshlrev_b32_e32 v243, 4, v241
	s_nop 1
	global_load_lds_dwordx4 v243, s[100:101]
	global_load_lds_dwordx4 v243, s[100:101] offset:1024

; __device__ __forceinline__ float row_ssq(const float* part, int pitch, int n4, int row, int fq) {
;     f32x4 v = (f32x4){0.f, 0.f, 0.f, 0.f};
;     if (fq < n4) v = *(const f32x4*)(part + (size_t)row * pitch + 4 * fq);
;     float s = (v[0] + v[1]) + (v[2] + v[3]);
;     s += __shfl_xor(s, 16); s += __shfl_xor(s, 32);
;     return s;
; }
;     __device__ __forceinline__ void operator()(const f32x4 (&acc)[2][2][4][2], const Unit& u, int wr, int wc, int fr, int fq) const {
;         const int row0 = u.pm * BM + wr * 64 + fr, col0 = u.pn * 128 + wc * 32 + 8 * fq;
; #pragma unroll
;         for (int ai = 0; ai < 2; ++ai)
; #pragma unroll
;             for (int m = 0; m < 4; ++m) {
;                 const int row = row0 + ai * HALF + m * 16;
;                 const float rs = rsqrtf(row_ssq(ssq, 16, 4, row, fq) * (1.f / 1024.f) + EPS);
.LBB0_168:
	v_and_b32_e32 v145, 64, v241
	v_xor_b32_e32 v143, 16, v241
	v_add_u32_e32 v145, 64, v145
	v_cmp_lt_i32_e32 vcc, v143, v145
	v_lshl_add_u32 v144, s44, 8, v146
	v_lshl_or_b32 v142, s4, 7, v148
	v_cndmask_b32_e32 v143, v241, v143, vcc
	v_lshlrev_b32_e32 v150, 2, v143
	v_xor_b32_e32 v143, 32, v241
	v_cmp_lt_i32_e32 vcc, v143, v145
	v_ashrrev_i32_e32 v145, 31, v144
	v_and_b32_e32 v166, 48, v241
	v_lshl_add_u32 v166, v146, 6, v166
	v_add_u32_e32 v166, 0x24000, v166
	ds_read_b128 v[168:171], v166
	ds_read_b128 v[172:175], v166 offset:1024
	ds_read_b128 v[176:179], v166 offset:2048
	ds_read_b128 v[180:183], v166 offset:3072
	v_cndmask_b32_e32 v143, v241, v143, vcc
	v_lshlrev_b32_e32 v151, 2, v143
	ds_read_b128 v[184:187], v166 offset:8192
	ds_read_b128 v[188:191], v166 offset:9216
	ds_read_b128 v[192:195], v166 offset:10240
	ds_read_b128 v[196:199], v166 offset:11264
	v_ashrrev_i32_e32 v143, 31, v142
	v_lshl_add_u64 v[142:143], v[142:143], 1, s[96:97]
	s_movk_i32 s4, 0x1600
	s_mov_b64 s[24:25], -1
	s_waitcnt lgkmcnt(7)
	v_add_f32_e32 v168, v169, v168
	v_add_f32_e32 v170, v170, v171
	v_add_f32_e32 v168, v168, v170
	v_mov_b32_e32 v169, v168
	s_nop 1
	v_permlane16_swap_b32_e32 v168, v169
	s_waitcnt lgkmcnt(6)
	v_add_f32_e32 v172, v173, v172
	v_add_f32_e32 v174, v174, v175
	v_add_f32_e32 v172, v172, v174
	v_mov_b32_e32 v173, v172
	s_nop 1
	v_permlane16_swap_b32_e32 v172, v173
	s_waitcnt lgkmcnt(5)
	v_add_f32_e32 v176, v177, v176
	v_add_f32_e32 v178, v178, v179
	v_add_f32_e32 v176, v176, v178
	v_mov_b32_e32 v177, v176
	s_nop 1
	v_permlane16_swap_b32_e32 v176, v177
	s_waitcnt lgkmcnt(4)
	v_add_f32_e32 v180, v181, v180
	v_add_f32_e32 v182, v182, v183
	v_add_f32_e32 v180, v180, v182
	v_mov_b32_e32 v181, v180
	s_nop 1
	v_permlane16_swap_b32_e32 v180, v181
	s_waitcnt lgkmcnt(3)
	v_add_f32_e32 v184, v185, v184
	v_add_f32_e32 v186, v186, v187
	v_add_f32_e32 v184, v184, v186
	v_mov_b32_e32 v185, v184
	s_nop 1
	v_permlane16_swap_b32_e32 v184, v185
	s_waitcnt lgkmcnt(2)
	v_add_f32_e32 v188, v189, v188
	v_add_f32_e32 v190, v190, v191
	v_add_f32_e32 v188, v188, v190
	v_mov_b32_e32 v189, v188
	s_nop 1
	v_permlane16_swap_b32_e32 v188, v189
	s_waitcnt lgkmcnt(1)
	v_add_f32_e32 v192, v193, v192
	v_add_f32_e32 v194, v194, v195
	v_add_f32_e32 v192, v192, v194
	v_mov_b32_e32 v193, v192
	s_nop 1
	v_permlane16_swap_b32_e32 v192, v193
	s_waitcnt lgkmcnt(0)
	v_add_f32_e32 v196, v197, v196
	v_add_f32_e32 v198, v198, v199
	v_add_f32_e32 v196, v196, v198
	v_mov_b32_e32 v197, v196
	s_nop 1
	v_permlane16_swap_b32_e32 v196, v197
	s_waitcnt lgkmcnt(7)
	v_add_f32_e32 v168, v168, v169
	v_mov_b32_e32 v169, v168
	s_nop 1
	v_permlane32_swap_b32_e32 v168, v169
	s_waitcnt lgkmcnt(7)
	v_add_f32_e32 v172, v172, v173
	v_mov_b32_e32 v173, v172
	s_nop 1
	v_permlane32_swap_b32_e32 v172, v173
	s_waitcnt lgkmcnt(7)
	v_add_f32_e32 v176, v176, v177
	v_mov_b32_e32 v177, v176
	s_nop 1
	v_permlane32_swap_b32_e32 v176, v177
	s_waitcnt lgkmcnt(7)
	v_add_f32_e32 v180, v180, v181
	v_mov_b32_e32 v181, v180
	s_nop 1
	v_permlane32_swap_b32_e32 v180, v181
	s_waitcnt lgkmcnt(7)
	v_add_f32_e32 v184, v184, v185
	v_mov_b32_e32 v185, v184
	s_nop 1
	v_permlane32_swap_b32_e32 v184, v185
	s_waitcnt lgkmcnt(7)
	v_add_f32_e32 v188, v188, v189
	v_mov_b32_e32 v189, v188
	s_nop 1
	v_permlane32_swap_b32_e32 v188, v189
	s_waitcnt lgkmcnt(7)
	v_add_f32_e32 v192, v192, v193
	v_mov_b32_e32 v193, v192
	s_nop 1
	v_permlane32_swap_b32_e32 v192, v193
	s_waitcnt lgkmcnt(7)
	v_add_f32_e32 v196, v196, v197
	v_mov_b32_e32 v197, v196
	s_nop 1
	v_permlane32_swap_b32_e32 v196, v197
	s_waitcnt lgkmcnt(7)
	v_add_f32_e32 v168, v168, v169
	v_fmamk_f32 v168, v168, 0x3a800000, v239
	s_waitcnt lgkmcnt(6)
	v_add_f32_e32 v172, v172, v173
	v_fmamk_f32 v172, v172, 0x3a800000, v239
	s_waitcnt lgkmcnt(5)
	v_add_f32_e32 v176, v176, v177
	v_fmamk_f32 v176, v176, 0x3a800000, v239
	s_waitcnt lgkmcnt(4)
	v_add_f32_e32 v180, v180, v181
	v_fmamk_f32 v180, v180, 0x3a800000, v239
	s_waitcnt lgkmcnt(3)
	v_add_f32_e32 v184, v184, v185
	v_fmamk_f32 v184, v184, 0x3a800000, v239
	s_waitcnt lgkmcnt(2)
	v_add_f32_e32 v188, v188, v189
	v_fmamk_f32 v188, v188, 0x3a800000, v239
	s_waitcnt lgkmcnt(1)
	v_add_f32_e32 v192, v192, v193
	v_fmamk_f32 v192, v192, 0x3a800000, v239
	s_waitcnt lgkmcnt(0)
; __device__ __forceinline__ unsigned pk2(float lo, float hi) { f32x2_t v = {lo, hi}; bf16x2_t b = __builtin_convertvector(v, bf16x2_t); return __builtin_bit_cast(unsigned, b); }
; __device__ __forceinline__ float fast_sigmoid(float x) { return __builtin_amdgcn_rcpf(1.f + __expf(-x)); }
;     __device__ __forceinline__ void operator()(const f32x4 (&acc)[2][2][4][2], const Unit& u, int wr, int wc, int fr, int fq) const {
;     ...
;                 const int row = row0 + ai * HALF + m * 16;
;                 const float rs = rsqrtf(row_ssq(ssq, 16, 4, row, fq) * (1.f / 1024.f) + EPS);
;                 float r[8];
; #pragma unroll
;                 for (int n = 0; n < 2; ++n)
; #pragma unroll
;                     for (int e = 0; e < 4; ++e) { const float gv = acc[ai][0][m][n][e] * rs, uv = acc[ai][1][m][n][e] * rs; r[n * 4 + e] = gv * fast_sigmoid(gv) * uv; }
;                 u32x4 w; w.x = pk2(r[0], r[1]); w.y = pk2(r[2], r[3]); w.z = pk2(r[4], r[5]); w.w = pk2(r[6], r[7]);
;                 *(u32x4*)(O + (size_t)row * DFF + col0) = w;
	v_add_f32_e32 v196, v196, v197
	v_fmamk_f32 v196, v196, 0x3a800000, v239
	v_cmp_gt_f32_e32 vcc, s55, v168
	v_mul_f32_e32 v169, 0x4b800000, v168
	s_nop 0
	v_cndmask_b32_e32 v168, v168, v169, vcc
	v_rsq_f32_e32 v168, v168
	s_nop 0
	v_mul_f32_e32 v169, 0x45800000, v168
	v_cndmask_b32_e32 v158, v168, v169, vcc
	v_cmp_gt_f32_e32 vcc, s55, v172
	v_mul_f32_e32 v173, 0x4b800000, v172
	s_nop 0
	v_cndmask_b32_e32 v172, v172, v173, vcc
	v_rsq_f32_e32 v172, v172
	s_nop 0
	v_mul_f32_e32 v173, 0x45800000, v172
	v_cndmask_b32_e32 v159, v172, v173, vcc
	v_cmp_gt_f32_e32 vcc, s55, v176
	v_mul_f32_e32 v177, 0x4b800000, v176
	s_nop 0
	v_cndmask_b32_e32 v176, v176, v177, vcc
	v_rsq_f32_e32 v176, v176
	s_nop 0
	v_mul_f32_e32 v177, 0x45800000, v176
	v_cndmask_b32_e32 v160, v176, v177, vcc
	v_cmp_gt_f32_e32 vcc, s55, v180
	v_mul_f32_e32 v181, 0x4b800000, v180
	s_nop 0
	v_cndmask_b32_e32 v180, v180, v181, vcc
	v_rsq_f32_e32 v180, v180
	s_nop 0
	v_mul_f32_e32 v181, 0x45800000, v180
	v_cndmask_b32_e32 v161, v180, v181, vcc
	v_cmp_gt_f32_e32 vcc, s55, v184
	v_mul_f32_e32 v185, 0x4b800000, v184
	s_nop 0
	v_cndmask_b32_e32 v184, v184, v185, vcc
	v_rsq_f32_e32 v184, v184
	s_nop 0
	v_mul_f32_e32 v185, 0x45800000, v184
	v_cndmask_b32_e32 v162, v184, v185, vcc
	v_cmp_gt_f32_e32 vcc, s55, v188
	v_mul_f32_e32 v189, 0x4b800000, v188
	s_nop 0
	v_cndmask_b32_e32 v188, v188, v189, vcc
	v_rsq_f32_e32 v188, v188
	s_nop 0
	v_mul_f32_e32 v189, 0x45800000, v188
	v_cndmask_b32_e32 v163, v188, v189, vcc
	v_cmp_gt_f32_e32 vcc, s55, v192
	v_mul_f32_e32 v193, 0x4b800000, v192
	s_nop 0
	v_cndmask_b32_e32 v192, v192, v193, vcc
	v_rsq_f32_e32 v192, v192
	s_nop 0
	v_mul_f32_e32 v193, 0x45800000, v192
	v_cndmask_b32_e32 v164, v192, v193, vcc
	v_cmp_gt_f32_e32 vcc, s55, v196
	v_mul_f32_e32 v197, 0x4b800000, v196
	s_nop 0
	v_cndmask_b32_e32 v196, v196, v197, vcc
	v_rsq_f32_e32 v196, v196
	s_nop 0
	v_mul_f32_e32 v197, 0x45800000, v196
	v_cndmask_b32_e32 v165, v196, v197, vcc
	v_mov_b32_e32 v152, v158
	v_pk_mul_f32 v[126:127], v[126:127], v[152:153] op_sel_hi:[1,0]
	v_pk_mul_f32 v[118:119], v[118:119], v[152:153] op_sel_hi:[1,0]
	v_mul_f32_e32 v145, 0xbfb8aa3b, v126
	v_exp_f32_e32 v145, v145
	v_pk_mul_f32 v[120:121], v[120:121], v[152:153] op_sel_hi:[1,0]
	v_pk_mul_f32 v[122:123], v[122:123], v[152:153] op_sel_hi:[1,0]
	v_pk_mul_f32 v[114:115], v[114:115], v[152:153] op_sel_hi:[1,0]
	v_add_f32_e32 v145, 1.0, v145
	v_rcp_f32_e32 v154, v145
	v_mul_f32_e32 v145, 0xbfb8aa3b, v127
	v_exp_f32_e32 v145, v145
	v_pk_mul_f32 v[116:117], v[116:117], v[152:153] op_sel_hi:[1,0]
	v_add_f32_e32 v145, 1.0, v145
	v_rcp_f32_e32 v155, v145
	s_nop 0
	v_pk_mul_f32 v[126:127], v[126:127], v[154:155]
	s_nop 0
	v_pk_mul_f32 v[118:119], v[118:119], v[126:127]
	v_pk_mul_f32 v[126:127], v[128:129], v[152:153] op_sel_hi:[1,0]
	s_nop 0
	v_mul_f32_e32 v128, 0xbfb8aa3b, v126
	v_mul_f32_e32 v129, 0xbfb8aa3b, v127
	v_exp_f32_e32 v128, v128
	v_exp_f32_e32 v129, v129
	v_add_f32_e32 v128, 1.0, v128
	v_add_f32_e32 v129, 1.0, v129
	v_rcp_f32_e32 v128, v128
	v_rcp_f32_e32 v129, v129
	s_nop 0
	v_pk_mul_f32 v[126:127], v[126:127], v[128:129]
	s_nop 0
	v_pk_mul_f32 v[120:121], v[120:121], v[126:127]
	v_mul_f32_e32 v126, 0xbfb8aa3b, v122
	v_mul_f32_e32 v127, 0xbfb8aa3b, v123
	v_exp_f32_e32 v126, v126
	v_exp_f32_e32 v127, v127
	v_add_f32_e32 v126, 1.0, v126
	v_add_f32_e32 v127, 1.0, v127
	v_rcp_f32_e32 v126, v126
	v_rcp_f32_e32 v127, v127
	s_nop 0
	v_pk_mul_f32 v[122:123], v[122:123], v[126:127]
	s_nop 0
	v_pk_mul_f32 v[122:123], v[114:115], v[122:123]
	v_pk_mul_f32 v[114:115], v[124:125], v[152:153] op_sel_hi:[1,0]
	s_nop 0
	v_mul_f32_e32 v124, 0xbfb8aa3b, v114
	v_mul_f32_e32 v125, 0xbfb8aa3b, v115
	v_exp_f32_e32 v124, v124
	v_exp_f32_e32 v125, v125
	v_add_f32_e32 v124, 1.0, v124
	v_add_f32_e32 v125, 1.0, v125
	v_rcp_f32_e32 v124, v124
	v_rcp_f32_e32 v125, v125
	s_nop 0
	v_pk_mul_f32 v[114:115], v[114:115], v[124:125]
	s_nop 0
	v_pk_mul_f32 v[124:125], v[116:117], v[114:115]
	v_cvt_pk_bf16_f32 v114, v118, v119
	v_cvt_pk_bf16_f32 v115, v120, v121
	v_cvt_pk_bf16_f32 v116, v122, v123
	v_cvt_pk_bf16_f32 v117, v124, v125
	v_mad_i64_i32 v[118:119], s[6:7], v144, s4, v[142:143]
	global_store_dwordx4 v[118:119], v[114:117], off
	s_nop 1
	v_or_b32_e32 v114, 16, v144
	v_mov_b32_e32 v116, v159
	v_pk_mul_f32 v[110:111], v[110:111], v[116:117] op_sel_hi:[1,0]
	v_pk_mul_f32 v[102:103], v[102:103], v[116:117] op_sel_hi:[1,0]
	v_mul_f32_e32 v115, 0xbfb8aa3b, v110
	v_exp_f32_e32 v115, v115
	v_pk_mul_f32 v[104:105], v[104:105], v[116:117] op_sel_hi:[1,0]
	v_pk_mul_f32 v[106:107], v[106:107], v[116:117] op_sel_hi:[1,0]
	v_pk_mul_f32 v[98:99], v[98:99], v[116:117] op_sel_hi:[1,0]
	v_add_f32_e32 v115, 1.0, v115
	v_rcp_f32_e32 v118, v115
	v_mul_f32_e32 v115, 0xbfb8aa3b, v111
	v_exp_f32_e32 v115, v115
	v_pk_mul_f32 v[100:101], v[100:101], v[116:117] op_sel_hi:[1,0]
	v_add_f32_e32 v115, 1.0, v115
	v_rcp_f32_e32 v119, v115
	s_nop 0
	v_pk_mul_f32 v[110:111], v[110:111], v[118:119]
	s_nop 0
	v_pk_mul_f32 v[102:103], v[102:103], v[110:111]
	v_pk_mul_f32 v[110:111], v[112:113], v[116:117] op_sel_hi:[1,0]
	s_nop 0
	v_mul_f32_e32 v112, 0xbfb8aa3b, v110
	v_mul_f32_e32 v113, 0xbfb8aa3b, v111
	v_exp_f32_e32 v112, v112
	v_exp_f32_e32 v113, v113
	v_add_f32_e32 v112, 1.0, v112
	v_add_f32_e32 v113, 1.0, v113
	v_rcp_f32_e32 v112, v112
	v_rcp_f32_e32 v113, v113
	s_nop 0
	v_pk_mul_f32 v[110:111], v[110:111], v[112:113]
	s_nop 0
	v_pk_mul_f32 v[104:105], v[104:105], v[110:111]
	v_mul_f32_e32 v110, 0xbfb8aa3b, v106
	v_mul_f32_e32 v111, 0xbfb8aa3b, v107
	v_exp_f32_e32 v110, v110
	v_exp_f32_e32 v111, v111
	v_add_f32_e32 v110, 1.0, v110
	v_add_f32_e32 v111, 1.0, v111
; __device__ __forceinline__ unsigned pk2(float lo, float hi) { f32x2_t v = {lo, hi}; bf16x2_t b = __builtin_convertvector(v, bf16x2_t); return __builtin_bit_cast(unsigned, b); }
; __device__ __forceinline__ float fast_sigmoid(float x) { return __builtin_amdgcn_rcpf(1.f + __expf(-x)); }
;     __device__ __forceinline__ void operator()(const f32x4 (&acc)[2][2][4][2], const Unit& u, int wr, int wc, int fr, int fq) const {
;     ...
;         for (int ai = 0; ai < 2; ++ai)
; #pragma unroll
;             for (int m = 0; m < 4; ++m) {
;                 const int row = row0 + ai * HALF + m * 16;
;                 const float rs = rsqrtf(row_ssq(ssq, 16, 4, row, fq) * (1.f / 1024.f) + EPS);
;                 float r[8];
; #pragma unroll
;                 for (int n = 0; n < 2; ++n)
; #pragma unroll
;                     for (int e = 0; e < 4; ++e) { const float gv = acc[ai][0][m][n][e] * rs, uv = acc[ai][1][m][n][e] * rs; r[n * 4 + e] = gv * fast_sigmoid(gv) * uv; }
;                 u32x4 w; w.x = pk2(r[0], r[1]); w.y = pk2(r[2], r[3]); w.z = pk2(r[4], r[5]); w.w = pk2(r[6], r[7]);
;                 *(u32x4*)(O + (size_t)row * DFF + col0) = w;
	v_rcp_f32_e32 v110, v110
	v_rcp_f32_e32 v111, v111
	s_nop 0
	v_pk_mul_f32 v[106:107], v[106:107], v[110:111]
	s_nop 0
	v_pk_mul_f32 v[106:107], v[98:99], v[106:107]
	v_pk_mul_f32 v[98:99], v[108:109], v[116:117] op_sel_hi:[1,0]
	s_nop 0
	v_mul_f32_e32 v108, 0xbfb8aa3b, v98
	v_mul_f32_e32 v109, 0xbfb8aa3b, v99
	v_exp_f32_e32 v108, v108
	v_exp_f32_e32 v109, v109
	v_add_f32_e32 v108, 1.0, v108
	v_add_f32_e32 v109, 1.0, v109
	v_rcp_f32_e32 v108, v108
	v_rcp_f32_e32 v109, v109
	s_nop 0
	v_pk_mul_f32 v[98:99], v[98:99], v[108:109]
	s_nop 0
	v_pk_mul_f32 v[108:109], v[100:101], v[98:99]
	v_cvt_pk_bf16_f32 v98, v102, v103
	v_cvt_pk_bf16_f32 v99, v104, v105
	v_cvt_pk_bf16_f32 v100, v106, v107
	v_cvt_pk_bf16_f32 v101, v108, v109
	v_mad_i64_i32 v[102:103], s[6:7], v114, s4, v[142:143]
	global_store_dwordx4 v[102:103], v[98:101], off
	s_nop 1
	v_or_b32_e32 v98, 32, v144
	v_mov_b32_e32 v100, v160
	v_pk_mul_f32 v[94:95], v[94:95], v[100:101] op_sel_hi:[1,0]
	v_pk_mul_f32 v[86:87], v[86:87], v[100:101] op_sel_hi:[1,0]
	v_mul_f32_e32 v99, 0xbfb8aa3b, v94
	v_exp_f32_e32 v99, v99
	v_pk_mul_f32 v[88:89], v[88:89], v[100:101] op_sel_hi:[1,0]
	v_pk_mul_f32 v[90:91], v[90:91], v[100:101] op_sel_hi:[1,0]
	v_pk_mul_f32 v[82:83], v[82:83], v[100:101] op_sel_hi:[1,0]
	v_add_f32_e32 v99, 1.0, v99
	v_rcp_f32_e32 v102, v99
	v_mul_f32_e32 v99, 0xbfb8aa3b, v95
	v_exp_f32_e32 v99, v99
	v_pk_mul_f32 v[84:85], v[84:85], v[100:101] op_sel_hi:[1,0]
	v_add_f32_e32 v99, 1.0, v99
	v_rcp_f32_e32 v103, v99
	s_nop 0
	v_pk_mul_f32 v[94:95], v[94:95], v[102:103]
	s_nop 0
	v_pk_mul_f32 v[86:87], v[86:87], v[94:95]
	v_pk_mul_f32 v[94:95], v[96:97], v[100:101] op_sel_hi:[1,0]
	s_nop 0
	v_mul_f32_e32 v96, 0xbfb8aa3b, v94
	v_mul_f32_e32 v97, 0xbfb8aa3b, v95
	v_exp_f32_e32 v96, v96
	v_exp_f32_e32 v97, v97
	v_add_f32_e32 v96, 1.0, v96
	v_add_f32_e32 v97, 1.0, v97
	v_rcp_f32_e32 v96, v96
	v_rcp_f32_e32 v97, v97
	s_nop 0
	v_pk_mul_f32 v[94:95], v[94:95], v[96:97]
	s_nop 0
	v_pk_mul_f32 v[88:89], v[88:89], v[94:95]
	v_mul_f32_e32 v94, 0xbfb8aa3b, v90
	v_mul_f32_e32 v95, 0xbfb8aa3b, v91
	v_exp_f32_e32 v94, v94
	v_exp_f32_e32 v95, v95
	v_add_f32_e32 v94, 1.0, v94
	v_add_f32_e32 v95, 1.0, v95
	v_rcp_f32_e32 v94, v94
	v_rcp_f32_e32 v95, v95
	s_nop 0
	v_pk_mul_f32 v[90:91], v[90:91], v[94:95]
	s_nop 0
	v_pk_mul_f32 v[90:91], v[82:83], v[90:91]
	v_pk_mul_f32 v[82:83], v[92:93], v[100:101] op_sel_hi:[1,0]
	s_nop 0
	v_mul_f32_e32 v92, 0xbfb8aa3b, v82
	v_mul_f32_e32 v93, 0xbfb8aa3b, v83
	v_exp_f32_e32 v92, v92
	v_exp_f32_e32 v93, v93
	v_add_f32_e32 v92, 1.0, v92
	v_add_f32_e32 v93, 1.0, v93
	v_rcp_f32_e32 v92, v92
	v_rcp_f32_e32 v93, v93
	s_nop 0
	v_pk_mul_f32 v[82:83], v[82:83], v[92:93]
	s_nop 0
	v_pk_mul_f32 v[92:93], v[84:85], v[82:83]
	v_cvt_pk_bf16_f32 v82, v86, v87
	v_cvt_pk_bf16_f32 v83, v88, v89
	v_cvt_pk_bf16_f32 v84, v90, v91
	v_cvt_pk_bf16_f32 v85, v92, v93
	v_mad_i64_i32 v[86:87], s[6:7], v98, s4, v[142:143]
	global_store_dwordx4 v[86:87], v[82:85], off
	s_nop 1
	v_or_b32_e32 v82, 48, v144
	v_mov_b32_e32 v84, v161
	v_pk_mul_f32 v[78:79], v[78:79], v[84:85] op_sel_hi:[1,0]
	v_pk_mul_f32 v[70:71], v[70:71], v[84:85] op_sel_hi:[1,0]
	v_mul_f32_e32 v83, 0xbfb8aa3b, v78
	v_exp_f32_e32 v83, v83
	v_pk_mul_f32 v[72:73], v[72:73], v[84:85] op_sel_hi:[1,0]
	v_pk_mul_f32 v[74:75], v[74:75], v[84:85] op_sel_hi:[1,0]
	v_pk_mul_f32 v[66:67], v[66:67], v[84:85] op_sel_hi:[1,0]
	v_add_f32_e32 v83, 1.0, v83
	v_rcp_f32_e32 v86, v83
	v_mul_f32_e32 v83, 0xbfb8aa3b, v79
	v_exp_f32_e32 v83, v83
	v_pk_mul_f32 v[68:69], v[68:69], v[84:85] op_sel_hi:[1,0]
	v_add_f32_e32 v83, 1.0, v83
	v_rcp_f32_e32 v87, v83
	s_nop 0
	v_pk_mul_f32 v[78:79], v[78:79], v[86:87]
	s_nop 0
	v_pk_mul_f32 v[70:71], v[70:71], v[78:79]
	v_pk_mul_f32 v[78:79], v[80:81], v[84:85] op_sel_hi:[1,0]
	s_nop 0
	v_mul_f32_e32 v80, 0xbfb8aa3b, v78
	v_mul_f32_e32 v81, 0xbfb8aa3b, v79
	v_exp_f32_e32 v80, v80
	v_exp_f32_e32 v81, v81
	v_add_f32_e32 v80, 1.0, v80
	v_add_f32_e32 v81, 1.0, v81
	v_rcp_f32_e32 v80, v80
	v_rcp_f32_e32 v81, v81
	s_nop 0
	v_pk_mul_f32 v[78:79], v[78:79], v[80:81]
	s_nop 0
	v_pk_mul_f32 v[72:73], v[72:73], v[78:79]
	v_mul_f32_e32 v78, 0xbfb8aa3b, v74
	v_mul_f32_e32 v79, 0xbfb8aa3b, v75
	v_exp_f32_e32 v78, v78
	v_exp_f32_e32 v79, v79
	v_add_f32_e32 v78, 1.0, v78
	v_add_f32_e32 v79, 1.0, v79
	v_rcp_f32_e32 v78, v78
	v_rcp_f32_e32 v79, v79
	s_nop 0
	v_pk_mul_f32 v[74:75], v[74:75], v[78:79]
	s_nop 0
	v_pk_mul_f32 v[74:75], v[66:67], v[74:75]
	v_pk_mul_f32 v[66:67], v[76:77], v[84:85] op_sel_hi:[1,0]
	s_nop 0
	v_mul_f32_e32 v76, 0xbfb8aa3b, v66
	v_mul_f32_e32 v77, 0xbfb8aa3b, v67
	v_exp_f32_e32 v76, v76
	v_exp_f32_e32 v77, v77
	v_add_f32_e32 v76, 1.0, v76
	v_add_f32_e32 v77, 1.0, v77
	v_rcp_f32_e32 v76, v76
	v_rcp_f32_e32 v77, v77
	s_nop 0
	v_pk_mul_f32 v[66:67], v[66:67], v[76:77]
	s_nop 0
	v_pk_mul_f32 v[76:77], v[68:69], v[66:67]
	v_cvt_pk_bf16_f32 v66, v70, v71
	v_cvt_pk_bf16_f32 v67, v72, v73
	v_cvt_pk_bf16_f32 v68, v74, v75
	v_cvt_pk_bf16_f32 v69, v76, v77
	v_mad_i64_i32 v[70:71], s[6:7], v82, s4, v[142:143]
	global_store_dwordx4 v[70:71], v[66:69], off
	s_nop 1
	v_add_u32_e32 v66, 0x80, v144
	v_mov_b32_e32 v68, v162
	v_pk_mul_f32 v[62:63], v[62:63], v[68:69] op_sel_hi:[1,0]
	v_pk_mul_f32 v[54:55], v[54:55], v[68:69] op_sel_hi:[1,0]
	v_mul_f32_e32 v67, 0xbfb8aa3b, v62
	v_exp_f32_e32 v67, v67
	v_pk_mul_f32 v[56:57], v[56:57], v[68:69] op_sel_hi:[1,0]
	v_pk_mul_f32 v[58:59], v[58:59], v[68:69] op_sel_hi:[1,0]
	v_pk_mul_f32 v[50:51], v[50:51], v[68:69] op_sel_hi:[1,0]
	v_add_f32_e32 v67, 1.0, v67
	v_rcp_f32_e32 v70, v67
	v_mul_f32_e32 v67, 0xbfb8aa3b, v63
	v_exp_f32_e32 v67, v67
	v_pk_mul_f32 v[52:53], v[52:53], v[68:69] op_sel_hi:[1,0]
; __device__ __forceinline__ unsigned pk2(float lo, float hi) { f32x2_t v = {lo, hi}; bf16x2_t b = __builtin_convertvector(v, bf16x2_t); return __builtin_bit_cast(unsigned, b); }
; __device__ __forceinline__ float fast_sigmoid(float x) { return __builtin_amdgcn_rcpf(1.f + __expf(-x)); }
;     __device__ __forceinline__ void operator()(const f32x4 (&acc)[2][2][4][2], const Unit& u, int wr, int wc, int fr, int fq) const {
;     ...
;         for (int ai = 0; ai < 2; ++ai)
; #pragma unroll
;             for (int m = 0; m < 4; ++m) {
;                 const int row = row0 + ai * HALF + m * 16;
;                 const float rs = rsqrtf(row_ssq(ssq, 16, 4, row, fq) * (1.f / 1024.f) + EPS);
;                 float r[8];
; #pragma unroll
;                 for (int n = 0; n < 2; ++n)
; #pragma unroll
;                     for (int e = 0; e < 4; ++e) { const float gv = acc[ai][0][m][n][e] * rs, uv = acc[ai][1][m][n][e] * rs; r[n * 4 + e] = gv * fast_sigmoid(gv) * uv; }
;                 u32x4 w; w.x = pk2(r[0], r[1]); w.y = pk2(r[2], r[3]); w.z = pk2(r[4], r[5]); w.w = pk2(r[6], r[7]);
;                 *(u32x4*)(O + (size_t)row * DFF + col0) = w;
	v_add_f32_e32 v67, 1.0, v67
	v_rcp_f32_e32 v71, v67
	s_nop 0
	v_pk_mul_f32 v[62:63], v[62:63], v[70:71]
	s_nop 0
	v_pk_mul_f32 v[54:55], v[54:55], v[62:63]
	v_pk_mul_f32 v[62:63], v[64:65], v[68:69] op_sel_hi:[1,0]
	s_nop 0
	v_mul_f32_e32 v64, 0xbfb8aa3b, v62
	v_mul_f32_e32 v65, 0xbfb8aa3b, v63
	v_exp_f32_e32 v64, v64
	v_exp_f32_e32 v65, v65
	v_add_f32_e32 v64, 1.0, v64
	v_add_f32_e32 v65, 1.0, v65
	v_rcp_f32_e32 v64, v64
	v_rcp_f32_e32 v65, v65
	s_nop 0
	v_pk_mul_f32 v[62:63], v[62:63], v[64:65]
	s_nop 0
	v_pk_mul_f32 v[56:57], v[56:57], v[62:63]
	v_mul_f32_e32 v62, 0xbfb8aa3b, v58
	v_mul_f32_e32 v63, 0xbfb8aa3b, v59
	v_exp_f32_e32 v62, v62
	v_exp_f32_e32 v63, v63
	v_add_f32_e32 v62, 1.0, v62
	v_add_f32_e32 v63, 1.0, v63
	v_rcp_f32_e32 v62, v62
	v_rcp_f32_e32 v63, v63
	s_nop 0
	v_pk_mul_f32 v[58:59], v[58:59], v[62:63]
	s_nop 0
	v_pk_mul_f32 v[58:59], v[50:51], v[58:59]
	v_pk_mul_f32 v[50:51], v[60:61], v[68:69] op_sel_hi:[1,0]
	s_nop 0
	v_mul_f32_e32 v60, 0xbfb8aa3b, v50
	v_mul_f32_e32 v61, 0xbfb8aa3b, v51
	v_exp_f32_e32 v60, v60
	v_exp_f32_e32 v61, v61
	v_add_f32_e32 v60, 1.0, v60
	v_add_f32_e32 v61, 1.0, v61
	v_rcp_f32_e32 v60, v60
	v_rcp_f32_e32 v61, v61
	s_nop 0
	v_pk_mul_f32 v[50:51], v[50:51], v[60:61]
	s_nop 0
	v_pk_mul_f32 v[60:61], v[52:53], v[50:51]
	v_cvt_pk_bf16_f32 v50, v54, v55
	v_cvt_pk_bf16_f32 v51, v56, v57
	v_cvt_pk_bf16_f32 v52, v58, v59
	v_cvt_pk_bf16_f32 v53, v60, v61
	v_mad_i64_i32 v[54:55], s[6:7], v66, s4, v[142:143]
	global_store_dwordx4 v[54:55], v[50:53], off
	s_nop 1
	v_add_u32_e32 v50, 0x90, v144
	v_mov_b32_e32 v52, v163
	v_pk_mul_f32 v[46:47], v[46:47], v[52:53] op_sel_hi:[1,0]
	v_pk_mul_f32 v[38:39], v[38:39], v[52:53] op_sel_hi:[1,0]
	v_mul_f32_e32 v51, 0xbfb8aa3b, v46
	v_exp_f32_e32 v51, v51
	v_pk_mul_f32 v[40:41], v[40:41], v[52:53] op_sel_hi:[1,0]
	v_pk_mul_f32 v[42:43], v[42:43], v[52:53] op_sel_hi:[1,0]
	v_pk_mul_f32 v[34:35], v[34:35], v[52:53] op_sel_hi:[1,0]
	v_add_f32_e32 v51, 1.0, v51
	v_rcp_f32_e32 v54, v51
	v_mul_f32_e32 v51, 0xbfb8aa3b, v47
	v_exp_f32_e32 v51, v51
	v_pk_mul_f32 v[36:37], v[36:37], v[52:53] op_sel_hi:[1,0]
	v_add_f32_e32 v51, 1.0, v51
	v_rcp_f32_e32 v55, v51
	s_nop 0
	v_pk_mul_f32 v[46:47], v[46:47], v[54:55]
	s_nop 0
	v_pk_mul_f32 v[38:39], v[38:39], v[46:47]
	v_pk_mul_f32 v[46:47], v[48:49], v[52:53] op_sel_hi:[1,0]
	s_nop 0
	v_mul_f32_e32 v48, 0xbfb8aa3b, v46
	v_mul_f32_e32 v49, 0xbfb8aa3b, v47
	v_exp_f32_e32 v48, v48
	v_exp_f32_e32 v49, v49
	v_add_f32_e32 v48, 1.0, v48
	v_add_f32_e32 v49, 1.0, v49
	v_rcp_f32_e32 v48, v48
	v_rcp_f32_e32 v49, v49
	s_nop 0
	v_pk_mul_f32 v[46:47], v[46:47], v[48:49]
	s_nop 0
	v_pk_mul_f32 v[40:41], v[40:41], v[46:47]
	v_mul_f32_e32 v46, 0xbfb8aa3b, v42
	v_mul_f32_e32 v47, 0xbfb8aa3b, v43
	v_exp_f32_e32 v46, v46
	v_exp_f32_e32 v47, v47
	v_add_f32_e32 v46, 1.0, v46
	v_add_f32_e32 v47, 1.0, v47
	v_rcp_f32_e32 v46, v46
	v_rcp_f32_e32 v47, v47
	s_nop 0
	v_pk_mul_f32 v[42:43], v[42:43], v[46:47]
	s_nop 0
	v_pk_mul_f32 v[42:43], v[34:35], v[42:43]
	v_pk_mul_f32 v[34:35], v[44:45], v[52:53] op_sel_hi:[1,0]
	s_nop 0
	v_mul_f32_e32 v44, 0xbfb8aa3b, v34
	v_mul_f32_e32 v45, 0xbfb8aa3b, v35
	v_exp_f32_e32 v44, v44
	v_exp_f32_e32 v45, v45
	v_add_f32_e32 v44, 1.0, v44
	v_add_f32_e32 v45, 1.0, v45
	v_rcp_f32_e32 v44, v44
	v_rcp_f32_e32 v45, v45
	s_nop 0
	v_pk_mul_f32 v[34:35], v[34:35], v[44:45]
	s_nop 0
	v_pk_mul_f32 v[44:45], v[36:37], v[34:35]
	v_cvt_pk_bf16_f32 v34, v38, v39
	v_cvt_pk_bf16_f32 v35, v40, v41
	v_cvt_pk_bf16_f32 v36, v42, v43
	v_cvt_pk_bf16_f32 v37, v44, v45
	v_mad_i64_i32 v[38:39], s[6:7], v50, s4, v[142:143]
	global_store_dwordx4 v[38:39], v[34:37], off
	s_nop 1
	v_add_u32_e32 v34, 0xa0, v144
	v_mov_b32_e32 v36, v164
	v_pk_mul_f32 v[30:31], v[30:31], v[36:37] op_sel_hi:[1,0]
	v_pk_mul_f32 v[22:23], v[22:23], v[36:37] op_sel_hi:[1,0]
	v_mul_f32_e32 v35, 0xbfb8aa3b, v30
	v_exp_f32_e32 v35, v35
	v_pk_mul_f32 v[24:25], v[24:25], v[36:37] op_sel_hi:[1,0]
	v_pk_mul_f32 v[26:27], v[26:27], v[36:37] op_sel_hi:[1,0]
; __device__ __forceinline__ unsigned pk2(float lo, float hi) { f32x2_t v = {lo, hi}; bf16x2_t b = __builtin_convertvector(v, bf16x2_t); return __builtin_bit_cast(unsigned, b); }
; __device__ __forceinline__ float fast_sigmoid(float x) { return __builtin_amdgcn_rcpf(1.f + __expf(-x)); }
; #define PG8_BAR __builtin_amdgcn_s_barrier()
; template <class Epi>
; __device__ __forceinline__ void gemm_phase(LAS unsigned char* lds, int wave_s, const Gemm g, const StaticOrder S, const Epi E) {
;     ...
;         if (!has_next) break;
; #pragma unroll
;         for (int a = 0; a < 2; ++a)
; #pragma unroll
;             for (int b = 0; b < 2; ++b)
; #pragma unroll
;                 for (int m = 0; m < 4; ++m)
; #pragma unroll
;                     for (int n = 0; n < 2; ++n) acc[a][b][m][n] = (f32x4){0.f, 0.f, 0.f, 0.f};
;         cur = nxt; cA = nA; cB = nB; ++ui;
;         if (wr == 1) PG8_BAR;
;     __device__ __forceinline__ void operator()(const f32x4 (&acc)[2][2][4][2], const Unit& u, int wr, int wc, int fr, int fq) const {
;     ...
;         for (int ai = 0; ai < 2; ++ai)
; #pragma unroll
;             for (int m = 0; m < 4; ++m) {
;                 const int row = row0 + ai * HALF + m * 16;
;                 const float rs = rsqrtf(row_ssq(ssq, 16, 4, row, fq) * (1.f / 1024.f) + EPS);
;                 float r[8];
; #pragma unroll
;                 for (int n = 0; n < 2; ++n)
; #pragma unroll
;                     for (int e = 0; e < 4; ++e) { const float gv = acc[ai][0][m][n][e] * rs, uv = acc[ai][1][m][n][e] * rs; r[n * 4 + e] = gv * fast_sigmoid(gv) * uv; }
;                 u32x4 w; w.x = pk2(r[0], r[1]); w.y = pk2(r[2], r[3]); w.z = pk2(r[4], r[5]); w.w = pk2(r[6], r[7]);
;                 *(u32x4*)(O + (size_t)row * DFF + col0) = w;
	v_pk_mul_f32 v[18:19], v[18:19], v[36:37] op_sel_hi:[1,0]
	v_add_f32_e32 v35, 1.0, v35
	v_rcp_f32_e32 v38, v35
	v_mul_f32_e32 v35, 0xbfb8aa3b, v31
	v_exp_f32_e32 v35, v35
	v_pk_mul_f32 v[20:21], v[20:21], v[36:37] op_sel_hi:[1,0]
	v_add_f32_e32 v35, 1.0, v35
	v_rcp_f32_e32 v39, v35
	s_nop 0
	v_pk_mul_f32 v[30:31], v[30:31], v[38:39]
	s_nop 0
	v_pk_mul_f32 v[22:23], v[22:23], v[30:31]
	v_pk_mul_f32 v[30:31], v[32:33], v[36:37] op_sel_hi:[1,0]
	s_nop 0
	v_mul_f32_e32 v32, 0xbfb8aa3b, v30
	v_mul_f32_e32 v33, 0xbfb8aa3b, v31
	v_exp_f32_e32 v32, v32
	v_exp_f32_e32 v33, v33
	v_add_f32_e32 v32, 1.0, v32
	v_add_f32_e32 v33, 1.0, v33
	v_rcp_f32_e32 v32, v32
	v_rcp_f32_e32 v33, v33
	s_nop 0
	v_pk_mul_f32 v[30:31], v[30:31], v[32:33]
	s_nop 0
	v_pk_mul_f32 v[24:25], v[24:25], v[30:31]
	v_mul_f32_e32 v30, 0xbfb8aa3b, v26
	v_mul_f32_e32 v31, 0xbfb8aa3b, v27
	v_exp_f32_e32 v30, v30
	v_exp_f32_e32 v31, v31
	v_add_f32_e32 v30, 1.0, v30
	v_add_f32_e32 v31, 1.0, v31
	v_rcp_f32_e32 v30, v30
	v_rcp_f32_e32 v31, v31
	s_nop 0
	v_pk_mul_f32 v[26:27], v[26:27], v[30:31]
	s_nop 0
	v_pk_mul_f32 v[26:27], v[18:19], v[26:27]
	v_pk_mul_f32 v[18:19], v[28:29], v[36:37] op_sel_hi:[1,0]
	s_nop 0
	v_mul_f32_e32 v28, 0xbfb8aa3b, v18
	v_mul_f32_e32 v29, 0xbfb8aa3b, v19
	v_exp_f32_e32 v28, v28
	v_exp_f32_e32 v29, v29
	v_add_f32_e32 v28, 1.0, v28
	v_add_f32_e32 v29, 1.0, v29
	v_rcp_f32_e32 v28, v28
	v_rcp_f32_e32 v29, v29
	s_nop 0
	v_pk_mul_f32 v[18:19], v[18:19], v[28:29]
	s_nop 0
	v_pk_mul_f32 v[28:29], v[20:21], v[18:19]
	v_cvt_pk_bf16_f32 v18, v22, v23
	v_cvt_pk_bf16_f32 v19, v24, v25
	v_cvt_pk_bf16_f32 v20, v26, v27
	v_cvt_pk_bf16_f32 v21, v28, v29
	v_mad_i64_i32 v[22:23], s[6:7], v34, s4, v[142:143]
	global_store_dwordx4 v[22:23], v[18:21], off
	s_nop 1
	v_add_u32_e32 v18, 0xb0, v144
	v_mov_b32_e32 v20, v165
	v_pk_mul_f32 v[14:15], v[14:15], v[20:21] op_sel_hi:[1,0]
	v_pk_mul_f32 v[6:7], v[6:7], v[20:21] op_sel_hi:[1,0]
	v_mul_f32_e32 v19, 0xbfb8aa3b, v14
	v_exp_f32_e32 v19, v19
	v_pk_mul_f32 v[8:9], v[8:9], v[20:21] op_sel_hi:[1,0]
	v_pk_mul_f32 v[10:11], v[10:11], v[20:21] op_sel_hi:[1,0]
	v_pk_mul_f32 v[2:3], v[2:3], v[20:21] op_sel_hi:[1,0]
	v_add_f32_e32 v19, 1.0, v19
	v_rcp_f32_e32 v22, v19
	v_mul_f32_e32 v19, 0xbfb8aa3b, v15
	v_exp_f32_e32 v19, v19
	v_pk_mul_f32 v[4:5], v[4:5], v[20:21] op_sel_hi:[1,0]
	s_andn2_b64 vcc, exec, s[0:1]
	v_add_f32_e32 v19, 1.0, v19
	v_rcp_f32_e32 v23, v19
	s_nop 0
	v_pk_mul_f32 v[14:15], v[14:15], v[22:23]
	s_nop 0
	v_pk_mul_f32 v[6:7], v[6:7], v[14:15]
	v_pk_mul_f32 v[14:15], v[16:17], v[20:21] op_sel_hi:[1,0]
	s_nop 0
	v_mul_f32_e32 v16, 0xbfb8aa3b, v14
	v_mul_f32_e32 v17, 0xbfb8aa3b, v15
	v_exp_f32_e32 v16, v16
	v_exp_f32_e32 v17, v17
	v_add_f32_e32 v16, 1.0, v16
	v_add_f32_e32 v17, 1.0, v17
	v_rcp_f32_e32 v16, v16
	v_rcp_f32_e32 v17, v17
	s_nop 0
	v_pk_mul_f32 v[14:15], v[14:15], v[16:17]
	s_nop 0
	v_pk_mul_f32 v[8:9], v[8:9], v[14:15]
	v_mul_f32_e32 v14, 0xbfb8aa3b, v10
	v_mul_f32_e32 v15, 0xbfb8aa3b, v11
	v_exp_f32_e32 v14, v14
	v_exp_f32_e32 v15, v15
	v_add_f32_e32 v14, 1.0, v14
	v_add_f32_e32 v15, 1.0, v15
	v_rcp_f32_e32 v14, v14
	v_rcp_f32_e32 v15, v15
	s_nop 0
	v_pk_mul_f32 v[10:11], v[10:11], v[14:15]
	s_nop 0
	v_pk_mul_f32 v[10:11], v[2:3], v[10:11]
	v_pk_mul_f32 v[2:3], v[12:13], v[20:21] op_sel_hi:[1,0]
	s_nop 0
	v_mul_f32_e32 v12, 0xbfb8aa3b, v2
	v_mul_f32_e32 v13, 0xbfb8aa3b, v3
	v_exp_f32_e32 v12, v12
	v_exp_f32_e32 v13, v13
	v_add_f32_e32 v12, 1.0, v12
	v_add_f32_e32 v13, 1.0, v13
	v_rcp_f32_e32 v12, v12
	v_rcp_f32_e32 v13, v13
	s_nop 0
	v_pk_mul_f32 v[2:3], v[2:3], v[12:13]
	s_nop 0
	v_pk_mul_f32 v[12:13], v[4:5], v[2:3]
	v_cvt_pk_bf16_f32 v2, v6, v7
	v_cvt_pk_bf16_f32 v3, v8, v9
	v_cvt_pk_bf16_f32 v4, v10, v11
	v_cvt_pk_bf16_f32 v5, v12, v13
	v_mad_i64_i32 v[6:7], s[6:7], v18, s4, v[142:143]
	global_store_dwordx4 v[6:7], v[2:5], off
	s_cbranch_vccnz .LBB0_161
	s_andn2_b64 vcc, exec, s[12:13]
	s_cbranch_vccnz .LBB0_160
	s_mov_b32 s99, 0x13579bdf
	s_branch .LBB0_160

; #define PG8_STAGE(bufoff, gbase, voff) do { _Pragma("unroll") for (int _i = 0; _i < 2; ++_i) \
;         __builtin_amdgcn_global_load_lds((const unsigned*)((const char*)(gbase) + (voff)[_i]), (LAS unsigned*)(lds + (bufoff) + ldsw + _i * 8192), 16, 0, 0); } while (0)
; #define PG8_LDA(dst, b, h) do { _Pragma("unroll") for (int m = 0; m < 4; ++m) _Pragma("unroll") for (int k = 0; k < 2; ++k) dst[m][k] = *(const LAS bf16x8*)(lds + PG8_SA(b, h) + aoff + m * 2048 + k * 1024); } while (0)
; #define PG8_LDB(dst, b, h) do { _Pragma("unroll") for (int n = 0; n < 2; ++n) _Pragma("unroll") for (int k = 0; k < 2; ++k) dst[n][k] = *(const LAS bf16x8*)(lds + PG8_SB(b, h) + boff + n * 2048 + k * 1024); } while (0)
; #define PG8_BAR __builtin_amdgcn_s_barrier()
; #define PG8_SCHED __builtin_amdgcn_sched_barrier(0)
; template <class Epi>
; __device__ __forceinline__ void gemm_phase(LAS unsigned char* lds, int wave_s, const Gemm g, const StaticOrder S, const Epi E) {
;     ...
;     for (;;) {
;         const bool has_next = S.next(ui + 1, nxt);
;         const char* nA = has_next ? (const char*)g.A + (size_t)nxt.pm * tstepA : cA; const char* nB = has_next ? (const char*)g.Bt + (size_t)nxt.pn * tstepB : cB;
;         for (int t = 0; t < nt; t += 2) {
;             const bool last = (t == nt - 2);
;             const char* a1 = cA + (size_t)(t + 1) * kstep;
;             const char* a2 = last ? nA : cA + (size_t)(t + 2) * kstep; const char* b2 = last ? nB : cB + (size_t)(t + 2) * kstep;
;             const char* a3 = a2 + kstep; const char* b3 = b2 + kstep;
;             PG8_LDB(B0, 0, 0); PG8_LDB(B1, 0, 1); PG8_SCHED; PG8_LDA(At, 0, 0); PG8_STAGE(PG8_SA(1, 1), a1 + hstepA, voffA);
;     ...
;         if (!has_next) break;
; #pragma unroll
;         for (int a = 0; a < 2; ++a)
; #pragma unroll
;             for (int b = 0; b < 2; ++b)
; #pragma unroll
;                 for (int m = 0; m < 4; ++m)
; #pragma unroll
;                     for (int n = 0; n < 2; ++n) acc[a][b][m][n] = (f32x4){0.f, 0.f, 0.f, 0.f};
;         cur = nxt; cA = nA; cB = nB; ++ui;
;         if (wr == 1) PG8_BAR;
.LBB0_240:
	s_add_u32 s10, s14, 0x100
	v_mov_b32_e32 v2, 0
	s_addc_u32 s11, s15, 0
	s_mov_b32 s34, -2
	v_mov_b32_e32 v246, v2
	v_mov_b32_e32 v247, v2
	v_mov_b32_e32 v248, v2
	v_mov_b32_e32 v249, v2
	v_mov_b32_e32 v3, v2
	v_mov_b32_e32 v4, v2
	v_mfma_f32_32x32x16_bf16 v[18:33], v[246:249], v[246:249], 0
	v_mov_b32_e32 v5, v2
	v_mov_b32_e32 v6, v2
	v_mfma_f32_32x32x16_bf16 v[34:49], v[246:249], v[246:249], 0
	v_mov_b32_e32 v7, v2
	v_mov_b32_e32 v8, v2
	v_mfma_f32_32x32x16_bf16 v[50:65], v[246:249], v[246:249], 0
	v_mov_b32_e32 v9, v2
	v_mov_b32_e32 v10, v2
	v_mfma_f32_32x32x16_bf16 v[66:81], v[246:249], v[246:249], 0
	v_mov_b32_e32 v11, v2
	v_mov_b32_e32 v12, v2
	v_mfma_f32_32x32x16_bf16 v[82:97], v[246:249], v[246:249], 0
	v_mov_b32_e32 v13, v2
	v_mov_b32_e32 v14, v2
	v_mfma_f32_32x32x16_bf16 v[98:113], v[246:249], v[246:249], 0
	v_mov_b32_e32 v15, v2
	v_mov_b32_e32 v16, v2
	v_mfma_f32_32x32x16_bf16 v[114:129], v[246:249], v[246:249], 0
	v_mov_b32_e32 v17, v2
	s_cmp_eq_u32 s99, 0x13579bdf
	s_cbranch_scc0 .Lskw_1
	s_mov_b32 s99, 0
	s_barrier
.Lskw_1:
.LBB0_241:
	s_cmp_eq_u32 s34, 36
	s_cbranch_scc0 .Lpre_f1d_skip
	s_mov_b64 s[100:101], s[38:39]
	v_readlane_b32 s98, v250, 49
	v_readlane_b32 s99, v250, 50
	v_lshl_add_u32 v243, s31, 8, v160
	v_lshl_or_b32 v246, s4, 8, v162
	v_lshl_add_u32 v243, v243, 10, v246
	v_lshlrev_b32_e32 v243, 1, v243
	s_nop 1
	global_load_dwordx4 v[226:229], v243, s[100:101]
	global_load_dwordx4 v[230:233], v243, s[98:99]
	global_load_dwordx4 v[234:237], v243, s[100:101] offset:256
	global_load_dwordx4 v[242:245], v243, s[98:99] offset:256

; #define PG8_BAR __builtin_amdgcn_s_barrier()
; template <class Epi>
; __device__ __forceinline__ void gemm_phase(LAS unsigned char* lds, int wave_s, const Gemm g, const StaticOrder S, const Epi E) {
;     ...
;         if (!has_next) break;
; #pragma unroll
;         for (int a = 0; a < 2; ++a)
; #pragma unroll
;             for (int b = 0; b < 2; ++b)
; #pragma unroll
;                 for (int m = 0; m < 4; ++m)
; #pragma unroll
;                     for (int n = 0; n < 2; ++n) acc[a][b][m][n] = (f32x4){0.f, 0.f, 0.f, 0.f};
;         cur = nxt; cA = nA; cB = nB; ++ui;
;         if (wr == 1) PG8_BAR;
.Lepir_f1d_skip:
	s_or_b64 exec, exec, s[12:13]
	s_and_b64 vcc, exec, s[46:47]
	s_mov_b64 s[12:13], -1
	s_cbranch_vccnz .LBB0_229
	s_andn2_b64 vcc, exec, s[42:43]
	s_cbranch_vccnz .LBB0_228
	s_mov_b32 s99, 0x13579bdf
	s_branch .LBB0_228

; #define PG8_STAGE(bufoff, gbase, voff) do { _Pragma("unroll") for (int _i = 0; _i < 2; ++_i) \
;         __builtin_amdgcn_global_load_lds((const unsigned*)((const char*)(gbase) + (voff)[_i]), (LAS unsigned*)(lds + (bufoff) + ldsw + _i * 8192), 16, 0, 0); } while (0)
; #define PG8_LDA(dst, b, h) do { _Pragma("unroll") for (int m = 0; m < 4; ++m) _Pragma("unroll") for (int k = 0; k < 2; ++k) dst[m][k] = *(const LAS bf16x8*)(lds + PG8_SA(b, h) + aoff + m * 2048 + k * 1024); } while (0)
; #define PG8_LDB(dst, b, h) do { _Pragma("unroll") for (int n = 0; n < 2; ++n) _Pragma("unroll") for (int k = 0; k < 2; ++k) dst[n][k] = *(const LAS bf16x8*)(lds + PG8_SB(b, h) + boff + n * 2048 + k * 1024); } while (0)
; #define PG8_BAR __builtin_amdgcn_s_barrier()
; #define PG8_SCHED __builtin_amdgcn_sched_barrier(0)
; template <class Epi>
; __device__ __forceinline__ void gemm_phase(LAS unsigned char* lds, int wave_s, const Gemm g, const StaticOrder S, const Epi E) {
;     ...
;     for (;;) {
;         const bool has_next = S.next(ui + 1, nxt);
;         const char* nA = has_next ? (const char*)g.A + (size_t)nxt.pm * tstepA : cA; const char* nB = has_next ? (const char*)g.Bt + (size_t)nxt.pn * tstepB : cB;
;         for (int t = 0; t < nt; t += 2) {
;             const bool last = (t == nt - 2);
;             const char* a1 = cA + (size_t)(t + 1) * kstep;
;             const char* a2 = last ? nA : cA + (size_t)(t + 2) * kstep; const char* b2 = last ? nB : cB + (size_t)(t + 2) * kstep;
;             const char* a3 = a2 + kstep; const char* b3 = b2 + kstep;
;             PG8_LDB(B0, 0, 0); PG8_LDB(B1, 0, 1); PG8_SCHED; PG8_LDA(At, 0, 0); PG8_STAGE(PG8_SA(1, 1), a1 + hstepA, voffA);
;     ...
;         if (!has_next) break;
; #pragma unroll
;         for (int a = 0; a < 2; ++a)
; #pragma unroll
;             for (int b = 0; b < 2; ++b)
; #pragma unroll
;                 for (int m = 0; m < 4; ++m)
; #pragma unroll
;                     for (int n = 0; n < 2; ++n) acc[a][b][m][n] = (f32x4){0.f, 0.f, 0.f, 0.f};
;         cur = nxt; cA = nA; cB = nB; ++ui;
;         if (wr == 1) PG8_BAR;
.LBB0_327:
	s_ashr_i32 s23, s22, 31
	s_lshl_b64 s[6:7], s[22:23], 19
	s_add_u32 s24, s50, s6
	s_addc_u32 s25, s51, s7
	s_and_b64 s[6:7], s[48:49], exec
	s_cselect_b32 s23, s25, s1
	s_cselect_b32 s34, s24, s0
	s_ashr_i32 s21, s20, 31
	s_lshl_b64 s[6:7], s[20:21], 19
	v_readlane_b32 s10, v250, 33
	v_readlane_b32 s11, v250, 34
	s_add_u32 s26, s10, s6
	s_addc_u32 s27, s11, s7
	s_and_b64 s[6:7], s[48:49], exec
	s_cselect_b32 s10, s27, s29
	s_cselect_b32 s11, s26, s28
	s_add_u32 s0, s0, 0x40080
	s_addc_u32 s1, s1, 0
	s_add_u32 s21, s28, 0x100
	v_mov_b32_e32 v2, 0
	s_addc_u32 s35, s29, 0
	s_mov_b32 s50, -2
	v_mov_b32_e32 v3, v2
	v_mov_b32_e32 v4, v2
	v_mov_b32_e32 v5, v2
	v_mov_b32_e32 v6, v2
	v_mov_b32_e32 v7, v2
	v_mov_b32_e32 v8, v2
	v_mov_b32_e32 v9, v2
	v_mov_b32_e32 v10, v2
	s_waitcnt lgkmcnt(0)
	v_mov_b32_e32 v246, v2
	v_mov_b32_e32 v247, v2
	v_mov_b32_e32 v248, v2
	v_mov_b32_e32 v249, v2
	v_mov_b32_e32 v11, v2
	v_mov_b32_e32 v12, v2
	v_mfma_f32_32x32x16_bf16 v[18:33], v[246:249], v[246:249], 0
	v_mov_b32_e32 v13, v2
	v_mov_b32_e32 v14, v2
	v_mfma_f32_32x32x16_bf16 v[34:49], v[246:249], v[246:249], 0
	v_mov_b32_e32 v15, v2
	v_mov_b32_e32 v16, v2
	v_mfma_f32_32x32x16_bf16 v[50:65], v[246:249], v[246:249], 0
	v_mov_b32_e32 v17, v2
	v_mfma_f32_32x32x16_bf16 v[66:81], v[246:249], v[246:249], 0
	v_mfma_f32_32x32x16_bf16 v[82:97], v[246:249], v[246:249], 0
	v_mfma_f32_32x32x16_bf16 v[98:113], v[246:249], v[246:249], 0
	v_mfma_f32_32x32x16_bf16 v[114:129], v[246:249], v[246:249], 0
	s_cmp_eq_u32 s99, 0x13579bdf
	s_cbranch_scc0 .Lskw_2
	s_mov_b32 s99, 0
	s_barrier
.Lskw_2:
.LBB0_328:
	s_cmp_eq_u32 s50, 6
	s_cbranch_scc0 .Lsq_win_skip
	v_readlane_b32 s100, v140, 0
	v_readlane_b32 s101, v141, 0
	s_lshl_b32 s6, s4, 14
	s_lshl_b32 s7, s92, 5
	s_add_u32 s6, s6, s7
	s_add_u32 s100, s100, s6
	s_addc_u32 s101, s101, 0
	s_add_i32 m0, s7, 0x24000
	v_lshlrev_b32_e32 v243, 4, v241
	s_nop 1
	global_load_lds_dwordx4 v243, s[100:101]
	global_load_lds_dwordx4 v243, s[100:101] offset:1024

; #define PG8_BAR __builtin_amdgcn_s_barrier()
; template <class Epi>
; __device__ __forceinline__ void gemm_phase(LAS unsigned char* lds, int wave_s, const Gemm g, const StaticOrder S, const Epi E) {
;     ...
;         if (!has_next) break;
; #pragma unroll
;         for (int a = 0; a < 2; ++a)
; #pragma unroll
;             for (int b = 0; b < 2; ++b)
; #pragma unroll
;                 for (int m = 0; m < 4; ++m)
; #pragma unroll
;                     for (int n = 0; n < 2; ++n) acc[a][b][m][n] = (f32x4){0.f, 0.f, 0.f, 0.f};
;         cur = nxt; cA = nA; cB = nB; ++ui;
;         if (wr == 1) PG8_BAR;
.LBB0_496:
	s_andn2_b64 vcc, exec, s[48:49]
	s_mov_b64 s[0:1], -1
	v_readlane_b32 s30, v251, 4
	v_readlane_b32 s31, v251, 5
	s_cbranch_vccnz .LBB0_324
	v_readlane_b32 s0, v254, 20
	v_readlane_b32 s1, v254, 21
	s_andn2_b64 vcc, exec, s[0:1]
	s_cbranch_vccnz .LBB0_323
	s_mov_b32 s99, 0x13579bdf
	s_branch .LBB0_323

; #define PG8_STAGE(bufoff, gbase, voff) do { _Pragma("unroll") for (int _i = 0; _i < 2; ++_i) \
;         __builtin_amdgcn_global_load_lds((const unsigned*)((const char*)(gbase) + (voff)[_i]), (LAS unsigned*)(lds + (bufoff) + ldsw + _i * 8192), 16, 0, 0); } while (0)
; #define PG8_LDA(dst, b, h) do { _Pragma("unroll") for (int m = 0; m < 4; ++m) _Pragma("unroll") for (int k = 0; k < 2; ++k) dst[m][k] = *(const LAS bf16x8*)(lds + PG8_SA(b, h) + aoff + m * 2048 + k * 1024); } while (0)
; template <class Epi>
; __device__ __forceinline__ void gemm_phase(LAS unsigned char* lds, int wave_s, const Gemm g, const StaticOrder S, const Epi E) {
;     ...
;     for (;;) {
;         const bool has_next = S.next(ui + 1, nxt);
;         const char* nA = has_next ? (const char*)g.A + (size_t)nxt.pm * tstepA : cA; const char* nB = has_next ? (const char*)g.Bt + (size_t)nxt.pn * tstepB : cB;
;         for (int t = 0; t < nt; t += 2) {
;             const bool last = (t == nt - 2);
;             const char* a1 = cA + (size_t)(t + 1) * kstep;
;             const char* a2 = last ? nA : cA + (size_t)(t + 2) * kstep; const char* b2 = last ? nB : cB + (size_t)(t + 2) * kstep;
;             const char* a3 = a2 + kstep; const char* b3 = b2 + kstep;
;             PG8_LDB(B0, 0, 0); PG8_LDB(B1, 0, 1); PG8_SCHED; PG8_LDA(At, 0, 0); PG8_STAGE(PG8_SA(1, 1), a1 + hstepA, voffA);
;             PG8_WAIT_V(8); PG8_WAIT_L(0); PG8_BAR; PG8_MMA(0, 0, At, B0); PG8_MMA(0, 1, At, B1); PG8_BAR; PG8_SCHED;
;             PG8_LDA(At, 0, 1); PG8_STAGE(PG8_SB(0, 0), b2, voffB); PG8_STAGE(PG8_SB(0, 1), b2 + hstepB, voffB); PG8_STAGE(PG8_SA(0, 0), a2, voffA);
;             PG8_WAIT_V(8); PG8_WAIT_L(0); PG8_BAR; PG8_MMA(1, 0, At, B0); PG8_MMA(1, 1, At, B1); PG8_BAR; PG8_SCHED;
;             PG8_LDB(B0, 1, 0); PG8_LDB(B1, 1, 1); PG8_SCHED; PG8_LDA(At, 1, 0); PG8_STAGE(PG8_SA(0, 1), a2 + hstepA, voffA);
;             PG8_WAIT_V(8); PG8_WAIT_L(0); PG8_BAR; PG8_MMA(0, 0, At, B0); PG8_MMA(0, 1, At, B1); PG8_BAR; PG8_SCHED;
;     ...
;         if (!has_next) break;
; #pragma unroll
;         for (int a = 0; a < 2; ++a)
; #pragma unroll
;             for (int b = 0; b < 2; ++b)
; #pragma unroll
;                 for (int m = 0; m < 4; ++m)
; #pragma unroll
;                     for (int n = 0; n < 2; ++n) acc[a][b][m][n] = (f32x4){0.f, 0.f, 0.f, 0.f};
;         cur = nxt; cA = nA; cB = nB; ++ui;
;         if (wr == 1) PG8_BAR;
.LBB0_564:
	s_add_u32 s10, s20, 0x100
	v_mov_b32_e32 v2, 0
	s_addc_u32 s11, s21, 0
	s_mov_b32 s50, -2
	v_mov_b32_e32 v246, v2
	v_mov_b32_e32 v247, v2
	v_mov_b32_e32 v248, v2
	v_mov_b32_e32 v249, v2
	v_mov_b32_e32 v3, v2
	v_mov_b32_e32 v4, v2
	v_mfma_f32_32x32x16_bf16 v[18:33], v[246:249], v[246:249], 0
	v_mov_b32_e32 v5, v2
	v_mov_b32_e32 v6, v2
	v_mfma_f32_32x32x16_bf16 v[34:49], v[246:249], v[246:249], 0
	v_mov_b32_e32 v7, v2
	v_mov_b32_e32 v8, v2
	v_mfma_f32_32x32x16_bf16 v[50:65], v[246:249], v[246:249], 0
	v_mov_b32_e32 v9, v2
	v_mov_b32_e32 v10, v2
	v_mfma_f32_32x32x16_bf16 v[66:81], v[246:249], v[246:249], 0
	v_mov_b32_e32 v11, v2
	v_mov_b32_e32 v12, v2
	v_mfma_f32_32x32x16_bf16 v[82:97], v[246:249], v[246:249], 0
	v_mov_b32_e32 v13, v2
	v_mov_b32_e32 v14, v2
	v_mfma_f32_32x32x16_bf16 v[98:113], v[246:249], v[246:249], 0
	v_mov_b32_e32 v15, v2
	v_mov_b32_e32 v16, v2
	v_mfma_f32_32x32x16_bf16 v[114:129], v[246:249], v[246:249], 0
	v_mov_b32_e32 v17, v2
	s_cmp_eq_u32 s99, 0x13579bdf
	s_cbranch_scc0 .Lskw_3
	s_mov_b32 s99, 0
	s_barrier
.Lskw_3:
.LBB0_565:
	s_add_u32 s20, s18, 0x100
	s_addc_u32 s21, s19, 0
	s_add_i32 s6, 0, 0x10000
	s_cmp_eq_u32 s50, 2
	s_cselect_b32 s25, s1, s21
	s_cselect_b32 s24, s0, s20
	v_add_u32_e32 v0, s6, v166
	s_cselect_b32 s23, s17, s11
	s_cselect_b32 s22, s16, s10
	s_add_i32 s42, 0, 0x14000
	ds_read_b128 v[130:133], v0
	ds_read_b128 v[154:157], v0 offset:1024
	ds_read_b128 v[158:161], v0 offset:2048
	ds_read_b128 v[162:165], v0 offset:3072
	v_add_u32_e32 v0, s42, v166
	ds_read_b128 v[168:171], v0
	ds_read_b128 v[172:175], v0 offset:1024
	ds_read_b128 v[176:179], v0 offset:2048
	ds_read_b128 v[180:183], v0 offset:3072
	v_lshl_add_u64 v[134:135], s[18:19], 0, v[150:151]
	s_add_i32 m0, s27, 0xc000
	ds_read_b128 v[184:187], v167
	ds_read_b128 v[188:191], v167 offset:1024
	ds_read_b128 v[192:195], v167 offset:2048
	ds_read_b128 v[206:209], v167 offset:3072
	ds_read_b128 v[210:213], v167 offset:4096
	ds_read_b128 v[214:217], v167 offset:5120
	ds_read_b128 v[218:221], v167 offset:6144
	ds_read_b128 v[222:225], v167 offset:7168
	global_load_lds_dwordx4 v[134:135], off
	v_lshl_add_u64 v[134:135], s[18:19], 0, v[152:153]
	s_add_i32 m0, s27, 0xe000
	s_nop 0
	global_load_lds_dwordx4 v[134:135], off
	s_waitcnt vmcnt(8)
	s_waitcnt lgkmcnt(0)
	s_barrier
	s_cmp_eq_i32 s50, -2
	s_cbranch_scc0 .Lsq_uq_skip
	v_readlane_b32 s100, v146, 0
	v_readlane_b32 s101, v147, 0
	s_lshl_b32 s98, s40, 14
	s_lshl_b32 s99, s92, 5
	s_add_u32 s98, s98, s99
	s_add_u32 s100, s100, s98
	s_addc_u32 s101, s101, 0
	s_add_i32 m0, s99, 0x24000
	v_lshlrev_b32_e32 v243, 4, v241
	s_nop 1
	global_load_lds_dwordx4 v243, s[100:101]
	global_load_lds_dwordx4 v243, s[100:101] offset:1024

; __device__ __forceinline__ unsigned pk2(float lo, float hi) { f32x2_t v = {lo, hi}; bf16x2_t b = __builtin_convertvector(v, bf16x2_t); return __builtin_bit_cast(unsigned, b); }
; #define PG8_BAR __builtin_amdgcn_s_barrier()
; template <class Epi>
; __device__ __forceinline__ void gemm_phase(LAS unsigned char* lds, int wave_s, const Gemm g, const StaticOrder S, const Epi E) {
;     ...
;         if (!has_next) break;
; #pragma unroll
;         for (int a = 0; a < 2; ++a)
; #pragma unroll
;             for (int b = 0; b < 2; ++b)
; #pragma unroll
;                 for (int m = 0; m < 4; ++m)
; #pragma unroll
;                     for (int n = 0; n < 2; ++n) acc[a][b][m][n] = (f32x4){0.f, 0.f, 0.f, 0.f};
;         cur = nxt; cA = nA; cB = nB; ++ui;
;         if (wr == 1) PG8_BAR;
;     __device__ __forceinline__ void operator()(const f32x4 (&acc)[2][2][4][2], const Unit& u, int wr, int wc, int fr, int fq) const {
;     ...
;                     u32x4 w; w.x = pk2(v0[0], v0[1]); w.y = pk2(v0[2], v0[3]); w.z = pk2(v1[0], v1[1]); w.w = pk2(v1[2], v1[3]);
;                     *(u32x4*)(O + (size_t)row * ldc + c0 + 8 * fq) = w;
.LBB0_616:
	v_cvt_pk_bf16_f32 v6, v6, v7
	v_cvt_pk_bf16_f32 v7, v8, v9
	v_cvt_pk_bf16_f32 v8, v2, v3
	v_cvt_pk_bf16_f32 v9, v4, v5
	s_and_b64 vcc, exec, s[48:49]
	s_mov_b64 s[18:19], -1
	global_store_dwordx4 v[68:69], v[6:9], off offset:256
	s_cbranch_vccnz .LBB0_557
	s_andn2_b64 vcc, exec, s[12:13]
	s_cbranch_vccnz .LBB0_556
	s_mov_b32 s99, 0x13579bdf
	s_branch .LBB0_556

; #define PG8_STAGE(bufoff, gbase, voff) do { _Pragma("unroll") for (int _i = 0; _i < 2; ++_i) \
;         __builtin_amdgcn_global_load_lds((const unsigned*)((const char*)(gbase) + (voff)[_i]), (LAS unsigned*)(lds + (bufoff) + ldsw + _i * 8192), 16, 0, 0); } while (0)
; #define PG8_LDA(dst, b, h) do { _Pragma("unroll") for (int m = 0; m < 4; ++m) _Pragma("unroll") for (int k = 0; k < 2; ++k) dst[m][k] = *(const LAS bf16x8*)(lds + PG8_SA(b, h) + aoff + m * 2048 + k * 1024); } while (0)
; #define PG8_LDB(dst, b, h) do { _Pragma("unroll") for (int n = 0; n < 2; ++n) _Pragma("unroll") for (int k = 0; k < 2; ++k) dst[n][k] = *(const LAS bf16x8*)(lds + PG8_SB(b, h) + boff + n * 2048 + k * 1024); } while (0)
; #define PG8_WAIT_V(n) asm volatile("s_waitcnt vmcnt(" #n ")" ::: "memory")
; #define PG8_WAIT_L(n) asm volatile("s_waitcnt lgkmcnt(" #n ")" ::: "memory")
; #define PG8_BAR __builtin_amdgcn_s_barrier()
; #define PG8_SCHED __builtin_amdgcn_sched_barrier(0)
; template <class Epi>
; __device__ __forceinline__ void gemm_phase(LAS unsigned char* lds, int wave_s, const Gemm g, const StaticOrder S, const Epi E) {
;     ...
;     for (;;) {
;         const bool has_next = S.next(ui + 1, nxt);
;         const char* nA = has_next ? (const char*)g.A + (size_t)nxt.pm * tstepA : cA; const char* nB = has_next ? (const char*)g.Bt + (size_t)nxt.pn * tstepB : cB;
;         for (int t = 0; t < nt; t += 2) {
;             const bool last = (t == nt - 2);
;             const char* a1 = cA + (size_t)(t + 1) * kstep;
;             const char* a2 = last ? nA : cA + (size_t)(t + 2) * kstep; const char* b2 = last ? nB : cB + (size_t)(t + 2) * kstep;
;             const char* a3 = a2 + kstep; const char* b3 = b2 + kstep;
;             PG8_LDB(B0, 0, 0); PG8_LDB(B1, 0, 1); PG8_SCHED; PG8_LDA(At, 0, 0); PG8_STAGE(PG8_SA(1, 1), a1 + hstepA, voffA);
;             PG8_WAIT_V(8); PG8_WAIT_L(0); PG8_BAR; PG8_MMA(0, 0, At, B0); PG8_MMA(0, 1, At, B1); PG8_BAR; PG8_SCHED;
;     ...
;         if (!has_next) break;
; #pragma unroll
;         for (int a = 0; a < 2; ++a)
; #pragma unroll
;             for (int b = 0; b < 2; ++b)
; #pragma unroll
;                 for (int m = 0; m < 4; ++m)
; #pragma unroll
;                     for (int n = 0; n < 2; ++n) acc[a][b][m][n] = (f32x4){0.f, 0.f, 0.f, 0.f};
;         cur = nxt; cA = nA; cB = nB; ++ui;
;         if (wr == 1) PG8_BAR;
.LBB0_634:
	s_ashr_i32 s17, s16, 31
	s_lshl_b64 s[6:7], s[16:17], 17
	v_readlane_b32 s10, v255, 55
	v_readlane_b32 s11, v255, 56
	s_add_u32 s20, s10, s6
	s_addc_u32 s21, s11, s7
	s_and_b64 s[0:1], s[0:1], exec
	v_mov_b32_e32 v2, 0
	s_cselect_b32 s17, s21, s23
	s_cselect_b32 s10, s20, s22
	s_mov_b32 s11, 0
	s_mov_b64 s[0:1], -1
	s_mov_b64 s[26:27], 0
	v_mov_b32_e32 v246, v2
	v_mov_b32_e32 v247, v2
	v_mov_b32_e32 v248, v2
	v_mov_b32_e32 v249, v2
	v_mov_b32_e32 v3, v2
	v_mov_b32_e32 v4, v2
	v_mfma_f32_32x32x16_bf16 v[18:33], v[246:249], v[246:249], 0
	v_mov_b32_e32 v5, v2
	v_mov_b32_e32 v6, v2
	v_mfma_f32_32x32x16_bf16 v[34:49], v[246:249], v[246:249], 0
	v_mov_b32_e32 v7, v2
	v_mov_b32_e32 v8, v2
	v_mfma_f32_32x32x16_bf16 v[50:65], v[246:249], v[246:249], 0
	v_mov_b32_e32 v9, v2
	v_mov_b32_e32 v10, v2
	v_mfma_f32_32x32x16_bf16 v[66:81], v[246:249], v[246:249], 0
	v_mov_b32_e32 v11, v2
	v_mov_b32_e32 v12, v2
	v_mfma_f32_32x32x16_bf16 v[82:97], v[246:249], v[246:249], 0
	v_mov_b32_e32 v13, v2
	v_mov_b32_e32 v14, v2
	v_mfma_f32_32x32x16_bf16 v[98:113], v[246:249], v[246:249], 0
	v_mov_b32_e32 v15, v2
	v_mov_b32_e32 v16, v2
	v_mfma_f32_32x32x16_bf16 v[114:129], v[246:249], v[246:249], 0
	v_mov_b32_e32 v17, v2
	s_cmp_eq_u32 s99, 0x13579bdf
	s_cbranch_scc0 .Lskw_4
	s_mov_b32 s99, 0
	s_barrier
.Lskw_4:
.LBB0_635:
	s_add_u32 s12, s24, s11
	s_addc_u32 s13, s25, 0
	s_add_u32 s28, s12, 0x100
	s_addc_u32 s29, s13, 0
	s_and_b64 s[6:7], s[26:27], exec
	s_cselect_b32 s31, s19, s29
	s_cselect_b32 s30, s18, s28
	s_add_u32 s6, s22, s11
	s_addc_u32 s7, s23, 0
	s_add_u32 s11, s6, 0x100
	s_addc_u32 s28, s7, 0
	s_add_i32 s43, 0, 0x10000
	s_and_b64 s[6:7], s[26:27], exec
	s_cselect_b32 s35, s17, s28
	s_cselect_b32 s34, s10, s11
	s_add_i32 s6, 0, 0x14000
	s_add_u32 s48, s12, 0x210080
	s_addc_u32 s49, s13, 0
	s_add_i32 s12, s43, s37
	s_add_i32 m0, s95, 0xc000
	s_add_i32 s40, s95, 0xe000
	s_add_i32 s59, s12, 0x2000
	v_add_u32_e32 v134, s43, v161
	s_add_u32 s38, s34, 0x10000
	ds_read_b128 v[130:133], v134
	ds_read_b128 v[146:149], v134 offset:1024
	ds_read_b128 v[150:153], v134 offset:2048
	ds_read_b128 v[154:157], v134 offset:3072
	v_add_u32_e32 v134, s6, v161
	s_addc_u32 s39, s35, 0
	s_add_i32 s13, s6, s37
	ds_read_b128 v[164:167], v134
	ds_read_b128 v[168:171], v134 offset:1024
	ds_read_b128 v[172:175], v134 offset:2048
	ds_read_b128 v[176:179], v134 offset:3072
	s_add_i32 s42, s13, 0x2000
	s_add_i32 vcc_lo, 0, 0x18000
	s_add_i32 vcc_hi, 0, 0x1c000
	s_add_u32 s28, s30, 0x210000
	s_addc_u32 s29, s31, 0
	s_add_i32 s11, vcc_lo, s37
	s_add_i32 s58, s11, 0x2000
	s_add_u32 s26, s34, 0x10080
	s_addc_u32 s27, s35, 0
	s_add_i32 s7, vcc_hi, s37
	s_add_i32 s6, s7, 0x2000
	v_lshl_add_u64 v[134:135], s[48:49], 0, v[142:143]
	ds_read_b128 v[180:183], v163
	ds_read_b128 v[184:187], v163 offset:1024
	ds_read_b128 v[188:191], v163 offset:2048
	ds_read_b128 v[192:195], v163 offset:3072
	ds_read_b128 v[206:209], v163 offset:4096
	ds_read_b128 v[210:213], v163 offset:5120
	ds_read_b128 v[214:217], v163 offset:6144
	ds_read_b128 v[218:221], v163 offset:7168
	global_load_lds_dwordx4 v[134:135], off
	v_lshl_add_u64 v[134:135], s[48:49], 0, v[138:139]
	s_mov_b32 m0, s40
	s_nop 0
	global_load_lds_dwordx4 v[134:135], off
	s_waitcnt vmcnt(8)
	s_waitcnt lgkmcnt(0)
	s_barrier
	s_cmp_lg_u64 s[0:1], 0
	s_cbranch_scc0 .Lsq_ukv_skip
	v_readlane_b32 s100, v144, 0
	v_readlane_b32 s101, v145, 0
	s_lshl_b32 s98, s53, 13
	s_lshl_b32 s99, s92, 4
	s_add_u32 s98, s98, s99
	s_add_u32 s100, s100, s98
	s_addc_u32 s101, s101, 0
	s_add_i32 m0, s99, 0x24000
	v_lshlrev_b32_e32 v243, 4, v241
	s_nop 1
	global_load_lds_dwordx4 v243, s[100:101]

;     __device__ __forceinline__ void operator()(const f32x4 (&acc)[2][2][4][2], const Unit& u, int wr, int wc, int fr, int fq) const {
;     ...
;             for (int m = 0; m < 4; ++m) rsv[ai][m] = ssq_in ? rsqrtf(row_ssq(ssq_in, in_pitch, in_n4, row0 + ai * HALF + m * 16, fq) * inv_k + EPS) : 1.f;
; #pragma unroll
;         for (int bj = 0; bj < 2; ++bj) {
;             const int c0 = u.pn * BM + bj * HALF + wc * 32;
;             float scale = 1.f; bool sig = false, rp = false, st = true; float* sq = nullptr; int sqp = 0;
;             if (mode == 1) { const int slab = c0 >> 7;
;                 if (slab < 3) { sq = ssq_q + 4 * slab + wc; sqp = 16; } else if (slab < 5) { sq = ssq_kv + 4 * (slab - 3) + wc; sqp = 8; } else if (slab == 5) { rp = (wc == 0); st = (wc == 0); }
;                 else if (slab < 14) scale = C2_64; else if (slab < 18) {} else if (slab < 26) scale = C2_64; else if (slab < 42) {} else sig = true;
;             } else if (mode == 2) { rp = ((c0 % 96) == 64); scale = C2_96; }
;             if (!st) continue;
; #pragma unroll
;             for (int ai = 0; ai < 2; ++ai)
; #pragma unroll
;                 for (int m = 0; m < 4; ++m) {
;                     const int row = row0 + ai * HALF + m * 16; const float rs = rsv[ai][m] * scale;
;                     f32x4 v0 = acc[ai][bj][m][0] * rs, v1 = acc[ai][bj][m][1] * rs;
;                     if (rp) {
;                         const int pos = row & (SEQ - 1); const float* rb = rope + pos * 32 + 8 * (fq & 1); const bool hi2 = (fq >> 1) != 0;
;                         const f32x4 cs0 = *(const f32x4*)(rb), cs1 = *(const f32x4*)(rb + 4), sn0 = *(const f32x4*)(rb + 16), sn1 = *(const f32x4*)(rb + 20);
; #pragma unroll
;                         for (int e = 0; e < 4; ++e) { const float q0 = __shfl_xor(v0[e], 32), q1 = __shfl_xor(v1[e], 32);
;                             v0[e] = hi2 ? v0[e] * cs0[e] + q0 * sn0[e] : v0[e] * cs0[e] - q0 * sn0[e];
;                             v1[e] = hi2 ? v1[e] * cs1[e] + q1 * sn1[e] : v1[e] * cs1[e] - q1 * sn1[e]; } }
;                     if (sig) {
; #pragma unroll
;                         for (int e = 0; e < 4; ++e) { v0[e] = fast_sigmoid(v0[e]); v1[e] = fast_sigmoid(v1[e]); } }
;                     if (sq) { float s = (v0[0] * v0[0] + v0[1] * v0[1]) + (v0[2] * v0[2] + v0[3] * v0[3]) + (v1[0] * v1[0] + v1[1] * v1[1]) + (v1[2] * v1[2] + v1[3] * v1[3]);
.LBB0_654:
	s_or_b64 exec, exec, s[0:1]
	s_waitcnt lgkmcnt(0)
	v_add_f32_e32 v132, v134, v135
	v_fmamk_f32 v132, v132, 0x3b800000, v239
	s_mov_b32 s0, 0x800000
	v_cmp_gt_f32_e32 vcc, s0, v132
	v_mul_f32_e32 v133, 0x4b800000, v132
	v_pk_add_f32 v[130:131], v[168:169], v[130:131]
	v_cndmask_b32_e32 v132, v132, v133, vcc
	v_rsq_f32_e32 v132, v132
	v_add_f32_e32 v130, v130, v131
	v_mov_b32_e32 v131, v130
	s_nop 1
	v_permlane16_swap_b32_e32 v130, v131
	v_readlane_b32 s1, v254, 20
	v_mul_f32_e32 v133, 0x45800000, v132
	v_cndmask_b32_e32 v132, v132, v133, vcc
	v_add_f32_e32 v133, v175, v176
	v_fmamk_f32 v133, v133, 0x3b800000, v239
	v_cmp_gt_f32_e32 vcc, s0, v133
	v_mul_f32_e32 v134, 0x4b800000, v133
	s_waitcnt lgkmcnt(0)
	v_add_f32_e32 v130, v130, v131
	v_cndmask_b32_e32 v133, v133, v134, vcc
	v_rsq_f32_e32 v133, v133
	v_mov_b32_e32 v131, v130
	s_nop 1
	v_permlane32_swap_b32_e32 v130, v131
	v_readlane_b32 s10, v250, 45
	v_readlane_b32 s11, v250, 46
	v_mul_f32_e32 v134, 0x45800000, v133
	v_cndmask_b32_e32 v134, v133, v134, vcc
	v_add_f32_e32 v133, v158, v174
	v_fmamk_f32 v133, v133, 0x3b800000, v239
	v_cmp_gt_f32_e32 vcc, s0, v133
	v_mul_f32_e32 v135, 0x4b800000, v133
	s_waitcnt lgkmcnt(0)
	v_add_f32_e32 v130, v130, v131
	v_cndmask_b32_e32 v133, v133, v135, vcc
	v_rsq_f32_e32 v133, v133
	v_fmamk_f32 v130, v130, 0x3b800000, v239
	v_mul_f32_e32 v131, 0x4b800000, v130
	s_mov_b64 s[6:7], 0x90000
	v_mul_f32_e32 v135, 0x45800000, v133
	v_cndmask_b32_e32 v158, v133, v135, vcc
	v_add_f32_e32 v133, v160, v173
	v_fmamk_f32 v133, v133, 0x3b800000, v239
	v_cmp_gt_f32_e32 vcc, s0, v133
	v_mul_f32_e32 v135, 0x4b800000, v133
	v_pk_mul_f32 v[94:95], v[94:95], v[158:159] op_sel_hi:[1,0]
	v_cndmask_b32_e32 v133, v133, v135, vcc
	v_rsq_f32_e32 v133, v133
	v_pk_mul_f32 v[96:97], v[96:97], v[158:159] op_sel_hi:[1,0]
	v_pk_mul_f32 v[32:33], v[32:33], v[158:159] op_sel_hi:[1,0]
	v_pk_mul_f32 v[30:31], v[30:31], v[158:159] op_sel_hi:[1,0]
	v_mul_f32_e32 v135, 0x45800000, v133
	v_cndmask_b32_e32 v160, v133, v135, vcc
	v_add_f32_e32 v133, v162, v172
	v_fmamk_f32 v133, v133, 0x3b800000, v239
	v_cmp_gt_f32_e32 vcc, s0, v133
	v_mul_f32_e32 v135, 0x4b800000, v133
	v_pk_mul_f32 v[102:103], v[102:103], v[160:161] op_sel_hi:[1,0]
	v_cndmask_b32_e32 v133, v133, v135, vcc
	v_rsq_f32_e32 v133, v133
	v_pk_mul_f32 v[104:105], v[104:105], v[160:161] op_sel_hi:[1,0]
	v_pk_mul_f32 v[40:41], v[40:41], v[160:161] op_sel_hi:[1,0]
	v_pk_mul_f32 v[38:39], v[38:39], v[160:161] op_sel_hi:[1,0]
	v_mul_f32_e32 v135, 0x45800000, v133
	v_cndmask_b32_e32 v162, v133, v135, vcc
	v_add_f32_e32 v133, v164, v171
	v_fmamk_f32 v133, v133, 0x3b800000, v239
	v_cmp_gt_f32_e32 vcc, s0, v133
	v_mul_f32_e32 v135, 0x4b800000, v133
	v_pk_mul_f32 v[110:111], v[110:111], v[162:163] op_sel_hi:[1,0]
	v_cndmask_b32_e32 v133, v133, v135, vcc
	v_rsq_f32_e32 v133, v133
	v_pk_mul_f32 v[112:113], v[112:113], v[162:163] op_sel_hi:[1,0]
	v_pk_mul_f32 v[48:49], v[48:49], v[162:163] op_sel_hi:[1,0]
	v_pk_mul_f32 v[46:47], v[46:47], v[162:163] op_sel_hi:[1,0]
	v_mul_f32_e32 v135, 0x45800000, v133
	v_cndmask_b32_e32 v164, v133, v135, vcc
	v_add_f32_e32 v133, v166, v170
	v_fmamk_f32 v133, v133, 0x3b800000, v239
	v_cmp_gt_f32_e32 vcc, s0, v133
	v_mul_f32_e32 v135, 0x4b800000, v133
	v_pk_mul_f32 v[118:119], v[118:119], v[164:165] op_sel_hi:[1,0]
	v_cndmask_b32_e32 v133, v133, v135, vcc
	v_rsq_f32_e32 v133, v133
	v_pk_mul_f32 v[120:121], v[120:121], v[164:165] op_sel_hi:[1,0]
	v_pk_mul_f32 v[58:59], v[58:59], v[164:165] op_sel_hi:[1,0]
	v_mul_f32_e32 v135, 0x45800000, v133
	v_cndmask_b32_e32 v166, v133, v135, vcc
	v_cmp_gt_f32_e32 vcc, s0, v130
	s_lshl_b32 s0, s4, 8
	s_or_b32 s0, s0, s1
	v_pk_mul_f32 v[126:127], v[126:127], v[166:167] op_sel_hi:[1,0]
	s_ashr_i32 s1, s0, 31
	v_pk_mul_f32 v[168:169], v[124:125], v[166:167] op_sel_hi:[1,0]
	v_pk_mul_f32 v[124:125], v[122:123], v[166:167] op_sel_hi:[1,0]
	v_cvt_pk_bf16_f32 v122, v126, v127
	v_lshlrev_b64 v[126:127], 12, v[146:147]
	v_lshl_add_u64 v[126:127], s[10:11], 0, v[126:127]
	s_lshl_b64 s[0:1], s[0:1], 1
	v_pk_mul_f32 v[128:129], v[128:129], v[166:167] op_sel_hi:[1,0]
	v_lshl_add_u64 v[126:127], v[126:127], 0, s[0:1]
	v_cvt_pk_bf16_f32 v123, v128, v129
	v_cvt_pk_bf16_f32 v124, v124, v125
	v_cvt_pk_bf16_f32 v125, v168, v169
	v_lshl_add_u64 v[126:127], v[126:127], 0, v[0:1]
	global_store_dwordx4 v[126:127], v[122:125], off
	v_cndmask_b32_e32 v130, v130, v131, vcc
	v_rsq_f32_e32 v130, v130
	v_pk_mul_f32 v[122:123], v[116:117], v[164:165] op_sel_hi:[1,0]
	v_pk_mul_f32 v[116:117], v[114:115], v[164:165] op_sel_hi:[1,0]
	v_cvt_pk_bf16_f32 v114, v118, v119
	v_lshlrev_b64 v[118:119], 12, v[148:149]
	v_lshl_add_u64 v[118:119], s[10:11], 0, v[118:119]
	v_lshl_add_u64 v[118:119], v[118:119], 0, s[0:1]
	v_cvt_pk_bf16_f32 v115, v120, v121
	v_cvt_pk_bf16_f32 v116, v116, v117
	v_cvt_pk_bf16_f32 v117, v122, v123
	v_lshl_add_u64 v[118:119], v[118:119], 0, v[0:1]
	global_store_dwordx4 v[118:119], v[114:117], off
	v_mul_f32_e32 v131, 0x45800000, v130
	v_pk_mul_f32 v[88:89], v[88:89], v[134:135] op_sel_hi:[1,0]
	v_pk_mul_f32 v[114:115], v[108:109], v[162:163] op_sel_hi:[1,0]
	v_pk_mul_f32 v[108:109], v[106:107], v[162:163] op_sel_hi:[1,0]
	v_cvt_pk_bf16_f32 v106, v110, v111
	v_lshlrev_b64 v[110:111], 12, v[150:151]
	v_lshl_add_u64 v[110:111], s[10:11], 0, v[110:111]
	v_lshl_add_u64 v[110:111], v[110:111], 0, s[0:1]
	v_cvt_pk_bf16_f32 v107, v112, v113
	v_cvt_pk_bf16_f32 v108, v108, v109
	v_cvt_pk_bf16_f32 v109, v114, v115
	v_lshl_add_u64 v[110:111], v[110:111], 0, v[0:1]
	global_store_dwordx4 v[110:111], v[106:109], off
	s_mov_b32 s4, 0x90000
	v_cndmask_b32_e32 v130, v130, v131, vcc
; #define PG8_BAR __builtin_amdgcn_s_barrier()
; template <class Epi>
; __device__ __forceinline__ void gemm_phase(LAS unsigned char* lds, int wave_s, const Gemm g, const StaticOrder S, const Epi E) {
;     ...
;         if (!has_next) break;
; #pragma unroll
;         for (int a = 0; a < 2; ++a)
; #pragma unroll
;             for (int b = 0; b < 2; ++b)
; #pragma unroll
;                 for (int m = 0; m < 4; ++m)
; #pragma unroll
;                     for (int n = 0; n < 2; ++n) acc[a][b][m][n] = (f32x4){0.f, 0.f, 0.f, 0.f};
;         cur = nxt; cA = nA; cB = nB; ++ui;
;         if (wr == 1) PG8_BAR;
;     __device__ __forceinline__ void operator()(const f32x4 (&acc)[2][2][4][2], const Unit& u, int wr, int wc, int fr, int fq) const {
;     ...
;             for (int ai = 0; ai < 2; ++ai)
; #pragma unroll
;                 for (int m = 0; m < 4; ++m) {
;                     const int row = row0 + ai * HALF + m * 16; const float rs = rsv[ai][m] * scale;
;                     f32x4 v0 = acc[ai][bj][m][0] * rs, v1 = acc[ai][bj][m][1] * rs;
;                     if (rp) {
;                         const int pos = row & (SEQ - 1); const float* rb = rope + pos * 32 + 8 * (fq & 1); const bool hi2 = (fq >> 1) != 0;
;                         const f32x4 cs0 = *(const f32x4*)(rb), cs1 = *(const f32x4*)(rb + 4), sn0 = *(const f32x4*)(rb + 16), sn1 = *(const f32x4*)(rb + 20);
; #pragma unroll
;                         for (int e = 0; e < 4; ++e) { const float q0 = __shfl_xor(v0[e], 32), q1 = __shfl_xor(v1[e], 32);
;                             v0[e] = hi2 ? v0[e] * cs0[e] + q0 * sn0[e] : v0[e] * cs0[e] - q0 * sn0[e];
;                             v1[e] = hi2 ? v1[e] * cs1[e] + q1 * sn1[e] : v1[e] * cs1[e] - q1 * sn1[e]; } }
;                     if (sig) {
; #pragma unroll
;                         for (int e = 0; e < 4; ++e) { v0[e] = fast_sigmoid(v0[e]); v1[e] = fast_sigmoid(v1[e]); } }
;                     if (sq) { float s = (v0[0] * v0[0] + v0[1] * v0[1]) + (v0[2] * v0[2] + v0[3] * v0[3]) + (v1[0] * v1[0] + v1[1] * v1[1]) + (v1[2] * v1[2] + v1[3] * v1[3]);
;                         s += __shfl_xor(s, 16); s += __shfl_xor(s, 32); if (fq == 0) sq[(size_t)row * sqp] = s; }
;                     u32x4 w; w.x = pk2(v0[0], v0[1]); w.y = pk2(v0[2], v0[3]); w.z = pk2(v1[0], v1[1]); w.w = pk2(v1[2], v1[3]);
;                     *(u32x4*)(O + (size_t)row * ldc + c0 + 8 * fq) = w;
	v_pk_mul_f32 v[106:107], v[100:101], v[160:161] op_sel_hi:[1,0]
	v_pk_mul_f32 v[100:101], v[98:99], v[160:161] op_sel_hi:[1,0]
	v_cvt_pk_bf16_f32 v98, v102, v103
	v_lshlrev_b64 v[102:103], 12, v[152:153]
	v_lshl_add_u64 v[102:103], s[10:11], 0, v[102:103]
	v_lshl_add_u64 v[102:103], v[102:103], 0, s[0:1]
	v_cvt_pk_bf16_f32 v99, v104, v105
	v_cvt_pk_bf16_f32 v100, v100, v101
	v_cvt_pk_bf16_f32 v101, v106, v107
	v_lshl_add_u64 v[102:103], v[102:103], 0, v[0:1]
	global_store_dwordx4 v[102:103], v[98:101], off
	v_pk_mul_f32 v[86:87], v[86:87], v[134:135] op_sel_hi:[1,0]
	v_pk_mul_f32 v[76:77], v[76:77], v[132:133] op_sel_hi:[1,0]
	v_pk_mul_f32 v[98:99], v[92:93], v[158:159] op_sel_hi:[1,0]
	v_pk_mul_f32 v[92:93], v[90:91], v[158:159] op_sel_hi:[1,0]
	v_cvt_pk_bf16_f32 v90, v94, v95
	v_lshlrev_b64 v[94:95], 12, v[154:155]
	v_lshl_add_u64 v[94:95], s[10:11], 0, v[94:95]
	v_lshl_add_u64 v[94:95], v[94:95], 0, s[0:1]
	v_cvt_pk_bf16_f32 v91, v96, v97
	v_cvt_pk_bf16_f32 v92, v92, v93
	v_cvt_pk_bf16_f32 v93, v98, v99
	v_lshl_add_u64 v[94:95], v[94:95], 0, v[0:1]
	global_store_dwordx4 v[94:95], v[90:93], off
	v_pk_mul_f32 v[74:75], v[74:75], v[132:133] op_sel_hi:[1,0]
	v_pk_mul_f32 v[54:55], v[54:55], v[130:131] op_sel_hi:[1,0]
	v_pk_mul_f32 v[90:91], v[84:85], v[134:135] op_sel_hi:[1,0]
	v_pk_mul_f32 v[84:85], v[82:83], v[134:135] op_sel_hi:[1,0]
	v_cvt_pk_bf16_f32 v83, v88, v89
	v_add_co_u32_e32 v88, vcc, s4, v126
	v_cvt_pk_bf16_f32 v82, v86, v87
	v_cvt_pk_bf16_f32 v84, v84, v85
	v_cvt_pk_bf16_f32 v85, v90, v91
	v_addc_co_u32_e32 v89, vcc, 0, v127, vcc
	s_mov_b32 s4, 0xa0000
	global_store_dwordx4 v[88:89], v[82:85], off
	v_pk_mul_f32 v[56:57], v[56:57], v[130:131] op_sel_hi:[1,0]
	v_pk_mul_f32 v[24:25], v[24:25], v[134:135] op_sel_hi:[1,0]
	v_pk_mul_f32 v[82:83], v[68:69], v[132:133] op_sel_hi:[1,0]
	v_pk_mul_f32 v[68:69], v[66:67], v[132:133] op_sel_hi:[1,0]
	v_cvt_pk_bf16_f32 v67, v76, v77
	v_add_co_u32_e32 v76, vcc, s4, v126
	v_cvt_pk_bf16_f32 v66, v74, v75
	v_cvt_pk_bf16_f32 v68, v68, v69
	v_cvt_pk_bf16_f32 v69, v82, v83
	v_addc_co_u32_e32 v77, vcc, 0, v127, vcc
	global_store_dwordx4 v[76:77], v[66:69], off
	v_pk_mul_f32 v[22:23], v[22:23], v[134:135] op_sel_hi:[1,0]
	v_lshl_add_u64 v[86:87], v[126:127], 0, s[6:7]
	v_pk_mul_f32 v[66:67], v[52:53], v[130:131] op_sel_hi:[1,0]
	v_pk_mul_f32 v[52:53], v[50:51], v[130:131] op_sel_hi:[1,0]
	v_cvt_pk_bf16_f32 v50, v54, v55
	v_lshlrev_b64 v[54:55], 12, v[156:157]
	v_lshl_add_u64 v[54:55], s[10:11], 0, v[54:55]
	v_lshl_add_u64 v[54:55], v[54:55], 0, s[0:1]
	v_cvt_pk_bf16_f32 v51, v56, v57
	v_cvt_pk_bf16_f32 v52, v52, v53
	v_cvt_pk_bf16_f32 v53, v66, v67
	v_lshl_add_u64 v[54:55], v[54:55], 0, v[0:1]
	global_store_dwordx4 v[54:55], v[50:53], off
	v_pk_mul_f32 v[56:57], v[72:73], v[166:167] op_sel_hi:[1,0]
	v_pk_mul_f32 v[66:67], v[70:71], v[166:167] op_sel_hi:[1,0]
	v_pk_mul_f32 v[52:53], v[80:81], v[166:167] op_sel_hi:[1,0]
	v_pk_mul_f32 v[50:51], v[78:79], v[166:167] op_sel_hi:[1,0]
	s_mov_b64 s[6:7], 0xa0000
	v_cvt_pk_bf16_f32 v50, v50, v51
	v_cvt_pk_bf16_f32 v51, v52, v53
	v_cvt_pk_bf16_f32 v52, v66, v67
	v_cvt_pk_bf16_f32 v53, v56, v57
	global_store_dwordx4 v[126:127], v[50:53], off offset:256
	v_pk_mul_f32 v[56:57], v[60:61], v[164:165] op_sel_hi:[1,0]
	v_pk_mul_f32 v[16:17], v[16:17], v[132:133] op_sel_hi:[1,0]
	v_pk_mul_f32 v[52:53], v[64:65], v[164:165] op_sel_hi:[1,0]
	v_pk_mul_f32 v[50:51], v[62:63], v[164:165] op_sel_hi:[1,0]
	v_pk_mul_f32 v[14:15], v[14:15], v[132:133] op_sel_hi:[1,0]
	v_cvt_pk_bf16_f32 v50, v50, v51
	v_cvt_pk_bf16_f32 v51, v52, v53
	v_cvt_pk_bf16_f32 v52, v58, v59
	v_cvt_pk_bf16_f32 v53, v56, v57
	global_store_dwordx4 v[118:119], v[50:53], off offset:256
	v_lshl_add_u64 v[74:75], v[126:127], 0, s[6:7]
	v_pk_mul_f32 v[8:9], v[8:9], v[130:131] op_sel_hi:[1,0]
	v_pk_mul_f32 v[50:51], v[44:45], v[162:163] op_sel_hi:[1,0]
	v_pk_mul_f32 v[44:45], v[42:43], v[162:163] op_sel_hi:[1,0]
	v_cvt_pk_bf16_f32 v42, v46, v47
	v_cvt_pk_bf16_f32 v43, v48, v49
	v_cvt_pk_bf16_f32 v44, v44, v45
	v_cvt_pk_bf16_f32 v45, v50, v51
	global_store_dwordx4 v[110:111], v[42:45], off offset:256
	v_pk_mul_f32 v[6:7], v[6:7], v[130:131] op_sel_hi:[1,0]
	s_mov_b64 s[0:1], -1
	v_pk_mul_f32 v[42:43], v[36:37], v[160:161] op_sel_hi:[1,0]
	v_pk_mul_f32 v[36:37], v[34:35], v[160:161] op_sel_hi:[1,0]
	v_cvt_pk_bf16_f32 v34, v38, v39
	v_cvt_pk_bf16_f32 v35, v40, v41
	v_cvt_pk_bf16_f32 v36, v36, v37
	v_cvt_pk_bf16_f32 v37, v42, v43
	global_store_dwordx4 v[102:103], v[34:37], off offset:256
	s_and_b64 vcc, exec, s[46:47]
	s_nop 0
	v_pk_mul_f32 v[34:35], v[28:29], v[158:159] op_sel_hi:[1,0]
	v_pk_mul_f32 v[28:29], v[26:27], v[158:159] op_sel_hi:[1,0]
	v_cvt_pk_bf16_f32 v26, v30, v31
	v_cvt_pk_bf16_f32 v27, v32, v33
	v_cvt_pk_bf16_f32 v28, v28, v29
	v_cvt_pk_bf16_f32 v29, v34, v35
	global_store_dwordx4 v[94:95], v[26:29], off offset:256
	s_nop 1
	v_pk_mul_f32 v[26:27], v[20:21], v[134:135] op_sel_hi:[1,0]
	v_pk_mul_f32 v[20:21], v[18:19], v[134:135] op_sel_hi:[1,0]
	v_cvt_pk_bf16_f32 v18, v22, v23
	v_cvt_pk_bf16_f32 v19, v24, v25
	v_cvt_pk_bf16_f32 v20, v20, v21
	v_cvt_pk_bf16_f32 v21, v26, v27
	global_store_dwordx4 v[86:87], v[18:21], off offset:256
	s_nop 1
	v_pk_mul_f32 v[18:19], v[12:13], v[132:133] op_sel_hi:[1,0]
	v_pk_mul_f32 v[12:13], v[10:11], v[132:133] op_sel_hi:[1,0]
	v_cvt_pk_bf16_f32 v10, v14, v15
	v_cvt_pk_bf16_f32 v11, v16, v17
	v_cvt_pk_bf16_f32 v12, v12, v13
	v_cvt_pk_bf16_f32 v13, v18, v19
	global_store_dwordx4 v[74:75], v[10:13], off offset:256
	s_nop 1
	v_pk_mul_f32 v[10:11], v[4:5], v[130:131] op_sel_hi:[1,0]
	v_pk_mul_f32 v[4:5], v[2:3], v[130:131] op_sel_hi:[1,0]
	v_cvt_pk_bf16_f32 v2, v6, v7
	v_cvt_pk_bf16_f32 v3, v8, v9
	v_cvt_pk_bf16_f32 v4, v4, v5
	v_cvt_pk_bf16_f32 v5, v10, v11
	global_store_dwordx4 v[54:55], v[2:5], off offset:256
	s_cbranch_vccnz .LBB0_625
	v_readlane_b32 s0, v254, 22
	v_readlane_b32 s1, v254, 23
	s_andn2_b64 vcc, exec, s[0:1]
	s_cbranch_vccnz .LBB0_624
	s_mov_b32 s99, 0x13579bdf
	s_branch .LBB0_624

; #define PG8_BAR __builtin_amdgcn_s_barrier()
; template <class Epi>
; __device__ __forceinline__ void gemm_phase(LAS unsigned char* lds, int wave_s, const Gemm g, const StaticOrder S, const Epi E) {
;     ...
;     for (;;) {
;         const bool has_next = S.next(ui + 1, nxt);
;         const char* nA = has_next ? (const char*)g.A + (size_t)nxt.pm * tstepA : cA; const char* nB = has_next ? (const char*)g.Bt + (size_t)nxt.pn * tstepB : cB;
;         for (int t = 0; t < nt; t += 2) {
;             const bool last = (t == nt - 2);
;             const char* a1 = cA + (size_t)(t + 1) * kstep;
;             const char* a2 = last ? nA : cA + (size_t)(t + 2) * kstep; const char* b2 = last ? nB : cB + (size_t)(t + 2) * kstep;
;     ...
;         if (!has_next) break;
; #pragma unroll
;         for (int a = 0; a < 2; ++a)
; #pragma unroll
;             for (int b = 0; b < 2; ++b)
; #pragma unroll
;                 for (int m = 0; m < 4; ++m)
; #pragma unroll
;                     for (int n = 0; n < 2; ++n) acc[a][b][m][n] = (f32x4){0.f, 0.f, 0.f, 0.f};
;         cur = nxt; cA = nA; cB = nB; ++ui;
;         if (wr == 1) PG8_BAR;
.LBB0_1067:
	s_ashr_i32 s21, s20, 31
	s_lshl_b64 s[6:7], s[20:21], 19
	v_readlane_b32 s10, v253, 6
	v_readlane_b32 s11, v253, 7
	s_add_u32 s24, s10, s6
	s_addc_u32 s25, s11, s7
	s_and_b64 s[0:1], s[0:1], exec
	s_cselect_b32 s10, s25, s29
	s_cselect_b32 s11, s24, s28
	s_add_u32 s21, s28, 0x100
	v_mov_b32_e32 v2, 0
	s_addc_u32 s52, s29, 0
	s_mov_b32 s53, -2
	v_mov_b32_e32 v246, v2
	v_mov_b32_e32 v247, v2
	v_mov_b32_e32 v248, v2
	v_mov_b32_e32 v249, v2
	v_mov_b32_e32 v3, v2
	v_mov_b32_e32 v4, v2
	v_mfma_f32_32x32x16_bf16 v[18:33], v[246:249], v[246:249], 0
	v_mov_b32_e32 v5, v2
	v_mov_b32_e32 v6, v2
	v_mfma_f32_32x32x16_bf16 v[34:49], v[246:249], v[246:249], 0
	v_mov_b32_e32 v7, v2
	v_mov_b32_e32 v8, v2
	v_mfma_f32_32x32x16_bf16 v[50:65], v[246:249], v[246:249], 0
	v_mov_b32_e32 v9, v2
	v_mov_b32_e32 v10, v2
	v_mfma_f32_32x32x16_bf16 v[66:81], v[246:249], v[246:249], 0
	v_mov_b32_e32 v11, v2
	v_mov_b32_e32 v12, v2
	v_mfma_f32_32x32x16_bf16 v[82:97], v[246:249], v[246:249], 0
	v_mov_b32_e32 v13, v2
	v_mov_b32_e32 v14, v2
	v_mfma_f32_32x32x16_bf16 v[98:113], v[246:249], v[246:249], 0
	v_mov_b32_e32 v15, v2
	v_mov_b32_e32 v16, v2
	v_mfma_f32_32x32x16_bf16 v[114:129], v[246:249], v[246:249], 0
	v_mov_b32_e32 v17, v2
	s_cmp_eq_u32 s99, 0x13579bdf
	s_cbranch_scc0 .Lskw_5
	s_mov_b32 s99, 0
	s_barrier
.Lskw_5:
.LBB0_1068:
	s_cmp_eq_u32 s53, 6
	s_cbranch_scc0 .Lpre_wout_skip
	v_readlane_b32 s100, v254, 18
	v_readlane_b32 s101, v254, 19
	s_mov_b64 s[98:99], s[14:15]
	v_lshl_add_u32 v243, s40, 8, v160
	v_lshl_or_b32 v246, s4, 8, v162
	v_lshl_add_u32 v243, v243, 10, v246
	v_lshlrev_b32_e32 v243, 1, v243
	s_nop 1
	global_load_dwordx4 v[226:229], v243, s[100:101]
	global_load_dwordx4 v[230:233], v243, s[98:99]
	global_load_dwordx4 v[234:237], v243, s[100:101] offset:256
	global_load_dwordx4 v[242:245], v243, s[98:99] offset:256

; #define PG8_BAR __builtin_amdgcn_s_barrier()
; template <class Epi>
; __device__ __forceinline__ void gemm_phase(LAS unsigned char* lds, int wave_s, const Gemm g, const StaticOrder S, const Epi E) {
;     ...
;         if (!has_next) break;
; #pragma unroll
;         for (int a = 0; a < 2; ++a)
; #pragma unroll
;             for (int b = 0; b < 2; ++b)
; #pragma unroll
;                 for (int m = 0; m < 4; ++m)
; #pragma unroll
;                     for (int n = 0; n < 2; ++n) acc[a][b][m][n] = (f32x4){0.f, 0.f, 0.f, 0.f};
;         cur = nxt; cA = nA; cB = nB; ++ui;
;         if (wr == 1) PG8_BAR;
.Lepir_wout_skip:
	s_or_b64 exec, exec, s[26:27]
	s_and_b64 vcc, exec, s[46:47]
	s_mov_b64 s[0:1], -1
	s_cbranch_vccnz .LBB0_1058
	s_andn2_b64 vcc, exec, s[12:13]
	s_cbranch_vccnz .LBB0_1057
	s_mov_b32 s99, 0x13579bdf
	s_branch .LBB0_1057

; #define PG8_STAGE(bufoff, gbase, voff) do { _Pragma("unroll") for (int _i = 0; _i < 2; ++_i) \
;         __builtin_amdgcn_global_load_lds((const unsigned*)((const char*)(gbase) + (voff)[_i]), (LAS unsigned*)(lds + (bufoff) + ldsw + _i * 8192), 16, 0, 0); } while (0)
; #define PG8_LDA(dst, b, h) do { _Pragma("unroll") for (int m = 0; m < 4; ++m) _Pragma("unroll") for (int k = 0; k < 2; ++k) dst[m][k] = *(const LAS bf16x8*)(lds + PG8_SA(b, h) + aoff + m * 2048 + k * 1024); } while (0)
; #define PG8_LDB(dst, b, h) do { _Pragma("unroll") for (int n = 0; n < 2; ++n) _Pragma("unroll") for (int k = 0; k < 2; ++k) dst[n][k] = *(const LAS bf16x8*)(lds + PG8_SB(b, h) + boff + n * 2048 + k * 1024); } while (0)
; #define PG8_BAR __builtin_amdgcn_s_barrier()
; #define PG8_SCHED __builtin_amdgcn_sched_barrier(0)
; template <class Epi>
; __device__ __forceinline__ void gemm_phase(LAS unsigned char* lds, int wave_s, const Gemm g, const StaticOrder S, const Epi E) {
;     ...
;     for (;;) {
;         const bool has_next = S.next(ui + 1, nxt);
;         const char* nA = has_next ? (const char*)g.A + (size_t)nxt.pm * tstepA : cA; const char* nB = has_next ? (const char*)g.Bt + (size_t)nxt.pn * tstepB : cB;
;         for (int t = 0; t < nt; t += 2) {
;             const bool last = (t == nt - 2);
;             const char* a1 = cA + (size_t)(t + 1) * kstep;
;             const char* a2 = last ? nA : cA + (size_t)(t + 2) * kstep; const char* b2 = last ? nB : cB + (size_t)(t + 2) * kstep;
;             const char* a3 = a2 + kstep; const char* b3 = b2 + kstep;
;             PG8_LDB(B0, 0, 0); PG8_LDB(B1, 0, 1); PG8_SCHED; PG8_LDA(At, 0, 0); PG8_STAGE(PG8_SA(1, 1), a1 + hstepA, voffA);
;     ...
;         if (!has_next) break;
; #pragma unroll
;         for (int a = 0; a < 2; ++a)
; #pragma unroll
;             for (int b = 0; b < 2; ++b)
; #pragma unroll
;                 for (int m = 0; m < 4; ++m)
; #pragma unroll
;                     for (int n = 0; n < 2; ++n) acc[a][b][m][n] = (f32x4){0.f, 0.f, 0.f, 0.f};
;         cur = nxt; cA = nA; cB = nB; ++ui;
;         if (wr == 1) PG8_BAR;
.LBB0_1150:
	s_ashr_i32 s17, s16, 31
	s_lshl_b64 s[6:7], s[16:17], 19
	v_readlane_b32 s10, v253, 35
	v_readlane_b32 s11, v253, 36
	s_add_u32 s18, s10, s6
	s_addc_u32 s19, s11, s7
	s_and_b64 s[6:7], s[42:43], exec
	s_cselect_b32 s17, s19, s23
	s_cselect_b32 s40, s18, s22
	s_ashr_i32 s15, s14, 31
	s_lshl_b64 s[6:7], s[14:15], 19
	v_readlane_b32 s10, v252, 54
	v_readlane_b32 s11, v252, 55
	s_add_u32 s20, s10, s6
	s_addc_u32 s21, s11, s7
	s_and_b64 s[6:7], s[42:43], exec
	s_cselect_b32 s10, s21, s25
	s_cselect_b32 s11, s20, s24
	s_add_u32 s22, s22, 0x40080
	s_addc_u32 s23, s23, 0
	s_add_u32 s15, s24, 0x100
	v_mov_b32_e32 v2, 0
	s_addc_u32 s44, s25, 0
	s_mov_b32 s45, -2
	v_mov_b32_e32 v246, v2
	v_mov_b32_e32 v247, v2
	v_mov_b32_e32 v248, v2
	v_mov_b32_e32 v249, v2
	v_mov_b32_e32 v3, v2
	v_mov_b32_e32 v4, v2
	v_mfma_f32_32x32x16_bf16 v[18:33], v[246:249], v[246:249], 0
	v_mov_b32_e32 v5, v2
	v_mov_b32_e32 v6, v2
	v_mfma_f32_32x32x16_bf16 v[34:49], v[246:249], v[246:249], 0
	v_mov_b32_e32 v7, v2
	v_mov_b32_e32 v8, v2
	v_mfma_f32_32x32x16_bf16 v[50:65], v[246:249], v[246:249], 0
	v_mov_b32_e32 v9, v2
	v_mov_b32_e32 v10, v2
	v_mfma_f32_32x32x16_bf16 v[66:81], v[246:249], v[246:249], 0
	v_mov_b32_e32 v11, v2
	v_mov_b32_e32 v12, v2
	v_mfma_f32_32x32x16_bf16 v[82:97], v[246:249], v[246:249], 0
	v_mov_b32_e32 v13, v2
	v_mov_b32_e32 v14, v2
	v_mfma_f32_32x32x16_bf16 v[98:113], v[246:249], v[246:249], 0
	v_mov_b32_e32 v15, v2
	v_mov_b32_e32 v16, v2
	v_mfma_f32_32x32x16_bf16 v[114:129], v[246:249], v[246:249], 0
	v_mov_b32_e32 v17, v2
	s_cmp_eq_u32 s99, 0x13579bdf
	s_cbranch_scc0 .Lskw_6
	s_mov_b32 s99, 0
	s_barrier
.Lskw_6:
.LBB0_1151:
	s_cmp_eq_u32 s45, 6
	s_cbranch_scc0 .Lsq_ffn2up_skip
	v_readlane_b32 s100, v136, 0
	v_readlane_b32 s101, v137, 0
	s_lshl_b32 s6, s39, 14
	s_lshl_b32 s7, s92, 5
	s_add_u32 s6, s6, s7
	s_add_u32 s100, s100, s6
	s_addc_u32 s101, s101, 0
	s_add_i32 m0, s7, 0x24000
	v_lshlrev_b32_e32 v243, 4, v241
	s_nop 1
	global_load_lds_dwordx4 v243, s[100:101]
	global_load_lds_dwordx4 v243, s[100:101] offset:1024

; __device__ __forceinline__ float row_ssq(const float* part, int pitch, int n4, int row, int fq) {
;     f32x4 v = (f32x4){0.f, 0.f, 0.f, 0.f};
;     if (fq < n4) v = *(const f32x4*)(part + (size_t)row * pitch + 4 * fq);
;     float s = (v[0] + v[1]) + (v[2] + v[3]);
;     s += __shfl_xor(s, 16); s += __shfl_xor(s, 32);
;     return s;
; }
;     __device__ __forceinline__ void operator()(const f32x4 (&acc)[2][2][4][2], const Unit& u, int wr, int wc, int fr, int fq) const {
;         const int row0 = u.pm * BM + wr * 64 + fr, col0 = u.pn * 128 + wc * 32 + 8 * fq;
; #pragma unroll
;         for (int ai = 0; ai < 2; ++ai)
; #pragma unroll
;             for (int m = 0; m < 4; ++m) {
;                 const int row = row0 + ai * HALF + m * 16;
;                 const float rs = rsqrtf(row_ssq(ssq, 16, 4, row, fq) * (1.f / 1024.f) + EPS);
.LBB0_1154:
	v_and_b32_e32 v145, 64, v241
	v_xor_b32_e32 v143, 16, v241
	v_add_u32_e32 v145, 64, v145
	v_cmp_lt_i32_e32 vcc, v143, v145
	v_lshl_add_u32 v144, s39, 8, v146
	v_lshl_or_b32 v142, s4, 7, v148
	v_cndmask_b32_e32 v143, v241, v143, vcc
	v_lshlrev_b32_e32 v150, 2, v143
	v_xor_b32_e32 v143, 32, v241
	v_cmp_lt_i32_e32 vcc, v143, v145
	v_ashrrev_i32_e32 v145, 31, v144
	v_and_b32_e32 v166, 48, v241
	v_lshl_add_u32 v166, v146, 6, v166
	v_add_u32_e32 v166, 0x24000, v166
	ds_read_b128 v[168:171], v166
	ds_read_b128 v[172:175], v166 offset:1024
	ds_read_b128 v[176:179], v166 offset:2048
	ds_read_b128 v[180:183], v166 offset:3072
	v_cndmask_b32_e32 v143, v241, v143, vcc
	v_lshlrev_b32_e32 v151, 2, v143
	ds_read_b128 v[184:187], v166 offset:8192
	ds_read_b128 v[188:191], v166 offset:9216
	ds_read_b128 v[192:195], v166 offset:10240
	ds_read_b128 v[196:199], v166 offset:11264
	v_ashrrev_i32_e32 v143, 31, v142
	v_lshl_add_u64 v[142:143], v[142:143], 1, s[96:97]
	s_movk_i32 s4, 0x1600
	s_mov_b64 s[22:23], -1
	s_waitcnt lgkmcnt(7)
	v_add_f32_e32 v168, v169, v168
	v_add_f32_e32 v170, v170, v171
	v_add_f32_e32 v168, v168, v170
	v_mov_b32_e32 v169, v168
	s_nop 1
	v_permlane16_swap_b32_e32 v168, v169
	s_waitcnt lgkmcnt(6)
	v_add_f32_e32 v172, v173, v172
	v_add_f32_e32 v174, v174, v175
	v_add_f32_e32 v172, v172, v174
	v_mov_b32_e32 v173, v172
	s_nop 1
	v_permlane16_swap_b32_e32 v172, v173
	s_waitcnt lgkmcnt(5)
	v_add_f32_e32 v176, v177, v176
	v_add_f32_e32 v178, v178, v179
	v_add_f32_e32 v176, v176, v178
	v_mov_b32_e32 v177, v176
	s_nop 1
	v_permlane16_swap_b32_e32 v176, v177
	s_waitcnt lgkmcnt(4)
	v_add_f32_e32 v180, v181, v180
	v_add_f32_e32 v182, v182, v183
	v_add_f32_e32 v180, v180, v182
	v_mov_b32_e32 v181, v180
	s_nop 1
	v_permlane16_swap_b32_e32 v180, v181
	s_waitcnt lgkmcnt(3)
	v_add_f32_e32 v184, v185, v184
	v_add_f32_e32 v186, v186, v187
	v_add_f32_e32 v184, v184, v186
	v_mov_b32_e32 v185, v184
	s_nop 1
	v_permlane16_swap_b32_e32 v184, v185
	s_waitcnt lgkmcnt(2)
	v_add_f32_e32 v188, v189, v188
	v_add_f32_e32 v190, v190, v191
	v_add_f32_e32 v188, v188, v190
	v_mov_b32_e32 v189, v188
	s_nop 1
	v_permlane16_swap_b32_e32 v188, v189
	s_waitcnt lgkmcnt(1)
	v_add_f32_e32 v192, v193, v192
	v_add_f32_e32 v194, v194, v195
	v_add_f32_e32 v192, v192, v194
	v_mov_b32_e32 v193, v192
	s_nop 1
	v_permlane16_swap_b32_e32 v192, v193
	s_waitcnt lgkmcnt(0)
	v_add_f32_e32 v196, v197, v196
	v_add_f32_e32 v198, v198, v199
	v_add_f32_e32 v196, v196, v198
	v_mov_b32_e32 v197, v196
	s_nop 1
	v_permlane16_swap_b32_e32 v196, v197
	s_waitcnt lgkmcnt(7)
	v_add_f32_e32 v168, v168, v169
	v_mov_b32_e32 v169, v168
	s_nop 1
	v_permlane32_swap_b32_e32 v168, v169
	s_waitcnt lgkmcnt(7)
	v_add_f32_e32 v172, v172, v173
	v_mov_b32_e32 v173, v172
	s_nop 1
	v_permlane32_swap_b32_e32 v172, v173
	s_waitcnt lgkmcnt(7)
	v_add_f32_e32 v176, v176, v177
	v_mov_b32_e32 v177, v176
	s_nop 1
	v_permlane32_swap_b32_e32 v176, v177
	s_waitcnt lgkmcnt(7)
	v_add_f32_e32 v180, v180, v181
	v_mov_b32_e32 v181, v180
	s_nop 1
	v_permlane32_swap_b32_e32 v180, v181
	s_waitcnt lgkmcnt(7)
	v_add_f32_e32 v184, v184, v185
	v_mov_b32_e32 v185, v184
	s_nop 1
	v_permlane32_swap_b32_e32 v184, v185
	s_waitcnt lgkmcnt(7)
	v_add_f32_e32 v188, v188, v189
	v_mov_b32_e32 v189, v188
	s_nop 1
	v_permlane32_swap_b32_e32 v188, v189
	s_waitcnt lgkmcnt(7)
	v_add_f32_e32 v192, v192, v193
	v_mov_b32_e32 v193, v192
	s_nop 1
	v_permlane32_swap_b32_e32 v192, v193
	s_waitcnt lgkmcnt(7)
	v_add_f32_e32 v196, v196, v197
	v_mov_b32_e32 v197, v196
	s_nop 1
	v_permlane32_swap_b32_e32 v196, v197
	s_waitcnt lgkmcnt(7)
	v_add_f32_e32 v168, v168, v169
	v_fmamk_f32 v168, v168, 0x3a800000, v239
	s_waitcnt lgkmcnt(6)
	v_add_f32_e32 v172, v172, v173
	v_fmamk_f32 v172, v172, 0x3a800000, v239
	s_waitcnt lgkmcnt(5)
	v_add_f32_e32 v176, v176, v177
	v_fmamk_f32 v176, v176, 0x3a800000, v239
	s_waitcnt lgkmcnt(4)
	v_add_f32_e32 v180, v180, v181
	v_fmamk_f32 v180, v180, 0x3a800000, v239
	s_waitcnt lgkmcnt(3)
	v_add_f32_e32 v184, v184, v185
	v_fmamk_f32 v184, v184, 0x3a800000, v239
	s_waitcnt lgkmcnt(2)
	v_add_f32_e32 v188, v188, v189
	v_fmamk_f32 v188, v188, 0x3a800000, v239
	s_waitcnt lgkmcnt(1)
	v_add_f32_e32 v192, v192, v193
	v_fmamk_f32 v192, v192, 0x3a800000, v239
	s_waitcnt lgkmcnt(0)
; __device__ __forceinline__ unsigned pk2(float lo, float hi) { f32x2_t v = {lo, hi}; bf16x2_t b = __builtin_convertvector(v, bf16x2_t); return __builtin_bit_cast(unsigned, b); }
; __device__ __forceinline__ float fast_sigmoid(float x) { return __builtin_amdgcn_rcpf(1.f + __expf(-x)); }
;     __device__ __forceinline__ void operator()(const f32x4 (&acc)[2][2][4][2], const Unit& u, int wr, int wc, int fr, int fq) const {
;     ...
;                 const int row = row0 + ai * HALF + m * 16;
;                 const float rs = rsqrtf(row_ssq(ssq, 16, 4, row, fq) * (1.f / 1024.f) + EPS);
;                 float r[8];
; #pragma unroll
;                 for (int n = 0; n < 2; ++n)
; #pragma unroll
;                     for (int e = 0; e < 4; ++e) { const float gv = acc[ai][0][m][n][e] * rs, uv = acc[ai][1][m][n][e] * rs; r[n * 4 + e] = gv * fast_sigmoid(gv) * uv; }
;                 u32x4 w; w.x = pk2(r[0], r[1]); w.y = pk2(r[2], r[3]); w.z = pk2(r[4], r[5]); w.w = pk2(r[6], r[7]);
;                 *(u32x4*)(O + (size_t)row * DFF + col0) = w;
	v_add_f32_e32 v196, v196, v197
	v_fmamk_f32 v196, v196, 0x3a800000, v239
	v_cmp_gt_f32_e32 vcc, s55, v168
	v_mul_f32_e32 v169, 0x4b800000, v168
	s_nop 0
	v_cndmask_b32_e32 v168, v168, v169, vcc
	v_rsq_f32_e32 v168, v168
	s_nop 0
	v_mul_f32_e32 v169, 0x45800000, v168
	v_cndmask_b32_e32 v158, v168, v169, vcc
	v_cmp_gt_f32_e32 vcc, s55, v172
	v_mul_f32_e32 v173, 0x4b800000, v172
	s_nop 0
	v_cndmask_b32_e32 v172, v172, v173, vcc
	v_rsq_f32_e32 v172, v172
	s_nop 0
	v_mul_f32_e32 v173, 0x45800000, v172
	v_cndmask_b32_e32 v159, v172, v173, vcc
	v_cmp_gt_f32_e32 vcc, s55, v176
	v_mul_f32_e32 v177, 0x4b800000, v176
	s_nop 0
	v_cndmask_b32_e32 v176, v176, v177, vcc
	v_rsq_f32_e32 v176, v176
	s_nop 0
	v_mul_f32_e32 v177, 0x45800000, v176
	v_cndmask_b32_e32 v160, v176, v177, vcc
	v_cmp_gt_f32_e32 vcc, s55, v180
	v_mul_f32_e32 v181, 0x4b800000, v180
	s_nop 0
	v_cndmask_b32_e32 v180, v180, v181, vcc
	v_rsq_f32_e32 v180, v180
	s_nop 0
	v_mul_f32_e32 v181, 0x45800000, v180
	v_cndmask_b32_e32 v161, v180, v181, vcc
	v_cmp_gt_f32_e32 vcc, s55, v184
	v_mul_f32_e32 v185, 0x4b800000, v184
	s_nop 0
	v_cndmask_b32_e32 v184, v184, v185, vcc
	v_rsq_f32_e32 v184, v184
	s_nop 0
	v_mul_f32_e32 v185, 0x45800000, v184
	v_cndmask_b32_e32 v162, v184, v185, vcc
	v_cmp_gt_f32_e32 vcc, s55, v188
	v_mul_f32_e32 v189, 0x4b800000, v188
	s_nop 0
	v_cndmask_b32_e32 v188, v188, v189, vcc
	v_rsq_f32_e32 v188, v188
	s_nop 0
	v_mul_f32_e32 v189, 0x45800000, v188
	v_cndmask_b32_e32 v163, v188, v189, vcc
	v_cmp_gt_f32_e32 vcc, s55, v192
	v_mul_f32_e32 v193, 0x4b800000, v192
	s_nop 0
	v_cndmask_b32_e32 v192, v192, v193, vcc
	v_rsq_f32_e32 v192, v192
	s_nop 0
	v_mul_f32_e32 v193, 0x45800000, v192
	v_cndmask_b32_e32 v164, v192, v193, vcc
	v_cmp_gt_f32_e32 vcc, s55, v196
	v_mul_f32_e32 v197, 0x4b800000, v196
	s_nop 0
	v_cndmask_b32_e32 v196, v196, v197, vcc
	v_rsq_f32_e32 v196, v196
	s_nop 0
	v_mul_f32_e32 v197, 0x45800000, v196
	v_cndmask_b32_e32 v165, v196, v197, vcc
	v_mov_b32_e32 v152, v158
	v_pk_mul_f32 v[126:127], v[126:127], v[152:153] op_sel_hi:[1,0]
	v_pk_mul_f32 v[118:119], v[118:119], v[152:153] op_sel_hi:[1,0]
	v_mul_f32_e32 v145, 0xbfb8aa3b, v126
	v_exp_f32_e32 v145, v145
	v_pk_mul_f32 v[120:121], v[120:121], v[152:153] op_sel_hi:[1,0]
	v_pk_mul_f32 v[122:123], v[122:123], v[152:153] op_sel_hi:[1,0]
	v_pk_mul_f32 v[114:115], v[114:115], v[152:153] op_sel_hi:[1,0]
	v_add_f32_e32 v145, 1.0, v145
	v_rcp_f32_e32 v154, v145
	v_mul_f32_e32 v145, 0xbfb8aa3b, v127
	v_exp_f32_e32 v145, v145
	v_pk_mul_f32 v[116:117], v[116:117], v[152:153] op_sel_hi:[1,0]
	v_add_f32_e32 v145, 1.0, v145
	v_rcp_f32_e32 v155, v145
	s_nop 0
	v_pk_mul_f32 v[126:127], v[126:127], v[154:155]
	s_nop 0
	v_pk_mul_f32 v[118:119], v[118:119], v[126:127]
	v_pk_mul_f32 v[126:127], v[128:129], v[152:153] op_sel_hi:[1,0]
	s_nop 0
	v_mul_f32_e32 v128, 0xbfb8aa3b, v126
	v_mul_f32_e32 v129, 0xbfb8aa3b, v127
	v_exp_f32_e32 v128, v128
	v_exp_f32_e32 v129, v129
	v_add_f32_e32 v128, 1.0, v128
	v_add_f32_e32 v129, 1.0, v129
	v_rcp_f32_e32 v128, v128
	v_rcp_f32_e32 v129, v129
	s_nop 0
	v_pk_mul_f32 v[126:127], v[126:127], v[128:129]
	s_nop 0
	v_pk_mul_f32 v[120:121], v[120:121], v[126:127]
	v_mul_f32_e32 v126, 0xbfb8aa3b, v122
	v_mul_f32_e32 v127, 0xbfb8aa3b, v123
	v_exp_f32_e32 v126, v126
	v_exp_f32_e32 v127, v127
	v_add_f32_e32 v126, 1.0, v126
	v_add_f32_e32 v127, 1.0, v127
	v_rcp_f32_e32 v126, v126
	v_rcp_f32_e32 v127, v127
	s_nop 0
	v_pk_mul_f32 v[122:123], v[122:123], v[126:127]
	s_nop 0
	v_pk_mul_f32 v[122:123], v[114:115], v[122:123]
	v_pk_mul_f32 v[114:115], v[124:125], v[152:153] op_sel_hi:[1,0]
	s_nop 0
	v_mul_f32_e32 v124, 0xbfb8aa3b, v114
	v_mul_f32_e32 v125, 0xbfb8aa3b, v115
	v_exp_f32_e32 v124, v124
	v_exp_f32_e32 v125, v125
	v_add_f32_e32 v124, 1.0, v124
	v_add_f32_e32 v125, 1.0, v125
	v_rcp_f32_e32 v124, v124
	v_rcp_f32_e32 v125, v125
	s_nop 0
	v_pk_mul_f32 v[114:115], v[114:115], v[124:125]
	s_nop 0
	v_pk_mul_f32 v[124:125], v[116:117], v[114:115]
	v_cvt_pk_bf16_f32 v114, v118, v119
	v_cvt_pk_bf16_f32 v115, v120, v121
	v_cvt_pk_bf16_f32 v116, v122, v123
	v_cvt_pk_bf16_f32 v117, v124, v125
	v_mad_i64_i32 v[118:119], s[6:7], v144, s4, v[142:143]
	global_store_dwordx4 v[118:119], v[114:117], off
	s_nop 1
	v_or_b32_e32 v114, 16, v144
	v_mov_b32_e32 v116, v159
	v_pk_mul_f32 v[110:111], v[110:111], v[116:117] op_sel_hi:[1,0]
	v_pk_mul_f32 v[102:103], v[102:103], v[116:117] op_sel_hi:[1,0]
	v_mul_f32_e32 v115, 0xbfb8aa3b, v110
	v_exp_f32_e32 v115, v115
	v_pk_mul_f32 v[104:105], v[104:105], v[116:117] op_sel_hi:[1,0]
	v_pk_mul_f32 v[106:107], v[106:107], v[116:117] op_sel_hi:[1,0]
	v_pk_mul_f32 v[98:99], v[98:99], v[116:117] op_sel_hi:[1,0]
	v_add_f32_e32 v115, 1.0, v115
	v_rcp_f32_e32 v118, v115
	v_mul_f32_e32 v115, 0xbfb8aa3b, v111
	v_exp_f32_e32 v115, v115
	v_pk_mul_f32 v[100:101], v[100:101], v[116:117] op_sel_hi:[1,0]
	v_add_f32_e32 v115, 1.0, v115
	v_rcp_f32_e32 v119, v115
	s_nop 0
	v_pk_mul_f32 v[110:111], v[110:111], v[118:119]
	s_nop 0
	v_pk_mul_f32 v[102:103], v[102:103], v[110:111]
	v_pk_mul_f32 v[110:111], v[112:113], v[116:117] op_sel_hi:[1,0]
	s_nop 0
	v_mul_f32_e32 v112, 0xbfb8aa3b, v110
	v_mul_f32_e32 v113, 0xbfb8aa3b, v111
	v_exp_f32_e32 v112, v112
	v_exp_f32_e32 v113, v113
	v_add_f32_e32 v112, 1.0, v112
	v_add_f32_e32 v113, 1.0, v113
	v_rcp_f32_e32 v112, v112
	v_rcp_f32_e32 v113, v113
	s_nop 0
	v_pk_mul_f32 v[110:111], v[110:111], v[112:113]
	s_nop 0
	v_pk_mul_f32 v[104:105], v[104:105], v[110:111]
	v_mul_f32_e32 v110, 0xbfb8aa3b, v106
	v_mul_f32_e32 v111, 0xbfb8aa3b, v107
	v_exp_f32_e32 v110, v110
	v_exp_f32_e32 v111, v111
	v_add_f32_e32 v110, 1.0, v110
	v_add_f32_e32 v111, 1.0, v111
; __device__ __forceinline__ unsigned pk2(float lo, float hi) { f32x2_t v = {lo, hi}; bf16x2_t b = __builtin_convertvector(v, bf16x2_t); return __builtin_bit_cast(unsigned, b); }
; __device__ __forceinline__ float fast_sigmoid(float x) { return __builtin_amdgcn_rcpf(1.f + __expf(-x)); }
;     __device__ __forceinline__ void operator()(const f32x4 (&acc)[2][2][4][2], const Unit& u, int wr, int wc, int fr, int fq) const {
;     ...
;                 float r[8];
; #pragma unroll
;                 for (int n = 0; n < 2; ++n)
; #pragma unroll
;                     for (int e = 0; e < 4; ++e) { const float gv = acc[ai][0][m][n][e] * rs, uv = acc[ai][1][m][n][e] * rs; r[n * 4 + e] = gv * fast_sigmoid(gv) * uv; }
;                 u32x4 w; w.x = pk2(r[0], r[1]); w.y = pk2(r[2], r[3]); w.z = pk2(r[4], r[5]); w.w = pk2(r[6], r[7]);
;                 *(u32x4*)(O + (size_t)row * DFF + col0) = w;
	v_rcp_f32_e32 v110, v110
	v_rcp_f32_e32 v111, v111
	s_nop 0
	v_pk_mul_f32 v[106:107], v[106:107], v[110:111]
	s_nop 0
	v_pk_mul_f32 v[106:107], v[98:99], v[106:107]
	v_pk_mul_f32 v[98:99], v[108:109], v[116:117] op_sel_hi:[1,0]
	s_nop 0
	v_mul_f32_e32 v108, 0xbfb8aa3b, v98
	v_mul_f32_e32 v109, 0xbfb8aa3b, v99
	v_exp_f32_e32 v108, v108
	v_exp_f32_e32 v109, v109
	v_add_f32_e32 v108, 1.0, v108
	v_add_f32_e32 v109, 1.0, v109
	v_rcp_f32_e32 v108, v108
	v_rcp_f32_e32 v109, v109
	s_nop 0
	v_pk_mul_f32 v[98:99], v[98:99], v[108:109]
	s_nop 0
	v_pk_mul_f32 v[108:109], v[100:101], v[98:99]
	v_cvt_pk_bf16_f32 v98, v102, v103
	v_cvt_pk_bf16_f32 v99, v104, v105
	v_cvt_pk_bf16_f32 v100, v106, v107
	v_cvt_pk_bf16_f32 v101, v108, v109
	v_mad_i64_i32 v[102:103], s[6:7], v114, s4, v[142:143]
	global_store_dwordx4 v[102:103], v[98:101], off
	s_nop 1
	v_or_b32_e32 v98, 32, v144
	v_mov_b32_e32 v100, v160
	v_pk_mul_f32 v[94:95], v[94:95], v[100:101] op_sel_hi:[1,0]
	v_pk_mul_f32 v[86:87], v[86:87], v[100:101] op_sel_hi:[1,0]
	v_mul_f32_e32 v99, 0xbfb8aa3b, v94
	v_exp_f32_e32 v99, v99
	v_pk_mul_f32 v[88:89], v[88:89], v[100:101] op_sel_hi:[1,0]
	v_pk_mul_f32 v[90:91], v[90:91], v[100:101] op_sel_hi:[1,0]
	v_pk_mul_f32 v[82:83], v[82:83], v[100:101] op_sel_hi:[1,0]
	v_add_f32_e32 v99, 1.0, v99
	v_rcp_f32_e32 v102, v99
	v_mul_f32_e32 v99, 0xbfb8aa3b, v95
	v_exp_f32_e32 v99, v99
	v_pk_mul_f32 v[84:85], v[84:85], v[100:101] op_sel_hi:[1,0]
	v_add_f32_e32 v99, 1.0, v99
	v_rcp_f32_e32 v103, v99
	s_nop 0
	v_pk_mul_f32 v[94:95], v[94:95], v[102:103]
	s_nop 0
	v_pk_mul_f32 v[86:87], v[86:87], v[94:95]
	v_pk_mul_f32 v[94:95], v[96:97], v[100:101] op_sel_hi:[1,0]
	s_nop 0
	v_mul_f32_e32 v96, 0xbfb8aa3b, v94
	v_mul_f32_e32 v97, 0xbfb8aa3b, v95
	v_exp_f32_e32 v96, v96
	v_exp_f32_e32 v97, v97
	v_add_f32_e32 v96, 1.0, v96
	v_add_f32_e32 v97, 1.0, v97
	v_rcp_f32_e32 v96, v96
	v_rcp_f32_e32 v97, v97
	s_nop 0
	v_pk_mul_f32 v[94:95], v[94:95], v[96:97]
	s_nop 0
	v_pk_mul_f32 v[88:89], v[88:89], v[94:95]
	v_mul_f32_e32 v94, 0xbfb8aa3b, v90
	v_mul_f32_e32 v95, 0xbfb8aa3b, v91
	v_exp_f32_e32 v94, v94
	v_exp_f32_e32 v95, v95
	v_add_f32_e32 v94, 1.0, v94
	v_add_f32_e32 v95, 1.0, v95
	v_rcp_f32_e32 v94, v94
	v_rcp_f32_e32 v95, v95
	s_nop 0
	v_pk_mul_f32 v[90:91], v[90:91], v[94:95]
	s_nop 0
	v_pk_mul_f32 v[90:91], v[82:83], v[90:91]
	v_pk_mul_f32 v[82:83], v[92:93], v[100:101] op_sel_hi:[1,0]
	s_nop 0
	v_mul_f32_e32 v92, 0xbfb8aa3b, v82
	v_mul_f32_e32 v93, 0xbfb8aa3b, v83
	v_exp_f32_e32 v92, v92
	v_exp_f32_e32 v93, v93
	v_add_f32_e32 v92, 1.0, v92
	v_add_f32_e32 v93, 1.0, v93
	v_rcp_f32_e32 v92, v92
	v_rcp_f32_e32 v93, v93
	s_nop 0
	v_pk_mul_f32 v[82:83], v[82:83], v[92:93]
	s_nop 0
	v_pk_mul_f32 v[92:93], v[84:85], v[82:83]
	v_cvt_pk_bf16_f32 v82, v86, v87
	v_cvt_pk_bf16_f32 v83, v88, v89
	v_cvt_pk_bf16_f32 v84, v90, v91
	v_cvt_pk_bf16_f32 v85, v92, v93
	v_mad_i64_i32 v[86:87], s[6:7], v98, s4, v[142:143]
	global_store_dwordx4 v[86:87], v[82:85], off
	s_nop 1
	v_or_b32_e32 v82, 48, v144
	v_mov_b32_e32 v84, v161
	v_pk_mul_f32 v[78:79], v[78:79], v[84:85] op_sel_hi:[1,0]
	v_pk_mul_f32 v[70:71], v[70:71], v[84:85] op_sel_hi:[1,0]
	v_mul_f32_e32 v83, 0xbfb8aa3b, v78
	v_exp_f32_e32 v83, v83
	v_pk_mul_f32 v[72:73], v[72:73], v[84:85] op_sel_hi:[1,0]
	v_pk_mul_f32 v[74:75], v[74:75], v[84:85] op_sel_hi:[1,0]
	v_pk_mul_f32 v[66:67], v[66:67], v[84:85] op_sel_hi:[1,0]
	v_add_f32_e32 v83, 1.0, v83
	v_rcp_f32_e32 v86, v83
	v_mul_f32_e32 v83, 0xbfb8aa3b, v79
	v_exp_f32_e32 v83, v83
	v_pk_mul_f32 v[68:69], v[68:69], v[84:85] op_sel_hi:[1,0]
	v_add_f32_e32 v83, 1.0, v83
	v_rcp_f32_e32 v87, v83
	s_nop 0
	v_pk_mul_f32 v[78:79], v[78:79], v[86:87]
	s_nop 0
	v_pk_mul_f32 v[70:71], v[70:71], v[78:79]
	v_pk_mul_f32 v[78:79], v[80:81], v[84:85] op_sel_hi:[1,0]
	s_nop 0
	v_mul_f32_e32 v80, 0xbfb8aa3b, v78
	v_mul_f32_e32 v81, 0xbfb8aa3b, v79
	v_exp_f32_e32 v80, v80
	v_exp_f32_e32 v81, v81
	v_add_f32_e32 v80, 1.0, v80
	v_add_f32_e32 v81, 1.0, v81
	v_rcp_f32_e32 v80, v80
	v_rcp_f32_e32 v81, v81
	s_nop 0
	v_pk_mul_f32 v[78:79], v[78:79], v[80:81]
	s_nop 0
	v_pk_mul_f32 v[72:73], v[72:73], v[78:79]
	v_mul_f32_e32 v78, 0xbfb8aa3b, v74
	v_mul_f32_e32 v79, 0xbfb8aa3b, v75
	v_exp_f32_e32 v78, v78
	v_exp_f32_e32 v79, v79
	v_add_f32_e32 v78, 1.0, v78
	v_add_f32_e32 v79, 1.0, v79
	v_rcp_f32_e32 v78, v78
	v_rcp_f32_e32 v79, v79
	s_nop 0
	v_pk_mul_f32 v[74:75], v[74:75], v[78:79]
	s_nop 0
	v_pk_mul_f32 v[74:75], v[66:67], v[74:75]
	v_pk_mul_f32 v[66:67], v[76:77], v[84:85] op_sel_hi:[1,0]
	s_nop 0
	v_mul_f32_e32 v76, 0xbfb8aa3b, v66
	v_mul_f32_e32 v77, 0xbfb8aa3b, v67
	v_exp_f32_e32 v76, v76
	v_exp_f32_e32 v77, v77
	v_add_f32_e32 v76, 1.0, v76
	v_add_f32_e32 v77, 1.0, v77
	v_rcp_f32_e32 v76, v76
	v_rcp_f32_e32 v77, v77
	s_nop 0
	v_pk_mul_f32 v[66:67], v[66:67], v[76:77]
	s_nop 0
	v_pk_mul_f32 v[76:77], v[68:69], v[66:67]
	v_cvt_pk_bf16_f32 v66, v70, v71
	v_cvt_pk_bf16_f32 v67, v72, v73
	v_cvt_pk_bf16_f32 v68, v74, v75
	v_cvt_pk_bf16_f32 v69, v76, v77
	v_mad_i64_i32 v[70:71], s[6:7], v82, s4, v[142:143]
	global_store_dwordx4 v[70:71], v[66:69], off
	s_nop 1
	v_add_u32_e32 v66, 0x80, v144
	v_mov_b32_e32 v68, v162
	v_pk_mul_f32 v[62:63], v[62:63], v[68:69] op_sel_hi:[1,0]
	v_pk_mul_f32 v[54:55], v[54:55], v[68:69] op_sel_hi:[1,0]
	v_mul_f32_e32 v67, 0xbfb8aa3b, v62
	v_exp_f32_e32 v67, v67
	v_pk_mul_f32 v[56:57], v[56:57], v[68:69] op_sel_hi:[1,0]
	v_pk_mul_f32 v[58:59], v[58:59], v[68:69] op_sel_hi:[1,0]
	v_pk_mul_f32 v[50:51], v[50:51], v[68:69] op_sel_hi:[1,0]
	v_add_f32_e32 v67, 1.0, v67
	v_rcp_f32_e32 v70, v67
	v_mul_f32_e32 v67, 0xbfb8aa3b, v63
	v_exp_f32_e32 v67, v67
	v_pk_mul_f32 v[52:53], v[52:53], v[68:69] op_sel_hi:[1,0]
; __device__ __forceinline__ unsigned pk2(float lo, float hi) { f32x2_t v = {lo, hi}; bf16x2_t b = __builtin_convertvector(v, bf16x2_t); return __builtin_bit_cast(unsigned, b); }
; __device__ __forceinline__ float fast_sigmoid(float x) { return __builtin_amdgcn_rcpf(1.f + __expf(-x)); }
;     __device__ __forceinline__ void operator()(const f32x4 (&acc)[2][2][4][2], const Unit& u, int wr, int wc, int fr, int fq) const {
;     ...
;                 float r[8];
; #pragma unroll
;                 for (int n = 0; n < 2; ++n)
; #pragma unroll
;                     for (int e = 0; e < 4; ++e) { const float gv = acc[ai][0][m][n][e] * rs, uv = acc[ai][1][m][n][e] * rs; r[n * 4 + e] = gv * fast_sigmoid(gv) * uv; }
;                 u32x4 w; w.x = pk2(r[0], r[1]); w.y = pk2(r[2], r[3]); w.z = pk2(r[4], r[5]); w.w = pk2(r[6], r[7]);
;                 *(u32x4*)(O + (size_t)row * DFF + col0) = w;
	v_add_f32_e32 v67, 1.0, v67
	v_rcp_f32_e32 v71, v67
	s_nop 0
	v_pk_mul_f32 v[62:63], v[62:63], v[70:71]
	s_nop 0
	v_pk_mul_f32 v[54:55], v[54:55], v[62:63]
	v_pk_mul_f32 v[62:63], v[64:65], v[68:69] op_sel_hi:[1,0]
	s_nop 0
	v_mul_f32_e32 v64, 0xbfb8aa3b, v62
	v_mul_f32_e32 v65, 0xbfb8aa3b, v63
	v_exp_f32_e32 v64, v64
	v_exp_f32_e32 v65, v65
	v_add_f32_e32 v64, 1.0, v64
	v_add_f32_e32 v65, 1.0, v65
	v_rcp_f32_e32 v64, v64
	v_rcp_f32_e32 v65, v65
	s_nop 0
	v_pk_mul_f32 v[62:63], v[62:63], v[64:65]
	s_nop 0
	v_pk_mul_f32 v[56:57], v[56:57], v[62:63]
	v_mul_f32_e32 v62, 0xbfb8aa3b, v58
	v_mul_f32_e32 v63, 0xbfb8aa3b, v59
	v_exp_f32_e32 v62, v62
	v_exp_f32_e32 v63, v63
	v_add_f32_e32 v62, 1.0, v62
	v_add_f32_e32 v63, 1.0, v63
	v_rcp_f32_e32 v62, v62
	v_rcp_f32_e32 v63, v63
	s_nop 0
	v_pk_mul_f32 v[58:59], v[58:59], v[62:63]
	s_nop 0
	v_pk_mul_f32 v[58:59], v[50:51], v[58:59]
	v_pk_mul_f32 v[50:51], v[60:61], v[68:69] op_sel_hi:[1,0]
	s_nop 0
	v_mul_f32_e32 v60, 0xbfb8aa3b, v50
	v_mul_f32_e32 v61, 0xbfb8aa3b, v51
	v_exp_f32_e32 v60, v60
	v_exp_f32_e32 v61, v61
	v_add_f32_e32 v60, 1.0, v60
	v_add_f32_e32 v61, 1.0, v61
	v_rcp_f32_e32 v60, v60
	v_rcp_f32_e32 v61, v61
	s_nop 0
	v_pk_mul_f32 v[50:51], v[50:51], v[60:61]
	s_nop 0
	v_pk_mul_f32 v[60:61], v[52:53], v[50:51]
	v_cvt_pk_bf16_f32 v50, v54, v55
	v_cvt_pk_bf16_f32 v51, v56, v57
	v_cvt_pk_bf16_f32 v52, v58, v59
	v_cvt_pk_bf16_f32 v53, v60, v61
	v_mad_i64_i32 v[54:55], s[6:7], v66, s4, v[142:143]
	global_store_dwordx4 v[54:55], v[50:53], off
	s_nop 1
	v_add_u32_e32 v50, 0x90, v144
	v_mov_b32_e32 v52, v163
	v_pk_mul_f32 v[46:47], v[46:47], v[52:53] op_sel_hi:[1,0]
	v_pk_mul_f32 v[38:39], v[38:39], v[52:53] op_sel_hi:[1,0]
	v_mul_f32_e32 v51, 0xbfb8aa3b, v46
	v_exp_f32_e32 v51, v51
	v_pk_mul_f32 v[40:41], v[40:41], v[52:53] op_sel_hi:[1,0]
	v_pk_mul_f32 v[42:43], v[42:43], v[52:53] op_sel_hi:[1,0]
	v_pk_mul_f32 v[34:35], v[34:35], v[52:53] op_sel_hi:[1,0]
	v_add_f32_e32 v51, 1.0, v51
	v_rcp_f32_e32 v54, v51
	v_mul_f32_e32 v51, 0xbfb8aa3b, v47
	v_exp_f32_e32 v51, v51
	v_pk_mul_f32 v[36:37], v[36:37], v[52:53] op_sel_hi:[1,0]
	v_add_f32_e32 v51, 1.0, v51
	v_rcp_f32_e32 v55, v51
	s_nop 0
	v_pk_mul_f32 v[46:47], v[46:47], v[54:55]
	s_nop 0
	v_pk_mul_f32 v[38:39], v[38:39], v[46:47]
	v_pk_mul_f32 v[46:47], v[48:49], v[52:53] op_sel_hi:[1,0]
	s_nop 0
	v_mul_f32_e32 v48, 0xbfb8aa3b, v46
	v_mul_f32_e32 v49, 0xbfb8aa3b, v47
	v_exp_f32_e32 v48, v48
	v_exp_f32_e32 v49, v49
	v_add_f32_e32 v48, 1.0, v48
	v_add_f32_e32 v49, 1.0, v49
	v_rcp_f32_e32 v48, v48
	v_rcp_f32_e32 v49, v49
	s_nop 0
	v_pk_mul_f32 v[46:47], v[46:47], v[48:49]
	s_nop 0
	v_pk_mul_f32 v[40:41], v[40:41], v[46:47]
	v_mul_f32_e32 v46, 0xbfb8aa3b, v42
	v_mul_f32_e32 v47, 0xbfb8aa3b, v43
	v_exp_f32_e32 v46, v46
	v_exp_f32_e32 v47, v47
	v_add_f32_e32 v46, 1.0, v46
	v_add_f32_e32 v47, 1.0, v47
	v_rcp_f32_e32 v46, v46
	v_rcp_f32_e32 v47, v47
	s_nop 0
	v_pk_mul_f32 v[42:43], v[42:43], v[46:47]
	s_nop 0
	v_pk_mul_f32 v[42:43], v[34:35], v[42:43]
	v_pk_mul_f32 v[34:35], v[44:45], v[52:53] op_sel_hi:[1,0]
	s_nop 0
	v_mul_f32_e32 v44, 0xbfb8aa3b, v34
	v_mul_f32_e32 v45, 0xbfb8aa3b, v35
	v_exp_f32_e32 v44, v44
	v_exp_f32_e32 v45, v45
	v_add_f32_e32 v44, 1.0, v44
	v_add_f32_e32 v45, 1.0, v45
	v_rcp_f32_e32 v44, v44
	v_rcp_f32_e32 v45, v45
	s_nop 0
	v_pk_mul_f32 v[34:35], v[34:35], v[44:45]
	s_nop 0
	v_pk_mul_f32 v[44:45], v[36:37], v[34:35]
	v_cvt_pk_bf16_f32 v34, v38, v39
	v_cvt_pk_bf16_f32 v35, v40, v41
	v_cvt_pk_bf16_f32 v36, v42, v43
	v_cvt_pk_bf16_f32 v37, v44, v45
	v_mad_i64_i32 v[38:39], s[6:7], v50, s4, v[142:143]
	global_store_dwordx4 v[38:39], v[34:37], off
	s_nop 1
	v_add_u32_e32 v34, 0xa0, v144
	v_mov_b32_e32 v36, v164
	v_pk_mul_f32 v[30:31], v[30:31], v[36:37] op_sel_hi:[1,0]
	v_pk_mul_f32 v[22:23], v[22:23], v[36:37] op_sel_hi:[1,0]
	v_mul_f32_e32 v35, 0xbfb8aa3b, v30
	v_exp_f32_e32 v35, v35
	v_pk_mul_f32 v[24:25], v[24:25], v[36:37] op_sel_hi:[1,0]
	v_pk_mul_f32 v[26:27], v[26:27], v[36:37] op_sel_hi:[1,0]
; __device__ __forceinline__ unsigned pk2(float lo, float hi) { f32x2_t v = {lo, hi}; bf16x2_t b = __builtin_convertvector(v, bf16x2_t); return __builtin_bit_cast(unsigned, b); }
; __device__ __forceinline__ float fast_sigmoid(float x) { return __builtin_amdgcn_rcpf(1.f + __expf(-x)); }
; #define PG8_BAR __builtin_amdgcn_s_barrier()
; template <class Epi>
; __device__ __forceinline__ void gemm_phase(LAS unsigned char* lds, int wave_s, const Gemm g, const StaticOrder S, const Epi E) {
;     ...
;         if (!has_next) break;
; #pragma unroll
;         for (int a = 0; a < 2; ++a)
; #pragma unroll
;             for (int b = 0; b < 2; ++b)
; #pragma unroll
;                 for (int m = 0; m < 4; ++m)
; #pragma unroll
;                     for (int n = 0; n < 2; ++n) acc[a][b][m][n] = (f32x4){0.f, 0.f, 0.f, 0.f};
;         cur = nxt; cA = nA; cB = nB; ++ui;
;         if (wr == 1) PG8_BAR;
;     __device__ __forceinline__ void operator()(const f32x4 (&acc)[2][2][4][2], const Unit& u, int wr, int wc, int fr, int fq) const {
;     ...
;                 float r[8];
; #pragma unroll
;                 for (int n = 0; n < 2; ++n)
; #pragma unroll
;                     for (int e = 0; e < 4; ++e) { const float gv = acc[ai][0][m][n][e] * rs, uv = acc[ai][1][m][n][e] * rs; r[n * 4 + e] = gv * fast_sigmoid(gv) * uv; }
;                 u32x4 w; w.x = pk2(r[0], r[1]); w.y = pk2(r[2], r[3]); w.z = pk2(r[4], r[5]); w.w = pk2(r[6], r[7]);
;                 *(u32x4*)(O + (size_t)row * DFF + col0) = w;
	v_pk_mul_f32 v[18:19], v[18:19], v[36:37] op_sel_hi:[1,0]
	v_add_f32_e32 v35, 1.0, v35
	v_rcp_f32_e32 v38, v35
	v_mul_f32_e32 v35, 0xbfb8aa3b, v31
	v_exp_f32_e32 v35, v35
	v_pk_mul_f32 v[20:21], v[20:21], v[36:37] op_sel_hi:[1,0]
	v_add_f32_e32 v35, 1.0, v35
	v_rcp_f32_e32 v39, v35
	s_nop 0
	v_pk_mul_f32 v[30:31], v[30:31], v[38:39]
	s_nop 0
	v_pk_mul_f32 v[22:23], v[22:23], v[30:31]
	v_pk_mul_f32 v[30:31], v[32:33], v[36:37] op_sel_hi:[1,0]
	s_nop 0
	v_mul_f32_e32 v32, 0xbfb8aa3b, v30
	v_mul_f32_e32 v33, 0xbfb8aa3b, v31
	v_exp_f32_e32 v32, v32
	v_exp_f32_e32 v33, v33
	v_add_f32_e32 v32, 1.0, v32
	v_add_f32_e32 v33, 1.0, v33
	v_rcp_f32_e32 v32, v32
	v_rcp_f32_e32 v33, v33
	s_nop 0
	v_pk_mul_f32 v[30:31], v[30:31], v[32:33]
	s_nop 0
	v_pk_mul_f32 v[24:25], v[24:25], v[30:31]
	v_mul_f32_e32 v30, 0xbfb8aa3b, v26
	v_mul_f32_e32 v31, 0xbfb8aa3b, v27
	v_exp_f32_e32 v30, v30
	v_exp_f32_e32 v31, v31
	v_add_f32_e32 v30, 1.0, v30
	v_add_f32_e32 v31, 1.0, v31
	v_rcp_f32_e32 v30, v30
	v_rcp_f32_e32 v31, v31
	s_nop 0
	v_pk_mul_f32 v[26:27], v[26:27], v[30:31]
	s_nop 0
	v_pk_mul_f32 v[26:27], v[18:19], v[26:27]
	v_pk_mul_f32 v[18:19], v[28:29], v[36:37] op_sel_hi:[1,0]
	s_nop 0
	v_mul_f32_e32 v28, 0xbfb8aa3b, v18
	v_mul_f32_e32 v29, 0xbfb8aa3b, v19
	v_exp_f32_e32 v28, v28
	v_exp_f32_e32 v29, v29
	v_add_f32_e32 v28, 1.0, v28
	v_add_f32_e32 v29, 1.0, v29
	v_rcp_f32_e32 v28, v28
	v_rcp_f32_e32 v29, v29
	s_nop 0
	v_pk_mul_f32 v[18:19], v[18:19], v[28:29]
	s_nop 0
	v_pk_mul_f32 v[28:29], v[20:21], v[18:19]
	v_cvt_pk_bf16_f32 v18, v22, v23
	v_cvt_pk_bf16_f32 v19, v24, v25
	v_cvt_pk_bf16_f32 v20, v26, v27
	v_cvt_pk_bf16_f32 v21, v28, v29
	v_mad_i64_i32 v[22:23], s[6:7], v34, s4, v[142:143]
	global_store_dwordx4 v[22:23], v[18:21], off
	s_nop 1
	v_add_u32_e32 v18, 0xb0, v144
	v_mov_b32_e32 v20, v165
	v_pk_mul_f32 v[14:15], v[14:15], v[20:21] op_sel_hi:[1,0]
	v_pk_mul_f32 v[6:7], v[6:7], v[20:21] op_sel_hi:[1,0]
	v_mul_f32_e32 v19, 0xbfb8aa3b, v14
	v_exp_f32_e32 v19, v19
	v_pk_mul_f32 v[8:9], v[8:9], v[20:21] op_sel_hi:[1,0]
	v_pk_mul_f32 v[10:11], v[10:11], v[20:21] op_sel_hi:[1,0]
	v_pk_mul_f32 v[2:3], v[2:3], v[20:21] op_sel_hi:[1,0]
	v_add_f32_e32 v19, 1.0, v19
	v_rcp_f32_e32 v22, v19
	v_mul_f32_e32 v19, 0xbfb8aa3b, v15
	v_exp_f32_e32 v19, v19
	v_pk_mul_f32 v[4:5], v[4:5], v[20:21] op_sel_hi:[1,0]
	s_andn2_b64 vcc, exec, s[42:43]
	v_add_f32_e32 v19, 1.0, v19
	v_rcp_f32_e32 v23, v19
	s_nop 0
	v_pk_mul_f32 v[14:15], v[14:15], v[22:23]
	s_nop 0
	v_pk_mul_f32 v[6:7], v[6:7], v[14:15]
	v_pk_mul_f32 v[14:15], v[16:17], v[20:21] op_sel_hi:[1,0]
	s_nop 0
	v_mul_f32_e32 v16, 0xbfb8aa3b, v14
	v_mul_f32_e32 v17, 0xbfb8aa3b, v15
	v_exp_f32_e32 v16, v16
	v_exp_f32_e32 v17, v17
	v_add_f32_e32 v16, 1.0, v16
	v_add_f32_e32 v17, 1.0, v17
	v_rcp_f32_e32 v16, v16
	v_rcp_f32_e32 v17, v17
	s_nop 0
	v_pk_mul_f32 v[14:15], v[14:15], v[16:17]
	s_nop 0
	v_pk_mul_f32 v[8:9], v[8:9], v[14:15]
	v_mul_f32_e32 v14, 0xbfb8aa3b, v10
	v_mul_f32_e32 v15, 0xbfb8aa3b, v11
	v_exp_f32_e32 v14, v14
	v_exp_f32_e32 v15, v15
	v_add_f32_e32 v14, 1.0, v14
	v_add_f32_e32 v15, 1.0, v15
	v_rcp_f32_e32 v14, v14
	v_rcp_f32_e32 v15, v15
	s_nop 0
	v_pk_mul_f32 v[10:11], v[10:11], v[14:15]
	s_nop 0
	v_pk_mul_f32 v[10:11], v[2:3], v[10:11]
	v_pk_mul_f32 v[2:3], v[12:13], v[20:21] op_sel_hi:[1,0]
	s_nop 0
	v_mul_f32_e32 v12, 0xbfb8aa3b, v2
	v_mul_f32_e32 v13, 0xbfb8aa3b, v3
	v_exp_f32_e32 v12, v12
	v_exp_f32_e32 v13, v13
	v_add_f32_e32 v12, 1.0, v12
	v_add_f32_e32 v13, 1.0, v13
	v_rcp_f32_e32 v12, v12
	v_rcp_f32_e32 v13, v13
	s_nop 0
	v_pk_mul_f32 v[2:3], v[2:3], v[12:13]
	s_nop 0
	v_pk_mul_f32 v[12:13], v[4:5], v[2:3]
	v_cvt_pk_bf16_f32 v2, v6, v7
	v_cvt_pk_bf16_f32 v3, v8, v9
	v_cvt_pk_bf16_f32 v4, v10, v11
	v_cvt_pk_bf16_f32 v5, v12, v13
	v_mad_i64_i32 v[6:7], s[6:7], v18, s4, v[142:143]
	global_store_dwordx4 v[6:7], v[2:5], off
	s_cbranch_vccnz .LBB0_1147
	s_andn2_b64 vcc, exec, s[0:1]
	s_cbranch_vccnz .LBB0_1146
	s_mov_b32 s99, 0x13579bdf
	s_branch .LBB0_1146

; #define PG8_STAGE(bufoff, gbase, voff) do { _Pragma("unroll") for (int _i = 0; _i < 2; ++_i) \
;         __builtin_amdgcn_global_load_lds((const unsigned*)((const char*)(gbase) + (voff)[_i]), (LAS unsigned*)(lds + (bufoff) + ldsw + _i * 8192), 16, 0, 0); } while (0)
; #define PG8_LDA(dst, b, h) do { _Pragma("unroll") for (int m = 0; m < 4; ++m) _Pragma("unroll") for (int k = 0; k < 2; ++k) dst[m][k] = *(const LAS bf16x8*)(lds + PG8_SA(b, h) + aoff + m * 2048 + k * 1024); } while (0)
; #define PG8_LDB(dst, b, h) do { _Pragma("unroll") for (int n = 0; n < 2; ++n) _Pragma("unroll") for (int k = 0; k < 2; ++k) dst[n][k] = *(const LAS bf16x8*)(lds + PG8_SB(b, h) + boff + n * 2048 + k * 1024); } while (0)
; #define PG8_WAIT_V(n) asm volatile("s_waitcnt vmcnt(" #n ")" ::: "memory")
; template <class Epi>
; __device__ __forceinline__ void gemm_phase(LAS unsigned char* lds, int wave_s, const Gemm g, const StaticOrder S, const Epi E) {
;     ...
;         const bool has_next = S.next(ui + 1, nxt);
;         const char* nA = has_next ? (const char*)g.A + (size_t)nxt.pm * tstepA : cA; const char* nB = has_next ? (const char*)g.Bt + (size_t)nxt.pn * tstepB : cB;
;         for (int t = 0; t < nt; t += 2) {
;             const bool last = (t == nt - 2);
;             const char* a1 = cA + (size_t)(t + 1) * kstep;
;             const char* a2 = last ? nA : cA + (size_t)(t + 2) * kstep; const char* b2 = last ? nB : cB + (size_t)(t + 2) * kstep;
;             const char* a3 = a2 + kstep; const char* b3 = b2 + kstep;
;             PG8_LDB(B0, 0, 0); PG8_LDB(B1, 0, 1); PG8_SCHED; PG8_LDA(At, 0, 0); PG8_STAGE(PG8_SA(1, 1), a1 + hstepA, voffA);
;             PG8_WAIT_V(8); PG8_WAIT_L(0); PG8_BAR; PG8_MMA(0, 0, At, B0); PG8_MMA(0, 1, At, B1); PG8_BAR; PG8_SCHED;
;             PG8_LDA(At, 0, 1); PG8_STAGE(PG8_SB(0, 0), b2, voffB); PG8_STAGE(PG8_SB(0, 1), b2 + hstepB, voffB); PG8_STAGE(PG8_SA(0, 0), a2, voffA);
;             PG8_WAIT_V(8); PG8_WAIT_L(0); PG8_BAR; PG8_MMA(1, 0, At, B0); PG8_MMA(1, 1, At, B1); PG8_BAR; PG8_SCHED;
;     ...
;         for (int a = 0; a < 2; ++a)
; #pragma unroll
;             for (int b = 0; b < 2; ++b)
; #pragma unroll
;                 for (int m = 0; m < 4; ++m)
; #pragma unroll
;                     for (int n = 0; n < 2; ++n) acc[a][b][m][n] = (f32x4){0.f, 0.f, 0.f, 0.f};
;         cur = nxt; cA = nA; cB = nB; ++ui;
;         if (wr == 1) PG8_BAR;
.LBB0_1170:
	s_ashr_i32 s17, s16, 31
	s_lshl_b64 s[0:1], s[16:17], 17
	s_add_u32 s18, s20, s0
	s_addc_u32 s19, s21, s1
	s_and_b64 s[0:1], s[42:43], exec
	s_cselect_b32 s17, s19, s25
	s_cselect_b32 s56, s18, s24
	s_ashr_i32 s15, s14, 31
	s_lshl_b64 s[0:1], s[14:15], 17
	v_readlane_b32 s6, v255, 4
	v_readlane_b32 s7, v255, 5
	s_add_u32 s20, s6, s0
	s_addc_u32 s21, s7, s1
	s_and_b64 s[0:1], s[42:43], exec
	v_mov_b32_e32 v2, 0
	s_cselect_b32 s15, s21, s23
	s_cselect_b32 s10, s20, s22
	s_mov_b32 s11, 0
	s_mov_b64 s[26:27], -1
	s_mov_b64 s[28:29], 0
	v_mov_b32_e32 v246, v2
	v_mov_b32_e32 v247, v2
	v_mov_b32_e32 v248, v2
	v_mov_b32_e32 v249, v2
	v_mov_b32_e32 v3, v2
	v_mov_b32_e32 v4, v2
	v_mfma_f32_32x32x16_bf16 v[18:33], v[246:249], v[246:249], 0
	v_mov_b32_e32 v5, v2
	v_mov_b32_e32 v6, v2
	v_mfma_f32_32x32x16_bf16 v[34:49], v[246:249], v[246:249], 0
	v_mov_b32_e32 v7, v2
	v_mov_b32_e32 v8, v2
	v_mfma_f32_32x32x16_bf16 v[50:65], v[246:249], v[246:249], 0
	v_mov_b32_e32 v9, v2
	v_mov_b32_e32 v10, v2
	v_mfma_f32_32x32x16_bf16 v[66:81], v[246:249], v[246:249], 0
	v_mov_b32_e32 v11, v2
	v_mov_b32_e32 v12, v2
	v_mfma_f32_32x32x16_bf16 v[82:97], v[246:249], v[246:249], 0
	v_mov_b32_e32 v13, v2
	v_mov_b32_e32 v14, v2
	v_mfma_f32_32x32x16_bf16 v[98:113], v[246:249], v[246:249], 0
	v_mov_b32_e32 v15, v2
	v_mov_b32_e32 v16, v2
	v_mfma_f32_32x32x16_bf16 v[114:129], v[246:249], v[246:249], 0
	v_mov_b32_e32 v17, v2
	s_cmp_eq_u32 s99, 0x13579bdf
	s_cbranch_scc0 .Lskw_7
	s_mov_b32 s99, 0
	s_barrier
.Lskw_7:
.LBB0_1171:
	s_add_u32 s6, s24, s11
	s_addc_u32 s7, s25, 0
	s_add_u32 s30, s6, 0x100
	s_addc_u32 s31, s7, 0
	s_and_b64 s[0:1], s[28:29], exec
	s_cselect_b32 s35, s17, s31
	s_cselect_b32 s34, s56, s30
	s_add_u32 s0, s22, s11
	s_addc_u32 s1, s23, 0
	s_add_u32 s11, s0, 0x100
	s_addc_u32 s30, s1, 0
	s_add_i32 s95, 0, 0x10000
	s_and_b64 s[0:1], s[28:29], exec
	s_cselect_b32 s39, s15, s30
	s_cselect_b32 s38, s10, s11
	s_add_i32 s1, 0, 0x14000
	s_add_u32 s46, s6, 0x10080
	s_addc_u32 s47, s7, 0
	s_add_i32 s7, s95, s4
	s_add_i32 m0, s52, 0xc000
	s_add_i32 s37, s52, 0xe000
	s_add_i32 s0, s7, 0x2000
	v_add_u32_e32 v141, s95, v139
	s_add_u32 s44, s38, 0x10000
	ds_read_b128 v[142:145], v141
	ds_read_b128 v[146:149], v141 offset:1024
	ds_read_b128 v[150:153], v141 offset:2048
	ds_read_b128 v[154:157], v141 offset:3072
	v_add_u32_e32 v141, s1, v139
	s_addc_u32 s45, s39, 0
	s_add_i32 vcc_hi, s1, s4
	ds_read_b128 v[158:161], v141
	ds_read_b128 v[162:165], v141 offset:1024
	ds_read_b128 v[166:169], v141 offset:2048
	ds_read_b128 v[170:173], v141 offset:3072
	s_add_i32 vcc_lo, vcc_hi, 0x2000
	s_add_i32 s58, 0, 0x18000
	s_add_i32 s94, 0, 0x1c000
	s_add_u32 s30, s34, 0x10000
	s_addc_u32 s31, s35, 0
	s_add_i32 s57, s58, s4
	s_add_i32 s11, s57, 0x2000
	s_add_u32 s28, s38, 0x10080
	s_addc_u32 s29, s39, 0
	s_add_i32 s6, s94, s4
	s_add_i32 s1, s6, 0x2000
	v_lshl_add_u64 v[194:195], s[46:47], 0, v[136:137]
	ds_read_b128 v[174:177], v140
	ds_read_b128 v[178:181], v140 offset:1024
	ds_read_b128 v[182:185], v140 offset:2048
	ds_read_b128 v[186:189], v140 offset:3072
	ds_read_b128 v[190:193], v140 offset:4096
	ds_read_b128 v[206:209], v140 offset:5120
	ds_read_b128 v[210:213], v140 offset:6144
	ds_read_b128 v[214:217], v140 offset:7168
	global_load_lds_dwordx4 v[194:195], off
	v_lshl_add_u64 v[194:195], s[46:47], 0, v[132:133]
	s_mov_b32 m0, s37
	s_nop 0
	global_load_lds_dwordx4 v[194:195], off
	s_waitcnt vmcnt(8)
	s_waitcnt lgkmcnt(0)
	s_barrier
	s_setprio 1
	s_waitcnt lgkmcnt(0)
	v_mfma_f32_16x16x32_bf16 v[126:129], v[142:145], v[174:177], v[126:129]
	v_mfma_f32_16x16x32_bf16 v[122:125], v[150:153], v[174:177], v[122:125]
	v_mfma_f32_16x16x32_bf16 v[118:121], v[142:145], v[182:185], v[118:121]
	v_mfma_f32_16x16x32_bf16 v[114:117], v[150:153], v[182:185], v[114:117]
	v_mfma_f32_16x16x32_bf16 v[110:113], v[142:145], v[190:193], v[110:113]
	v_mfma_f32_16x16x32_bf16 v[106:109], v[150:153], v[190:193], v[106:109]
	v_mfma_f32_16x16x32_bf16 v[102:105], v[142:145], v[210:213], v[102:105]
	v_mfma_f32_16x16x32_bf16 v[98:101], v[150:153], v[210:213], v[98:101]
	v_mfma_f32_16x16x32_bf16 v[126:129], v[146:149], v[178:181], v[126:129]
	v_mfma_f32_16x16x32_bf16 v[122:125], v[154:157], v[178:181], v[122:125]
	v_mfma_f32_16x16x32_bf16 v[118:121], v[146:149], v[186:189], v[118:121]
	v_mfma_f32_16x16x32_bf16 v[114:117], v[154:157], v[186:189], v[114:117]
	v_mfma_f32_16x16x32_bf16 v[110:113], v[146:149], v[206:209], v[110:113]
	v_mfma_f32_16x16x32_bf16 v[106:109], v[154:157], v[206:209], v[106:109]
	v_mfma_f32_16x16x32_bf16 v[102:105], v[146:149], v[214:217], v[102:105]
	v_mfma_f32_16x16x32_bf16 v[98:101], v[154:157], v[214:217], v[98:101]
	s_setprio 0
	s_setprio 1
	v_mfma_f32_16x16x32_bf16 v[78:81], v[158:161], v[174:177], v[78:81]
	v_mfma_f32_16x16x32_bf16 v[74:77], v[166:169], v[174:177], v[74:77]
	v_mfma_f32_16x16x32_bf16 v[66:69], v[158:161], v[182:185], v[66:69]
	v_mfma_f32_16x16x32_bf16 v[58:61], v[166:169], v[182:185], v[58:61]
	v_mfma_f32_16x16x32_bf16 v[54:57], v[158:161], v[190:193], v[54:57]
	v_mfma_f32_16x16x32_bf16 v[50:53], v[166:169], v[190:193], v[50:53]
	v_mfma_f32_16x16x32_bf16 v[38:41], v[158:161], v[210:213], v[38:41]
	v_mfma_f32_16x16x32_bf16 v[34:37], v[166:169], v[210:213], v[34:37]
	v_mfma_f32_16x16x32_bf16 v[78:81], v[162:165], v[178:181], v[78:81]
	v_mfma_f32_16x16x32_bf16 v[74:77], v[170:173], v[178:181], v[74:77]
	v_mfma_f32_16x16x32_bf16 v[66:69], v[162:165], v[186:189], v[66:69]
	v_mfma_f32_16x16x32_bf16 v[58:61], v[170:173], v[186:189], v[58:61]
	v_mfma_f32_16x16x32_bf16 v[54:57], v[162:165], v[206:209], v[54:57]
	v_mfma_f32_16x16x32_bf16 v[50:53], v[170:173], v[206:209], v[50:53]
	v_mfma_f32_16x16x32_bf16 v[38:41], v[162:165], v[214:217], v[38:41]
	v_mfma_f32_16x16x32_bf16 v[34:37], v[170:173], v[214:217], v[34:37]
	s_setprio 0
	s_barrier
; #define PG8_STAGE(bufoff, gbase, voff) do { _Pragma("unroll") for (int _i = 0; _i < 2; ++_i) \
;         __builtin_amdgcn_global_load_lds((const unsigned*)((const char*)(gbase) + (voff)[_i]), (LAS unsigned*)(lds + (bufoff) + ldsw + _i * 8192), 16, 0, 0); } while (0)
; #define PG8_LDA(dst, b, h) do { _Pragma("unroll") for (int m = 0; m < 4; ++m) _Pragma("unroll") for (int k = 0; k < 2; ++k) dst[m][k] = *(const LAS bf16x8*)(lds + PG8_SA(b, h) + aoff + m * 2048 + k * 1024); } while (0)
; #define PG8_LDB(dst, b, h) do { _Pragma("unroll") for (int n = 0; n < 2; ++n) _Pragma("unroll") for (int k = 0; k < 2; ++k) dst[n][k] = *(const LAS bf16x8*)(lds + PG8_SB(b, h) + boff + n * 2048 + k * 1024); } while (0)
; #define PG8_MMA(ai, bj, At, Bt) do { __builtin_amdgcn_s_setprio(1); _Pragma("unroll") for (int m = 0; m < 4; ++m) _Pragma("unroll") for (int n = 0; n < 2; ++n) _Pragma("unroll") for (int k = 0; k < 2; ++k) \
;         acc[ai][bj][m][n] = __builtin_amdgcn_mfma_f32_16x16x32_bf16(Bt[n][k], At[m][k], acc[ai][bj][m][n], 0, 0, 0); __builtin_amdgcn_s_setprio(0); } while (0)
; #define PG8_WAIT_V(n) asm volatile("s_waitcnt vmcnt(" #n ")" ::: "memory")
; #define PG8_WAIT_L(n) asm volatile("s_waitcnt lgkmcnt(" #n ")" ::: "memory")
; #define PG8_BAR __builtin_amdgcn_s_barrier()
; #define PG8_SCHED __builtin_amdgcn_sched_barrier(0)
; template <class Epi>
; __device__ __forceinline__ void gemm_phase(LAS unsigned char* lds, int wave_s, const Gemm g, const StaticOrder S, const Epi E) {
;     ...
;             PG8_LDB(B0, 0, 0); PG8_LDB(B1, 0, 1); PG8_SCHED; PG8_LDA(At, 0, 0); PG8_STAGE(PG8_SA(1, 1), a1 + hstepA, voffA);
;             PG8_WAIT_V(8); PG8_WAIT_L(0); PG8_BAR; PG8_MMA(0, 0, At, B0); PG8_MMA(0, 1, At, B1); PG8_BAR; PG8_SCHED;
;             PG8_LDA(At, 0, 1); PG8_STAGE(PG8_SB(0, 0), b2, voffB); PG8_STAGE(PG8_SB(0, 1), b2 + hstepB, voffB); PG8_STAGE(PG8_SA(0, 0), a2, voffA);
;             PG8_WAIT_V(8); PG8_WAIT_L(0); PG8_BAR; PG8_MMA(1, 0, At, B0); PG8_MMA(1, 1, At, B1); PG8_BAR; PG8_SCHED;
;             PG8_LDB(B0, 1, 0); PG8_LDB(B1, 1, 1); PG8_SCHED; PG8_LDA(At, 1, 0); PG8_STAGE(PG8_SA(0, 1), a2 + hstepA, voffA);
;             PG8_WAIT_V(8); PG8_WAIT_L(0); PG8_BAR; PG8_MMA(0, 0, At, B0); PG8_MMA(0, 1, At, B1); PG8_BAR; PG8_SCHED;
	s_mov_b32 m0, s7
	v_lshl_add_u64 v[194:195], s[38:39], 0, v[134:135]
	ds_read_b128 v[174:177], v140 offset:16384
	ds_read_b128 v[178:181], v140 offset:17408
	ds_read_b128 v[182:185], v140 offset:18432
	ds_read_b128 v[186:189], v140 offset:19456
	ds_read_b128 v[190:193], v140 offset:20480
	ds_read_b128 v[206:209], v140 offset:21504
	ds_read_b128 v[210:213], v140 offset:22528
	ds_read_b128 v[214:217], v140 offset:23552
	global_load_lds_dwordx4 v[194:195], off
	v_lshl_add_u64 v[196:197], s[38:39], 0, v[130:131]
	s_mov_b32 m0, s0
	v_lshl_add_u64 v[198:199], s[44:45], 0, v[134:135]
	global_load_lds_dwordx4 v[196:197], off
	s_mov_b32 m0, vcc_hi
	v_lshl_add_u64 v[200:201], s[34:35], 0, v[132:133]
	global_load_lds_dwordx4 v[198:199], off
	v_lshl_add_u64 v[198:199], s[44:45], 0, v[130:131]
	s_mov_b32 m0, vcc_lo
	s_nop 0
	global_load_lds_dwordx4 v[198:199], off
	v_lshl_add_u64 v[198:199], s[34:35], 0, v[136:137]
	s_mov_b32 m0, s52
	s_nop 0
	global_load_lds_dwordx4 v[198:199], off
	s_mov_b32 m0, s40
	s_nop 0
	global_load_lds_dwordx4 v[200:201], off
	s_waitcnt vmcnt(8)
	s_waitcnt lgkmcnt(0)
	s_barrier
	s_setprio 1
	s_waitcnt lgkmcnt(0)
	v_mfma_f32_16x16x32_bf16 v[94:97], v[142:145], v[174:177], v[94:97]
	v_mfma_f32_16x16x32_bf16 v[90:93], v[150:153], v[174:177], v[90:93]
	v_mfma_f32_16x16x32_bf16 v[86:89], v[142:145], v[182:185], v[86:89]
	v_mfma_f32_16x16x32_bf16 v[82:85], v[150:153], v[182:185], v[82:85]
	v_mfma_f32_16x16x32_bf16 v[70:73], v[142:145], v[190:193], v[70:73]
	v_mfma_f32_16x16x32_bf16 v[62:65], v[150:153], v[190:193], v[62:65]
	v_mfma_f32_16x16x32_bf16 v[46:49], v[142:145], v[210:213], v[46:49]
	v_mfma_f32_16x16x32_bf16 v[42:45], v[150:153], v[210:213], v[42:45]
	v_mfma_f32_16x16x32_bf16 v[94:97], v[146:149], v[178:181], v[94:97]
	v_mfma_f32_16x16x32_bf16 v[90:93], v[154:157], v[178:181], v[90:93]
	v_mfma_f32_16x16x32_bf16 v[86:89], v[146:149], v[186:189], v[86:89]
	v_mfma_f32_16x16x32_bf16 v[82:85], v[154:157], v[186:189], v[82:85]
	v_mfma_f32_16x16x32_bf16 v[70:73], v[146:149], v[206:209], v[70:73]
	v_mfma_f32_16x16x32_bf16 v[62:65], v[154:157], v[206:209], v[62:65]
	v_mfma_f32_16x16x32_bf16 v[46:49], v[146:149], v[214:217], v[46:49]
	v_mfma_f32_16x16x32_bf16 v[42:45], v[154:157], v[214:217], v[42:45]
	s_setprio 0
	s_setprio 1
	v_mfma_f32_16x16x32_bf16 v[30:33], v[158:161], v[174:177], v[30:33]
	v_mfma_f32_16x16x32_bf16 v[26:29], v[166:169], v[174:177], v[26:29]
	v_mfma_f32_16x16x32_bf16 v[22:25], v[158:161], v[182:185], v[22:25]
	v_mfma_f32_16x16x32_bf16 v[18:21], v[166:169], v[182:185], v[18:21]
	v_mfma_f32_16x16x32_bf16 v[14:17], v[158:161], v[190:193], v[14:17]
	v_mfma_f32_16x16x32_bf16 v[10:13], v[166:169], v[190:193], v[10:13]
	v_mfma_f32_16x16x32_bf16 v[6:9], v[158:161], v[210:213], v[6:9]
	v_mfma_f32_16x16x32_bf16 v[2:5], v[166:169], v[210:213], v[2:5]
	v_mfma_f32_16x16x32_bf16 v[30:33], v[162:165], v[178:181], v[30:33]
	v_mfma_f32_16x16x32_bf16 v[26:29], v[170:173], v[178:181], v[26:29]
	v_mfma_f32_16x16x32_bf16 v[22:25], v[162:165], v[186:189], v[22:25]
	v_mfma_f32_16x16x32_bf16 v[18:21], v[170:173], v[186:189], v[18:21]
	v_mfma_f32_16x16x32_bf16 v[14:17], v[162:165], v[206:209], v[14:17]
	v_mfma_f32_16x16x32_bf16 v[10:13], v[170:173], v[206:209], v[10:13]
	v_mfma_f32_16x16x32_bf16 v[6:9], v[162:165], v[214:217], v[6:9]
	v_mfma_f32_16x16x32_bf16 v[2:5], v[170:173], v[214:217], v[2:5]
	s_setprio 0
	s_barrier
	v_add_u32_e32 v141, s58, v139
	ds_read_b128 v[142:145], v141
	ds_read_b128 v[146:149], v141 offset:1024
	ds_read_b128 v[150:153], v141 offset:2048
	ds_read_b128 v[154:157], v141 offset:3072
	v_add_u32_e32 v141, s94, v139
	ds_read_b128 v[158:161], v141
	ds_read_b128 v[162:165], v141 offset:1024
	ds_read_b128 v[166:169], v141 offset:2048
	ds_read_b128 v[170:173], v141 offset:3072
	s_mov_b32 m0, s48
	v_lshl_add_u64 v[202:203], s[30:31], 0, v[136:137]
	ds_read_b128 v[174:177], v140 offset:32768
	ds_read_b128 v[178:181], v140 offset:33792
	ds_read_b128 v[182:185], v140 offset:34816
	ds_read_b128 v[186:189], v140 offset:35840
	ds_read_b128 v[190:193], v140 offset:36864
	ds_read_b128 v[206:209], v140 offset:37888
	ds_read_b128 v[210:213], v140 offset:38912
	ds_read_b128 v[214:217], v140 offset:39936
	global_load_lds_dwordx4 v[202:203], off
	v_lshl_add_u64 v[202:203], s[30:31], 0, v[132:133]
	s_mov_b32 m0, s49
	s_nop 0
	global_load_lds_dwordx4 v[202:203], off
	s_waitcnt vmcnt(8)
	s_waitcnt lgkmcnt(0)
	s_barrier
	s_setprio 1
	s_waitcnt lgkmcnt(0)
	v_mfma_f32_16x16x32_bf16 v[126:129], v[142:145], v[174:177], v[126:129]
	v_mfma_f32_16x16x32_bf16 v[122:125], v[150:153], v[174:177], v[122:125]
	v_mfma_f32_16x16x32_bf16 v[118:121], v[142:145], v[182:185], v[118:121]
	v_mfma_f32_16x16x32_bf16 v[114:117], v[150:153], v[182:185], v[114:117]
	v_mfma_f32_16x16x32_bf16 v[110:113], v[142:145], v[190:193], v[110:113]
	v_mfma_f32_16x16x32_bf16 v[106:109], v[150:153], v[190:193], v[106:109]
	v_mfma_f32_16x16x32_bf16 v[102:105], v[142:145], v[210:213], v[102:105]
	v_mfma_f32_16x16x32_bf16 v[98:101], v[150:153], v[210:213], v[98:101]
	v_mfma_f32_16x16x32_bf16 v[126:129], v[146:149], v[178:181], v[126:129]
	v_mfma_f32_16x16x32_bf16 v[122:125], v[154:157], v[178:181], v[122:125]
	v_mfma_f32_16x16x32_bf16 v[118:121], v[146:149], v[186:189], v[118:121]
	v_mfma_f32_16x16x32_bf16 v[114:117], v[154:157], v[186:189], v[114:117]
	v_mfma_f32_16x16x32_bf16 v[110:113], v[146:149], v[206:209], v[110:113]
	v_mfma_f32_16x16x32_bf16 v[106:109], v[154:157], v[206:209], v[106:109]
	v_mfma_f32_16x16x32_bf16 v[102:105], v[146:149], v[214:217], v[102:105]
	v_mfma_f32_16x16x32_bf16 v[98:101], v[154:157], v[214:217], v[98:101]
	s_setprio 0
	s_setprio 1
	v_mfma_f32_16x16x32_bf16 v[78:81], v[158:161], v[174:177], v[78:81]
	v_mfma_f32_16x16x32_bf16 v[74:77], v[166:169], v[174:177], v[74:77]
	v_mfma_f32_16x16x32_bf16 v[66:69], v[158:161], v[182:185], v[66:69]
	v_mfma_f32_16x16x32_bf16 v[58:61], v[166:169], v[182:185], v[58:61]
	v_mfma_f32_16x16x32_bf16 v[54:57], v[158:161], v[190:193], v[54:57]
	v_mfma_f32_16x16x32_bf16 v[50:53], v[166:169], v[190:193], v[50:53]
	v_mfma_f32_16x16x32_bf16 v[38:41], v[158:161], v[210:213], v[38:41]
	v_mfma_f32_16x16x32_bf16 v[34:37], v[166:169], v[210:213], v[34:37]
	v_mfma_f32_16x16x32_bf16 v[78:81], v[162:165], v[178:181], v[78:81]
	v_mfma_f32_16x16x32_bf16 v[74:77], v[170:173], v[178:181], v[74:77]
	v_mfma_f32_16x16x32_bf16 v[66:69], v[162:165], v[186:189], v[66:69]
	v_mfma_f32_16x16x32_bf16 v[58:61], v[170:173], v[186:189], v[58:61]
	v_mfma_f32_16x16x32_bf16 v[54:57], v[162:165], v[206:209], v[54:57]
	v_mfma_f32_16x16x32_bf16 v[50:53], v[170:173], v[206:209], v[50:53]
	v_mfma_f32_16x16x32_bf16 v[38:41], v[162:165], v[214:217], v[38:41]
	v_mfma_f32_16x16x32_bf16 v[34:37], v[170:173], v[214:217], v[34:37]
	s_setprio 0
	s_barrier
; #define PG8_STAGE(bufoff, gbase, voff) do { _Pragma("unroll") for (int _i = 0; _i < 2; ++_i) \
;         __builtin_amdgcn_global_load_lds((const unsigned*)((const char*)(gbase) + (voff)[_i]), (LAS unsigned*)(lds + (bufoff) + ldsw + _i * 8192), 16, 0, 0); } while (0)
; #define PG8_LDA(dst, b, h) do { _Pragma("unroll") for (int m = 0; m < 4; ++m) _Pragma("unroll") for (int k = 0; k < 2; ++k) dst[m][k] = *(const LAS bf16x8*)(lds + PG8_SA(b, h) + aoff + m * 2048 + k * 1024); } while (0)
; #define PG8_MMA(ai, bj, At, Bt) do { __builtin_amdgcn_s_setprio(1); _Pragma("unroll") for (int m = 0; m < 4; ++m) _Pragma("unroll") for (int n = 0; n < 2; ++n) _Pragma("unroll") for (int k = 0; k < 2; ++k) \
;         acc[ai][bj][m][n] = __builtin_amdgcn_mfma_f32_16x16x32_bf16(Bt[n][k], At[m][k], acc[ai][bj][m][n], 0, 0, 0); __builtin_amdgcn_s_setprio(0); } while (0)
; #define PG8_WAIT_V(n) asm volatile("s_waitcnt vmcnt(" #n ")" ::: "memory")
; #define PG8_WAIT_L(n) asm volatile("s_waitcnt lgkmcnt(" #n ")" ::: "memory")
; #define PG8_BAR __builtin_amdgcn_s_barrier()
; #define PG8_SCHED __builtin_amdgcn_sched_barrier(0)
; template <class Epi>
; __device__ __forceinline__ void gemm_phase(LAS unsigned char* lds, int wave_s, const Gemm g, const StaticOrder S, const Epi E) {
;     ...
;             PG8_LDA(At, 1, 1); PG8_STAGE(PG8_SB(1, 0), b3, voffB); PG8_STAGE(PG8_SB(1, 1), b3 + hstepB, voffB); PG8_STAGE(PG8_SA(1, 0), a3, voffA);
;             PG8_WAIT_V(8); PG8_WAIT_L(0); PG8_BAR; PG8_MMA(1, 0, At, B0); PG8_MMA(1, 1, At, B1); PG8_BAR; PG8_SCHED;
;         }
;         if (wr == 0) PG8_BAR;
	s_mov_b32 m0, s57
	v_lshl_add_u64 v[194:195], v[194:195], 0, s[8:9]
	ds_read_b128 v[174:177], v140 offset:49152
	ds_read_b128 v[178:181], v140 offset:50176
	ds_read_b128 v[182:185], v140 offset:51200
	ds_read_b128 v[186:189], v140 offset:52224
	ds_read_b128 v[190:193], v140 offset:53248
	ds_read_b128 v[206:209], v140 offset:54272
	ds_read_b128 v[210:213], v140 offset:55296
	ds_read_b128 v[214:217], v140 offset:56320
	global_load_lds_dwordx4 v[194:195], off
	v_lshl_add_u64 v[194:195], v[196:197], 0, s[8:9]
	s_mov_b32 m0, s11
	s_nop 0
	global_load_lds_dwordx4 v[194:195], off
	v_lshl_add_u64 v[194:195], s[28:29], 0, v[134:135]
	s_mov_b32 m0, s6
	s_nop 0
	global_load_lds_dwordx4 v[194:195], off
	v_lshl_add_u64 v[194:195], s[28:29], 0, v[130:131]
	s_mov_b32 m0, s1
	s_nop 0
	global_load_lds_dwordx4 v[194:195], off
	v_lshl_add_u64 v[194:195], v[198:199], 0, s[8:9]
	s_mov_b32 m0, s50
	s_nop 0
	global_load_lds_dwordx4 v[194:195], off
	v_lshl_add_u64 v[194:195], v[200:201], 0, s[8:9]
	s_mov_b32 m0, s51
	s_nop 0
	global_load_lds_dwordx4 v[194:195], off
	s_waitcnt vmcnt(8)
	s_waitcnt lgkmcnt(0)
	s_barrier
	s_setprio 1
	s_waitcnt lgkmcnt(0)
	v_mfma_f32_16x16x32_bf16 v[94:97], v[142:145], v[174:177], v[94:97]
	v_mfma_f32_16x16x32_bf16 v[90:93], v[150:153], v[174:177], v[90:93]
	v_mfma_f32_16x16x32_bf16 v[86:89], v[142:145], v[182:185], v[86:89]
	v_mfma_f32_16x16x32_bf16 v[82:85], v[150:153], v[182:185], v[82:85]
	v_mfma_f32_16x16x32_bf16 v[70:73], v[142:145], v[190:193], v[70:73]
	v_mfma_f32_16x16x32_bf16 v[62:65], v[150:153], v[190:193], v[62:65]
	v_mfma_f32_16x16x32_bf16 v[46:49], v[142:145], v[210:213], v[46:49]
	v_mfma_f32_16x16x32_bf16 v[42:45], v[150:153], v[210:213], v[42:45]
	v_mfma_f32_16x16x32_bf16 v[94:97], v[146:149], v[178:181], v[94:97]
	v_mfma_f32_16x16x32_bf16 v[90:93], v[154:157], v[178:181], v[90:93]
	v_mfma_f32_16x16x32_bf16 v[86:89], v[146:149], v[186:189], v[86:89]
	v_mfma_f32_16x16x32_bf16 v[82:85], v[154:157], v[186:189], v[82:85]
	v_mfma_f32_16x16x32_bf16 v[70:73], v[146:149], v[206:209], v[70:73]
	v_mfma_f32_16x16x32_bf16 v[62:65], v[154:157], v[206:209], v[62:65]
	v_mfma_f32_16x16x32_bf16 v[46:49], v[146:149], v[214:217], v[46:49]
	v_mfma_f32_16x16x32_bf16 v[42:45], v[154:157], v[214:217], v[42:45]
	s_setprio 0
	s_setprio 1
	v_mfma_f32_16x16x32_bf16 v[30:33], v[158:161], v[174:177], v[30:33]
	v_mfma_f32_16x16x32_bf16 v[26:29], v[166:169], v[174:177], v[26:29]
	v_mfma_f32_16x16x32_bf16 v[22:25], v[158:161], v[182:185], v[22:25]
	v_mfma_f32_16x16x32_bf16 v[18:21], v[166:169], v[182:185], v[18:21]
	v_mfma_f32_16x16x32_bf16 v[14:17], v[158:161], v[190:193], v[14:17]
	v_mfma_f32_16x16x32_bf16 v[10:13], v[166:169], v[190:193], v[10:13]
	v_mfma_f32_16x16x32_bf16 v[6:9], v[158:161], v[210:213], v[6:9]
	v_mfma_f32_16x16x32_bf16 v[2:5], v[166:169], v[210:213], v[2:5]
	v_mfma_f32_16x16x32_bf16 v[30:33], v[162:165], v[178:181], v[30:33]
	v_mfma_f32_16x16x32_bf16 v[26:29], v[170:173], v[178:181], v[26:29]
	v_mfma_f32_16x16x32_bf16 v[22:25], v[162:165], v[186:189], v[22:25]
	v_mfma_f32_16x16x32_bf16 v[18:21], v[170:173], v[186:189], v[18:21]
	v_mfma_f32_16x16x32_bf16 v[14:17], v[162:165], v[206:209], v[14:17]
	v_mfma_f32_16x16x32_bf16 v[10:13], v[170:173], v[206:209], v[10:13]
	v_mfma_f32_16x16x32_bf16 v[6:9], v[162:165], v[214:217], v[6:9]
	v_mfma_f32_16x16x32_bf16 v[2:5], v[170:173], v[214:217], v[2:5]
	s_setprio 0
	s_barrier
	s_movk_i32 s11, 0x100
	s_andn2_b64 vcc, exec, s[26:27]
	s_mov_b64 s[28:29], -1
	s_mov_b64 s[26:27], 0
	s_cbranch_vccz .LBB0_1171
	s_and_b64 vcc, exec, s[12:13]
	s_cbranch_vccz .LBB0_1174
	s_barrier
; __device__ __forceinline__ float fast_sigmoid(float x) { return __builtin_amdgcn_rcpf(1.f + __expf(-x)); }
; #define PG8_BAR __builtin_amdgcn_s_barrier()
; template <class Epi>
; __device__ __forceinline__ void gemm_phase(LAS unsigned char* lds, int wave_s, const Gemm g, const StaticOrder S, const Epi E) {
;     ...
;         if (!has_next) break;
; #pragma unroll
;         for (int a = 0; a < 2; ++a)
; #pragma unroll
;             for (int b = 0; b < 2; ++b)
; #pragma unroll
;                 for (int m = 0; m < 4; ++m)
; #pragma unroll
;                     for (int n = 0; n < 2; ++n) acc[a][b][m][n] = (f32x4){0.f, 0.f, 0.f, 0.f};
;         cur = nxt; cA = nA; cB = nB; ++ui;
;         if (wr == 1) PG8_BAR;
;     __device__ __forceinline__ void operator()(const f32x4 (&acc)[2][2][4][2], const Unit& u, int wr, int wc, int fr, int fq) const {
;     ...
;                     const int row = row0 + ai * HALF + m * 16; const float rs = rsv[ai][m] * scale;
;                     f32x4 v0 = acc[ai][bj][m][0] * rs, v1 = acc[ai][bj][m][1] * rs;
;                     if (rp) {
;                         const int pos = row & (SEQ - 1); const float* rb = rope + pos * 32 + 8 * (fq & 1); const bool hi2 = (fq >> 1) != 0;
;                         const f32x4 cs0 = *(const f32x4*)(rb), cs1 = *(const f32x4*)(rb + 4), sn0 = *(const f32x4*)(rb + 16), sn1 = *(const f32x4*)(rb + 20);
; #pragma unroll
;                         for (int e = 0; e < 4; ++e) { const float q0 = __shfl_xor(v0[e], 32), q1 = __shfl_xor(v1[e], 32);
;                             v0[e] = hi2 ? v0[e] * cs0[e] + q0 * sn0[e] : v0[e] * cs0[e] - q0 * sn0[e];
;                             v1[e] = hi2 ? v1[e] * cs1[e] + q1 * sn1[e] : v1[e] * cs1[e] - q1 * sn1[e]; } }
;                     if (sig) {
; #pragma unroll
;                         for (int e = 0; e < 4; ++e) { v0[e] = fast_sigmoid(v0[e]); v1[e] = fast_sigmoid(v1[e]); } }
;                     if (sq) { float s = (v0[0] * v0[0] + v0[1] * v0[1]) + (v0[2] * v0[2] + v0[3] * v0[3]) + (v1[0] * v1[0] + v1[1] * v1[1]) + (v1[2] * v1[2] + v1[3] * v1[3]);
;                         s += __shfl_xor(s, 16); s += __shfl_xor(s, 32); if (fq == 0) sq[(size_t)row * sqp] = s; }
;                     u32x4 w; w.x = pk2(v0[0], v0[1]); w.y = pk2(v0[2], v0[3]); w.z = pk2(v1[0], v1[1]); w.w = pk2(v1[2], v1[3]);
;                     *(u32x4*)(O + (size_t)row * ldc + c0 + 8 * fq) = w;
.LBB0_1174:
	v_lshl_add_u32 v142, s55, 8, v138
	s_lshl_b32 s0, s54, 8
	v_readlane_b32 s1, v254, 18
	s_or_b32 s0, s0, s1
	v_cvt_pk_bf16_f32 v126, v126, v127
	v_cvt_pk_bf16_f32 v127, v128, v129
	v_cvt_pk_bf16_f32 v129, v124, v125
	v_ashrrev_i32_e32 v143, 31, v142
	v_readlane_b32 s6, v250, 47
	v_or_b32_e32 v124, 16, v142
	v_cvt_pk_bf16_f32 v118, v118, v119
	v_cvt_pk_bf16_f32 v119, v120, v121
	v_cvt_pk_bf16_f32 v121, v116, v117
	v_or_b32_e32 v116, 32, v142
	v_cvt_pk_bf16_f32 v110, v110, v111
	v_cvt_pk_bf16_f32 v111, v112, v113
	v_cvt_pk_bf16_f32 v113, v108, v109
	v_or_b32_e32 v108, 48, v142
	s_ashr_i32 s1, s0, 31
	v_cvt_pk_bf16_f32 v128, v122, v123
	v_lshlrev_b64 v[122:123], 11, v[142:143]
	v_readlane_b32 s7, v250, 48
	v_ashrrev_i32_e32 v125, 31, v124
	v_ashrrev_i32_e32 v117, 31, v116
	v_ashrrev_i32_e32 v109, 31, v108
	v_lshl_add_u64 v[122:123], s[6:7], 0, v[122:123]
	s_lshl_b64 s[0:1], s[0:1], 1
	v_cvt_pk_bf16_f32 v120, v114, v115
	v_lshlrev_b64 v[114:115], 11, v[124:125]
	v_cvt_pk_bf16_f32 v112, v106, v107
	v_lshlrev_b64 v[106:107], 11, v[116:117]
	v_cvt_pk_bf16_f32 v102, v102, v103
	v_cvt_pk_bf16_f32 v103, v104, v105
	v_cvt_pk_bf16_f32 v104, v98, v99
	v_lshlrev_b64 v[98:99], 11, v[108:109]
	v_lshl_add_u64 v[122:123], v[122:123], 0, s[0:1]
	v_lshl_add_u64 v[114:115], s[6:7], 0, v[114:115]
	v_lshl_add_u64 v[106:107], s[6:7], 0, v[106:107]
	v_lshl_add_u64 v[98:99], s[6:7], 0, v[98:99]
	v_lshl_add_u64 v[122:123], v[122:123], 0, v[0:1]
	v_lshl_add_u64 v[114:115], v[114:115], 0, s[0:1]
	v_lshl_add_u64 v[106:107], v[106:107], 0, s[0:1]
	v_lshl_add_u64 v[98:99], v[98:99], 0, s[0:1]
	s_mov_b64 s[0:1], 0x40000
	v_cvt_pk_bf16_f32 v94, v94, v95
	v_cvt_pk_bf16_f32 v95, v96, v97
	v_cvt_pk_bf16_f32 v96, v90, v91
	v_lshl_add_u64 v[90:91], v[122:123], 0, s[0:1]
	s_mov_b32 s0, 0x40000
	v_cvt_pk_bf16_f32 v97, v92, v93
	v_add_co_u32_e32 v92, vcc, s0, v122
	s_mov_b64 s[0:1], 0x48000
	s_nop 0
	v_addc_co_u32_e32 v93, vcc, 0, v123, vcc
	v_cvt_pk_bf16_f32 v86, v86, v87
	v_cvt_pk_bf16_f32 v87, v88, v89
	v_cvt_pk_bf16_f32 v88, v82, v83
	v_lshl_add_u64 v[82:83], v[122:123], 0, s[0:1]
	s_mov_b32 s0, 0x48000
	v_cvt_pk_bf16_f32 v89, v84, v85
	v_add_co_u32_e32 v84, vcc, s0, v122
	s_mov_b64 s[0:1], 0x50000
	s_nop 0
	v_addc_co_u32_e32 v85, vcc, 0, v123, vcc
	v_cvt_pk_bf16_f32 v70, v70, v71
	v_cvt_pk_bf16_f32 v71, v72, v73
	v_cvt_pk_bf16_f32 v72, v62, v63
	v_lshl_add_u64 v[62:63], v[122:123], 0, s[0:1]
	s_mov_b32 s0, 0x50000
	v_cvt_pk_bf16_f32 v73, v64, v65
	v_add_co_u32_e32 v64, vcc, s0, v122
	s_mov_b64 s[0:1], 0x58000
	s_nop 0
	v_addc_co_u32_e32 v65, vcc, 0, v123, vcc
	global_store_dwordx4 v[64:65], v[70:73], off
	v_lshl_add_u64 v[64:65], v[122:123], 0, s[0:1]
	s_mov_b32 s0, 0x58000
	v_cvt_pk_bf16_f32 v46, v46, v47
	v_cvt_pk_bf16_f32 v47, v48, v49
	v_cvt_pk_bf16_f32 v48, v42, v43
	v_add_co_u32_e32 v42, vcc, s0, v122
	v_cvt_pk_bf16_f32 v49, v44, v45
	s_nop 0
	v_addc_co_u32_e32 v43, vcc, 0, v123, vcc
	global_store_dwordx4 v[42:43], v[46:49], off
	v_cvt_pk_bf16_f32 v42, v78, v79
	v_cvt_pk_bf16_f32 v43, v80, v81
	v_cvt_pk_bf16_f32 v44, v74, v75
	v_cvt_pk_bf16_f32 v45, v76, v77
	v_lshl_add_u64 v[114:115], v[114:115], 0, v[0:1]
	global_store_dwordx4 v[122:123], v[42:45], off offset:256
	v_readlane_b32 s58, v254, 8
	v_lshl_add_u64 v[106:107], v[106:107], 0, v[0:1]
	v_cvt_pk_bf16_f32 v42, v66, v67
	v_cvt_pk_bf16_f32 v43, v68, v69
	v_cvt_pk_bf16_f32 v44, v58, v59
	v_cvt_pk_bf16_f32 v45, v60, v61
	v_cvt_pk_bf16_f32 v105, v100, v101
	v_lshl_add_u64 v[98:99], v[98:99], 0, v[0:1]
	global_store_dwordx4 v[114:115], v[42:45], off offset:256
	v_cvt_pk_bf16_f32 v38, v38, v39
	v_cvt_pk_bf16_f32 v39, v40, v41
	v_cvt_pk_bf16_f32 v42, v54, v55
	v_cvt_pk_bf16_f32 v43, v56, v57
	v_cvt_pk_bf16_f32 v44, v50, v51
	v_cvt_pk_bf16_f32 v45, v52, v53
	v_cvt_pk_bf16_f32 v40, v34, v35
	v_cvt_pk_bf16_f32 v41, v36, v37
	v_cvt_pk_bf16_f32 v30, v30, v31
	v_cvt_pk_bf16_f32 v31, v32, v33
	v_cvt_pk_bf16_f32 v32, v26, v27
	v_cvt_pk_bf16_f32 v33, v28, v29
	v_cvt_pk_bf16_f32 v22, v22, v23
	v_cvt_pk_bf16_f32 v23, v24, v25
	v_cvt_pk_bf16_f32 v24, v18, v19
	v_cvt_pk_bf16_f32 v25, v20, v21
	v_cvt_pk_bf16_f32 v14, v14, v15
	v_cvt_pk_bf16_f32 v15, v16, v17
	v_cvt_pk_bf16_f32 v16, v10, v11
	v_cvt_pk_bf16_f32 v17, v12, v13
	v_cvt_pk_bf16_f32 v6, v6, v7
	v_cvt_pk_bf16_f32 v7, v8, v9
	v_cvt_pk_bf16_f32 v8, v2, v3
	v_cvt_pk_bf16_f32 v9, v4, v5
	s_andn2_b64 vcc, exec, s[42:43]
	s_mov_b64 s[22:23], -1
	v_readlane_b32 s30, v251, 4
	v_readlane_b32 s59, v254, 9
	s_mov_b64 s[94:95], 0x480
	global_store_dwordx4 v[122:123], v[126:129], off
	global_store_dwordx4 v[114:115], v[118:121], off
	global_store_dwordx4 v[106:107], v[110:113], off
	global_store_dwordx4 v[98:99], v[102:105], off
	global_store_dwordx4 v[92:93], v[94:97], off
	global_store_dwordx4 v[84:85], v[86:89], off
	global_store_dwordx4 v[106:107], v[42:45], off offset:256
	global_store_dwordx4 v[98:99], v[38:41], off offset:256
	global_store_dwordx4 v[90:91], v[30:33], off offset:256
	global_store_dwordx4 v[82:83], v[22:25], off offset:256
	global_store_dwordx4 v[62:63], v[14:17], off offset:256
	global_store_dwordx4 v[64:65], v[6:9], off offset:256
	v_readlane_b32 s31, v251, 5
	s_cbranch_vccnz .LBB0_1163
	v_readlane_b32 s0, v254, 20
	v_readlane_b32 s1, v254, 21
	s_andn2_b64 vcc, exec, s[0:1]
	s_cbranch_vccnz .LBB0_1162
	s_mov_b32 s99, 0x13579bdf
	s_branch .LBB0_1162

; #define PG8_STAGE(bufoff, gbase, voff) do { _Pragma("unroll") for (int _i = 0; _i < 2; ++_i) \
;         __builtin_amdgcn_global_load_lds((const unsigned*)((const char*)(gbase) + (voff)[_i]), (LAS unsigned*)(lds + (bufoff) + ldsw + _i * 8192), 16, 0, 0); } while (0)
; #define PG8_LDA(dst, b, h) do { _Pragma("unroll") for (int m = 0; m < 4; ++m) _Pragma("unroll") for (int k = 0; k < 2; ++k) dst[m][k] = *(const LAS bf16x8*)(lds + PG8_SA(b, h) + aoff + m * 2048 + k * 1024); } while (0)
; #define PG8_LDB(dst, b, h) do { _Pragma("unroll") for (int n = 0; n < 2; ++n) _Pragma("unroll") for (int k = 0; k < 2; ++k) dst[n][k] = *(const LAS bf16x8*)(lds + PG8_SB(b, h) + boff + n * 2048 + k * 1024); } while (0)
; #define PG8_MMA(ai, bj, At, Bt) do { __builtin_amdgcn_s_setprio(1); _Pragma("unroll") for (int m = 0; m < 4; ++m) _Pragma("unroll") for (int n = 0; n < 2; ++n) _Pragma("unroll") for (int k = 0; k < 2; ++k) \
;         acc[ai][bj][m][n] = __builtin_amdgcn_mfma_f32_16x16x32_bf16(Bt[n][k], At[m][k], acc[ai][bj][m][n], 0, 0, 0); __builtin_amdgcn_s_setprio(0); } while (0)
; #define PG8_WAIT_V(n) asm volatile("s_waitcnt vmcnt(" #n ")" ::: "memory")
; #define PG8_WAIT_L(n) asm volatile("s_waitcnt lgkmcnt(" #n ")" ::: "memory")
; template <class Epi>
; __device__ __forceinline__ void gemm_phase(LAS unsigned char* lds, int wave_s, const Gemm g, const StaticOrder S, const Epi E) {
;     ...
;         for (int t = 0; t < nt; t += 2) {
;             const bool last = (t == nt - 2);
;             const char* a1 = cA + (size_t)(t + 1) * kstep;
;             const char* a2 = last ? nA : cA + (size_t)(t + 2) * kstep; const char* b2 = last ? nB : cB + (size_t)(t + 2) * kstep;
;             const char* a3 = a2 + kstep; const char* b3 = b2 + kstep;
;             PG8_LDB(B0, 0, 0); PG8_LDB(B1, 0, 1); PG8_SCHED; PG8_LDA(At, 0, 0); PG8_STAGE(PG8_SA(1, 1), a1 + hstepA, voffA);
;             PG8_WAIT_V(8); PG8_WAIT_L(0); PG8_BAR; PG8_MMA(0, 0, At, B0); PG8_MMA(0, 1, At, B1); PG8_BAR; PG8_SCHED;
;     __device__ __forceinline__ void operator()(const f32x4 (&acc)[2][2][4][2], const Unit& u, int wr, int wc, int fr, int fq) const {
;     ...
;                 for (int bj = 0; bj < 2; ++bj) {
;                     const size_t off = (size_t)row * DM + col0 + bj * HALF;
;                     const u32x4 hh = *(const u32x4*)(HI + off), ll = *(const u32x4*)(LO + off);
.Lskw_8:
.LBB0_1247:
	s_cmp_eq_u32 s34, 36
	s_cbranch_scc0 .Lpre_f2d_skip
	v_readlane_b32 s100, v253, 35
	v_readlane_b32 s101, v253, 36
	v_readlane_b32 s98, v250, 49
	v_readlane_b32 s99, v250, 50
	v_lshl_add_u32 v243, s31, 8, v160
	v_lshl_or_b32 v246, s4, 8, v162
	v_lshl_add_u32 v243, v243, 10, v246
	v_lshlrev_b32_e32 v243, 1, v243
	s_nop 1
	global_load_dwordx4 v[226:229], v243, s[100:101]
	global_load_dwordx4 v[230:233], v243, s[98:99]
	global_load_dwordx4 v[234:237], v243, s[100:101] offset:256
	global_load_dwordx4 v[242:245], v243, s[98:99] offset:256

; #define PG8_BAR __builtin_amdgcn_s_barrier()
; template <class Epi>
; __device__ __forceinline__ void gemm_phase(LAS unsigned char* lds, int wave_s, const Gemm g, const StaticOrder S, const Epi E) {
;     ...
;         if (!has_next) break;
; #pragma unroll
;         for (int a = 0; a < 2; ++a)
; #pragma unroll
;             for (int b = 0; b < 2; ++b)
; #pragma unroll
;                 for (int m = 0; m < 4; ++m)
; #pragma unroll
;                     for (int n = 0; n < 2; ++n) acc[a][b][m][n] = (f32x4){0.f, 0.f, 0.f, 0.f};
;         cur = nxt; cA = nA; cB = nB; ++ui;
;         if (wr == 1) PG8_BAR;
;     __device__ __forceinline__ void operator()(const f32x4 (&acc)[2][2][4][2], const Unit& u, int wr, int wc, int fr, int fq) const {
;     ...
;                 sq += __shfl_xor(sq, 16); sq += __shfl_xor(sq, 32);
;                 if (fq == 0) ssq_out[(size_t)row * 16 + 4 * u.pn + wc] = sq;
.Lepir_f2d_skip:
	s_or_b64 exec, exec, s[12:13]
	s_and_b64 vcc, exec, s[44:45]
	s_mov_b64 s[12:13], -1
	s_cbranch_vccnz .LBB0_1235
	s_andn2_b64 vcc, exec, s[38:39]
	s_cbranch_vccnz .LBB0_1234
	s_mov_b32 s99, 0x13579bdf
	s_branch .LBB0_1234

; #define PG8_STAGE(bufoff, gbase, voff) do { _Pragma("unroll") for (int _i = 0; _i < 2; ++_i) \
;         __builtin_amdgcn_global_load_lds((const unsigned*)((const char*)(gbase) + (voff)[_i]), (LAS unsigned*)(lds + (bufoff) + ldsw + _i * 8192), 16, 0, 0); } while (0)
; #define PG8_LDA(dst, b, h) do { _Pragma("unroll") for (int m = 0; m < 4; ++m) _Pragma("unroll") for (int k = 0; k < 2; ++k) dst[m][k] = *(const LAS bf16x8*)(lds + PG8_SA(b, h) + aoff + m * 2048 + k * 1024); } while (0)
; #define PG8_LDB(dst, b, h) do { _Pragma("unroll") for (int n = 0; n < 2; ++n) _Pragma("unroll") for (int k = 0; k < 2; ++k) dst[n][k] = *(const LAS bf16x8*)(lds + PG8_SB(b, h) + boff + n * 2048 + k * 1024); } while (0)
; #define PG8_WAIT_V(n) asm volatile("s_waitcnt vmcnt(" #n ")" ::: "memory")
; #define PG8_WAIT_L(n) asm volatile("s_waitcnt lgkmcnt(" #n ")" ::: "memory")
; #define PG8_BAR __builtin_amdgcn_s_barrier()
; #define PG8_SCHED __builtin_amdgcn_sched_barrier(0)
; template <class Epi>
; __device__ __forceinline__ void gemm_phase(LAS unsigned char* lds, int wave_s, const Gemm g, const StaticOrder S, const Epi E) {
;     ...
;         const bool has_next = S.next(ui + 1, nxt);
;         const char* nA = has_next ? (const char*)g.A + (size_t)nxt.pm * tstepA : cA; const char* nB = has_next ? (const char*)g.Bt + (size_t)nxt.pn * tstepB : cB;
;         for (int t = 0; t < nt; t += 2) {
;             const bool last = (t == nt - 2);
;             const char* a1 = cA + (size_t)(t + 1) * kstep;
;             const char* a2 = last ? nA : cA + (size_t)(t + 2) * kstep; const char* b2 = last ? nB : cB + (size_t)(t + 2) * kstep;
;             const char* a3 = a2 + kstep; const char* b3 = b2 + kstep;
;             PG8_LDB(B0, 0, 0); PG8_LDB(B1, 0, 1); PG8_SCHED; PG8_LDA(At, 0, 0); PG8_STAGE(PG8_SA(1, 1), a1 + hstepA, voffA);
;             PG8_WAIT_V(8); PG8_WAIT_L(0); PG8_BAR; PG8_MMA(0, 0, At, B0); PG8_MMA(0, 1, At, B1); PG8_BAR; PG8_SCHED;
;     ...
;         for (int a = 0; a < 2; ++a)
; #pragma unroll
;             for (int b = 0; b < 2; ++b)
; #pragma unroll
;                 for (int m = 0; m < 4; ++m)
; #pragma unroll
;                     for (int n = 0; n < 2; ++n) acc[a][b][m][n] = (f32x4){0.f, 0.f, 0.f, 0.f};
;         cur = nxt; cA = nA; cB = nB; ++ui;
;         if (wr == 1) PG8_BAR;
.LBB0_1334:
	s_ashr_i32 s49, s48, 31
	s_lshl_b64 s[6:7], s[48:49], 19
	v_readlane_b32 s10, v253, 35
	v_readlane_b32 s11, v253, 36
	s_add_u32 s50, s10, s6
	s_addc_u32 s51, s11, s7
	s_and_b64 s[6:7], s[42:43], exec
	s_cselect_b32 s28, s51, s13
	s_cselect_b32 s29, s50, s12
	s_ashr_i32 s57, s56, 31
	s_lshl_b64 s[6:7], s[56:57], 19
	v_readlane_b32 s10, v253, 31
	v_readlane_b32 s11, v253, 32
	s_add_u32 s52, s10, s6
	s_addc_u32 s53, s11, s7
	s_and_b64 s[6:7], s[42:43], exec
	s_cselect_b32 s10, s53, s15
	s_cselect_b32 s11, s52, s14
	s_add_u32 s12, s12, 0x40080
	s_addc_u32 s13, s13, 0
	s_add_u32 s30, s14, 0x100
	v_mov_b32_e32 v2, 0
	s_addc_u32 s31, s15, 0
	s_mov_b32 s34, -2
	v_mov_b32_e32 v246, v2
	v_mov_b32_e32 v247, v2
	v_mov_b32_e32 v248, v2
	v_mov_b32_e32 v249, v2
	v_mov_b32_e32 v3, v2
	v_mov_b32_e32 v4, v2
	v_mfma_f32_32x32x16_bf16 v[18:33], v[246:249], v[246:249], 0
	v_mov_b32_e32 v5, v2
	v_mov_b32_e32 v6, v2
	v_mfma_f32_32x32x16_bf16 v[34:49], v[246:249], v[246:249], 0
	v_mov_b32_e32 v7, v2
	v_mov_b32_e32 v8, v2
	v_mfma_f32_32x32x16_bf16 v[50:65], v[246:249], v[246:249], 0
	v_mov_b32_e32 v9, v2
	v_mov_b32_e32 v10, v2
	v_mfma_f32_32x32x16_bf16 v[66:81], v[246:249], v[246:249], 0
	v_mov_b32_e32 v11, v2
	v_mov_b32_e32 v12, v2
	v_mfma_f32_32x32x16_bf16 v[82:97], v[246:249], v[246:249], 0
	v_mov_b32_e32 v13, v2
	v_mov_b32_e32 v14, v2
	v_mfma_f32_32x32x16_bf16 v[98:113], v[246:249], v[246:249], 0
	v_mov_b32_e32 v15, v2
	v_mov_b32_e32 v16, v2
	v_mfma_f32_32x32x16_bf16 v[114:129], v[246:249], v[246:249], 0
	v_mov_b32_e32 v17, v2
	s_cmp_eq_u32 s99, 0x13579bdf
	s_cbranch_scc0 .Lskw_9
	s_mov_b32 s99, 0
	s_barrier
.Lskw_9:
.LBB0_1335:
	s_add_u32 s6, s12, 0xfffc0080
	s_addc_u32 s7, s13, -1
	s_add_i32 s35, 0, 0x10000
	s_cmp_eq_u32 s34, 12
	s_cselect_b32 s17, s28, s7
	s_cselect_b32 s16, s29, s6
	s_cselect_b32 s15, s10, s31
	s_cselect_b32 s14, s11, s30
	s_add_i32 s37, 0, 0x14000
	v_add_u32_e32 v158, s35, v155
	v_add_u32_e32 v174, s37, v155
	ds_read_b128 v[142:145], v158
	ds_read_b128 v[146:149], v158 offset:1024
	ds_read_b128 v[150:153], v158 offset:2048
	ds_read_b128 v[158:161], v158 offset:3072
	ds_read_b128 v[162:165], v174
	ds_read_b128 v[166:169], v174 offset:1024
	ds_read_b128 v[170:173], v174 offset:2048
	ds_read_b128 v[174:177], v174 offset:3072
	v_lshl_add_u64 v[194:195], s[12:13], 0, v[138:139]
	s_add_i32 m0, s19, 0xc000
	ds_read_b128 v[178:181], v157
	ds_read_b128 v[182:185], v157 offset:1024
	ds_read_b128 v[186:189], v157 offset:2048
	ds_read_b128 v[190:193], v157 offset:3072
	ds_read_b128 v[206:209], v157 offset:4096
	ds_read_b128 v[210:213], v157 offset:5120
	ds_read_b128 v[214:217], v157 offset:6144
	ds_read_b128 v[218:221], v157 offset:7168
	global_load_lds_dwordx4 v[194:195], off
	v_lshl_add_u64 v[194:195], s[12:13], 0, v[140:141]
	s_add_i32 m0, s19, 0xe000
	s_nop 0
	global_load_lds_dwordx4 v[194:195], off
	s_waitcnt vmcnt(8)
	s_waitcnt lgkmcnt(0)
	s_barrier
	s_setprio 1
	s_waitcnt lgkmcnt(0)
	v_mfma_f32_16x16x32_bf16 v[126:129], v[142:145], v[178:181], v[126:129]
	v_mfma_f32_16x16x32_bf16 v[122:125], v[150:153], v[178:181], v[122:125]
	v_mfma_f32_16x16x32_bf16 v[110:113], v[142:145], v[186:189], v[110:113]
	v_mfma_f32_16x16x32_bf16 v[106:109], v[150:153], v[186:189], v[106:109]
	v_mfma_f32_16x16x32_bf16 v[94:97], v[142:145], v[206:209], v[94:97]
	v_mfma_f32_16x16x32_bf16 v[90:93], v[150:153], v[206:209], v[90:93]
	v_mfma_f32_16x16x32_bf16 v[78:81], v[142:145], v[214:217], v[78:81]
	v_mfma_f32_16x16x32_bf16 v[74:77], v[150:153], v[214:217], v[74:77]
	v_mfma_f32_16x16x32_bf16 v[126:129], v[146:149], v[182:185], v[126:129]
	v_mfma_f32_16x16x32_bf16 v[122:125], v[158:161], v[182:185], v[122:125]
	v_mfma_f32_16x16x32_bf16 v[110:113], v[146:149], v[190:193], v[110:113]
	v_mfma_f32_16x16x32_bf16 v[106:109], v[158:161], v[190:193], v[106:109]
	v_mfma_f32_16x16x32_bf16 v[94:97], v[146:149], v[210:213], v[94:97]
	v_mfma_f32_16x16x32_bf16 v[90:93], v[158:161], v[210:213], v[90:93]
	v_mfma_f32_16x16x32_bf16 v[78:81], v[146:149], v[218:221], v[78:81]
	v_mfma_f32_16x16x32_bf16 v[74:77], v[158:161], v[218:221], v[74:77]
	s_setprio 0
	s_setprio 1
	v_mfma_f32_16x16x32_bf16 v[118:121], v[162:165], v[178:181], v[118:121]
	v_mfma_f32_16x16x32_bf16 v[114:117], v[170:173], v[178:181], v[114:117]
	v_mfma_f32_16x16x32_bf16 v[102:105], v[162:165], v[186:189], v[102:105]
	v_mfma_f32_16x16x32_bf16 v[98:101], v[170:173], v[186:189], v[98:101]
	v_mfma_f32_16x16x32_bf16 v[86:89], v[162:165], v[206:209], v[86:89]
	v_mfma_f32_16x16x32_bf16 v[82:85], v[170:173], v[206:209], v[82:85]
	v_mfma_f32_16x16x32_bf16 v[70:73], v[162:165], v[214:217], v[70:73]
	v_mfma_f32_16x16x32_bf16 v[66:69], v[170:173], v[214:217], v[66:69]
	v_mfma_f32_16x16x32_bf16 v[118:121], v[166:169], v[182:185], v[118:121]
	v_mfma_f32_16x16x32_bf16 v[114:117], v[174:177], v[182:185], v[114:117]
	v_mfma_f32_16x16x32_bf16 v[102:105], v[166:169], v[190:193], v[102:105]
	v_mfma_f32_16x16x32_bf16 v[98:101], v[174:177], v[190:193], v[98:101]
	v_mfma_f32_16x16x32_bf16 v[86:89], v[166:169], v[210:213], v[86:89]
	v_mfma_f32_16x16x32_bf16 v[82:85], v[174:177], v[210:213], v[82:85]
	v_mfma_f32_16x16x32_bf16 v[70:73], v[166:169], v[218:221], v[70:73]
	v_mfma_f32_16x16x32_bf16 v[66:69], v[174:177], v[218:221], v[66:69]
	s_setprio 0
	s_barrier
; #define PG8_STAGE(bufoff, gbase, voff) do { _Pragma("unroll") for (int _i = 0; _i < 2; ++_i) \
;         __builtin_amdgcn_global_load_lds((const unsigned*)((const char*)(gbase) + (voff)[_i]), (LAS unsigned*)(lds + (bufoff) + ldsw + _i * 8192), 16, 0, 0); } while (0)
; #define PG8_LDA(dst, b, h) do { _Pragma("unroll") for (int m = 0; m < 4; ++m) _Pragma("unroll") for (int k = 0; k < 2; ++k) dst[m][k] = *(const LAS bf16x8*)(lds + PG8_SA(b, h) + aoff + m * 2048 + k * 1024); } while (0)
; #define PG8_LDB(dst, b, h) do { _Pragma("unroll") for (int n = 0; n < 2; ++n) _Pragma("unroll") for (int k = 0; k < 2; ++k) dst[n][k] = *(const LAS bf16x8*)(lds + PG8_SB(b, h) + boff + n * 2048 + k * 1024); } while (0)
; #define PG8_MMA(ai, bj, At, Bt) do { __builtin_amdgcn_s_setprio(1); _Pragma("unroll") for (int m = 0; m < 4; ++m) _Pragma("unroll") for (int n = 0; n < 2; ++n) _Pragma("unroll") for (int k = 0; k < 2; ++k) \
;         acc[ai][bj][m][n] = __builtin_amdgcn_mfma_f32_16x16x32_bf16(Bt[n][k], At[m][k], acc[ai][bj][m][n], 0, 0, 0); __builtin_amdgcn_s_setprio(0); } while (0)
; #define PG8_WAIT_V(n) asm volatile("s_waitcnt vmcnt(" #n ")" ::: "memory")
; #define PG8_WAIT_L(n) asm volatile("s_waitcnt lgkmcnt(" #n ")" ::: "memory")
; #define PG8_BAR __builtin_amdgcn_s_barrier()
; #define PG8_SCHED __builtin_amdgcn_sched_barrier(0)
; template <class Epi>
; __device__ __forceinline__ void gemm_phase(LAS unsigned char* lds, int wave_s, const Gemm g, const StaticOrder S, const Epi E) {
;     ...
;             PG8_WAIT_V(8); PG8_WAIT_L(0); PG8_BAR; PG8_MMA(0, 0, At, B0); PG8_MMA(0, 1, At, B1); PG8_BAR; PG8_SCHED;
;             PG8_LDA(At, 0, 1); PG8_STAGE(PG8_SB(0, 0), b2, voffB); PG8_STAGE(PG8_SB(0, 1), b2 + hstepB, voffB); PG8_STAGE(PG8_SA(0, 0), a2, voffA);
;             PG8_WAIT_V(8); PG8_WAIT_L(0); PG8_BAR; PG8_MMA(1, 0, At, B0); PG8_MMA(1, 1, At, B1); PG8_BAR; PG8_SCHED;
;             PG8_LDB(B0, 1, 0); PG8_LDB(B1, 1, 1); PG8_SCHED; PG8_LDA(At, 1, 0); PG8_STAGE(PG8_SA(0, 1), a2 + hstepA, voffA);
;             PG8_WAIT_V(8); PG8_WAIT_L(0); PG8_BAR; PG8_MMA(0, 0, At, B0); PG8_MMA(0, 1, At, B1); PG8_BAR; PG8_SCHED;
	s_add_i32 s6, s35, s18
	v_lshl_add_u64 v[194:195], s[14:15], 0, v[0:1]
	s_mov_b32 m0, s6
	ds_read_b128 v[178:181], v157 offset:16384
	ds_read_b128 v[182:185], v157 offset:17408
	ds_read_b128 v[186:189], v157 offset:18432
	ds_read_b128 v[190:193], v157 offset:19456
	ds_read_b128 v[206:209], v157 offset:20480
	ds_read_b128 v[210:213], v157 offset:21504
	ds_read_b128 v[214:217], v157 offset:22528
	ds_read_b128 v[218:221], v157 offset:23552
	global_load_lds_dwordx4 v[194:195], off
	s_add_i32 m0, s6, 0x2000
	s_add_u32 s6, s14, 0x40000
	v_lshl_add_u64 v[196:197], s[14:15], 0, v[130:131]
	s_addc_u32 s7, s15, 0
	s_add_i32 s35, s37, s18
	global_load_lds_dwordx4 v[196:197], off
	v_lshl_add_u64 v[198:199], s[6:7], 0, v[0:1]
	s_mov_b32 m0, s35
	v_lshl_add_u64 v[200:201], s[16:17], 0, v[132:133]
	global_load_lds_dwordx4 v[198:199], off
	v_lshl_add_u64 v[198:199], s[6:7], 0, v[130:131]
	s_add_i32 m0, s35, 0x2000
	s_nop 0
	global_load_lds_dwordx4 v[198:199], off
	v_lshl_add_u64 v[198:199], s[16:17], 0, v[134:135]
	s_mov_b32 m0, s19
	s_nop 0
	global_load_lds_dwordx4 v[198:199], off
	s_mov_b32 m0, s20
	s_nop 0
	global_load_lds_dwordx4 v[200:201], off
	s_waitcnt vmcnt(8)
	s_waitcnt lgkmcnt(0)
	s_barrier
	s_setprio 1
	s_waitcnt lgkmcnt(0)
	v_mfma_f32_16x16x32_bf16 v[62:65], v[142:145], v[178:181], v[62:65]
	v_mfma_f32_16x16x32_bf16 v[58:61], v[150:153], v[178:181], v[58:61]
	v_mfma_f32_16x16x32_bf16 v[46:49], v[142:145], v[186:189], v[46:49]
	v_mfma_f32_16x16x32_bf16 v[42:45], v[150:153], v[186:189], v[42:45]
	v_mfma_f32_16x16x32_bf16 v[30:33], v[142:145], v[206:209], v[30:33]
	v_mfma_f32_16x16x32_bf16 v[26:29], v[150:153], v[206:209], v[26:29]
	v_mfma_f32_16x16x32_bf16 v[14:17], v[142:145], v[214:217], v[14:17]
	v_mfma_f32_16x16x32_bf16 v[10:13], v[150:153], v[214:217], v[10:13]
	v_mfma_f32_16x16x32_bf16 v[62:65], v[146:149], v[182:185], v[62:65]
	v_mfma_f32_16x16x32_bf16 v[58:61], v[158:161], v[182:185], v[58:61]
	v_mfma_f32_16x16x32_bf16 v[46:49], v[146:149], v[190:193], v[46:49]
	v_mfma_f32_16x16x32_bf16 v[42:45], v[158:161], v[190:193], v[42:45]
	v_mfma_f32_16x16x32_bf16 v[30:33], v[146:149], v[210:213], v[30:33]
	v_mfma_f32_16x16x32_bf16 v[26:29], v[158:161], v[210:213], v[26:29]
	v_mfma_f32_16x16x32_bf16 v[14:17], v[146:149], v[218:221], v[14:17]
	v_mfma_f32_16x16x32_bf16 v[10:13], v[158:161], v[218:221], v[10:13]
	s_setprio 0
	s_setprio 1
	v_mfma_f32_16x16x32_bf16 v[54:57], v[162:165], v[178:181], v[54:57]
	v_mfma_f32_16x16x32_bf16 v[50:53], v[170:173], v[178:181], v[50:53]
	v_mfma_f32_16x16x32_bf16 v[38:41], v[162:165], v[186:189], v[38:41]
	v_mfma_f32_16x16x32_bf16 v[34:37], v[170:173], v[186:189], v[34:37]
	v_mfma_f32_16x16x32_bf16 v[22:25], v[162:165], v[206:209], v[22:25]
	v_mfma_f32_16x16x32_bf16 v[18:21], v[170:173], v[206:209], v[18:21]
	v_mfma_f32_16x16x32_bf16 v[6:9], v[162:165], v[214:217], v[6:9]
	v_mfma_f32_16x16x32_bf16 v[2:5], v[170:173], v[214:217], v[2:5]
	v_mfma_f32_16x16x32_bf16 v[54:57], v[166:169], v[182:185], v[54:57]
	v_mfma_f32_16x16x32_bf16 v[50:53], v[174:177], v[182:185], v[50:53]
	v_mfma_f32_16x16x32_bf16 v[38:41], v[166:169], v[190:193], v[38:41]
	v_mfma_f32_16x16x32_bf16 v[34:37], v[174:177], v[190:193], v[34:37]
	v_mfma_f32_16x16x32_bf16 v[22:25], v[166:169], v[210:213], v[22:25]
	v_mfma_f32_16x16x32_bf16 v[18:21], v[174:177], v[210:213], v[18:21]
	v_mfma_f32_16x16x32_bf16 v[6:9], v[166:169], v[218:221], v[6:9]
	v_mfma_f32_16x16x32_bf16 v[2:5], v[174:177], v[218:221], v[2:5]
	s_setprio 0
	s_barrier
	s_add_i32 s35, 0, 0x18000
	s_add_i32 s37, 0, 0x1c000
	v_add_u32_e32 v158, s35, v155
	v_add_u32_e32 v174, s37, v155
	ds_read_b128 v[142:145], v158
	ds_read_b128 v[146:149], v158 offset:1024
	ds_read_b128 v[150:153], v158 offset:2048
	ds_read_b128 v[158:161], v158 offset:3072
	ds_read_b128 v[162:165], v174
	ds_read_b128 v[166:169], v174 offset:1024
	ds_read_b128 v[170:173], v174 offset:2048
	ds_read_b128 v[174:177], v174 offset:3072
	s_add_u32 s6, s16, 0x40000
	s_addc_u32 s7, s17, 0
	s_mov_b32 m0, s21
	v_lshl_add_u64 v[202:203], s[6:7], 0, v[134:135]
	ds_read_b128 v[178:181], v157 offset:32768
	ds_read_b128 v[182:185], v157 offset:33792
	ds_read_b128 v[186:189], v157 offset:34816
	ds_read_b128 v[190:193], v157 offset:35840
	ds_read_b128 v[206:209], v157 offset:36864
	ds_read_b128 v[210:213], v157 offset:37888
	ds_read_b128 v[214:217], v157 offset:38912
	ds_read_b128 v[218:221], v157 offset:39936
	global_load_lds_dwordx4 v[202:203], off
	v_lshl_add_u64 v[202:203], s[6:7], 0, v[132:133]
	s_mov_b32 m0, s22
	s_nop 0
	global_load_lds_dwordx4 v[202:203], off
	s_waitcnt vmcnt(8)
	s_waitcnt lgkmcnt(0)
	s_barrier
; #define PG8_STAGE(bufoff, gbase, voff) do { _Pragma("unroll") for (int _i = 0; _i < 2; ++_i) \
;         __builtin_amdgcn_global_load_lds((const unsigned*)((const char*)(gbase) + (voff)[_i]), (LAS unsigned*)(lds + (bufoff) + ldsw + _i * 8192), 16, 0, 0); } while (0)
; #define PG8_LDA(dst, b, h) do { _Pragma("unroll") for (int m = 0; m < 4; ++m) _Pragma("unroll") for (int k = 0; k < 2; ++k) dst[m][k] = *(const LAS bf16x8*)(lds + PG8_SA(b, h) + aoff + m * 2048 + k * 1024); } while (0)
; #define PG8_MMA(ai, bj, At, Bt) do { __builtin_amdgcn_s_setprio(1); _Pragma("unroll") for (int m = 0; m < 4; ++m) _Pragma("unroll") for (int n = 0; n < 2; ++n) _Pragma("unroll") for (int k = 0; k < 2; ++k) \
;         acc[ai][bj][m][n] = __builtin_amdgcn_mfma_f32_16x16x32_bf16(Bt[n][k], At[m][k], acc[ai][bj][m][n], 0, 0, 0); __builtin_amdgcn_s_setprio(0); } while (0)
; #define PG8_WAIT_V(n) asm volatile("s_waitcnt vmcnt(" #n ")" ::: "memory")
; #define PG8_WAIT_L(n) asm volatile("s_waitcnt lgkmcnt(" #n ")" ::: "memory")
; #define PG8_BAR __builtin_amdgcn_s_barrier()
; #define PG8_SCHED __builtin_amdgcn_sched_barrier(0)
; template <class Epi>
; __device__ __forceinline__ void gemm_phase(LAS unsigned char* lds, int wave_s, const Gemm g, const StaticOrder S, const Epi E) {
;     ...
;             PG8_WAIT_V(8); PG8_WAIT_L(0); PG8_BAR; PG8_MMA(0, 0, At, B0); PG8_MMA(0, 1, At, B1); PG8_BAR; PG8_SCHED;
;             PG8_LDA(At, 1, 1); PG8_STAGE(PG8_SB(1, 0), b3, voffB); PG8_STAGE(PG8_SB(1, 1), b3 + hstepB, voffB); PG8_STAGE(PG8_SA(1, 0), a3, voffA);
;             PG8_WAIT_V(8); PG8_WAIT_L(0); PG8_BAR; PG8_MMA(1, 0, At, B0); PG8_MMA(1, 1, At, B1); PG8_BAR; PG8_SCHED;
;         }
;         if (wr == 0) PG8_BAR;
	s_setprio 1
	s_waitcnt lgkmcnt(0)
	v_mfma_f32_16x16x32_bf16 v[126:129], v[142:145], v[178:181], v[126:129]
	v_mfma_f32_16x16x32_bf16 v[122:125], v[150:153], v[178:181], v[122:125]
	v_mfma_f32_16x16x32_bf16 v[110:113], v[142:145], v[186:189], v[110:113]
	v_mfma_f32_16x16x32_bf16 v[106:109], v[150:153], v[186:189], v[106:109]
	v_mfma_f32_16x16x32_bf16 v[94:97], v[142:145], v[206:209], v[94:97]
	v_mfma_f32_16x16x32_bf16 v[90:93], v[150:153], v[206:209], v[90:93]
	v_mfma_f32_16x16x32_bf16 v[78:81], v[142:145], v[214:217], v[78:81]
	v_mfma_f32_16x16x32_bf16 v[74:77], v[150:153], v[214:217], v[74:77]
	v_mfma_f32_16x16x32_bf16 v[126:129], v[146:149], v[182:185], v[126:129]
	v_mfma_f32_16x16x32_bf16 v[122:125], v[158:161], v[182:185], v[122:125]
	v_mfma_f32_16x16x32_bf16 v[110:113], v[146:149], v[190:193], v[110:113]
	v_mfma_f32_16x16x32_bf16 v[106:109], v[158:161], v[190:193], v[106:109]
	v_mfma_f32_16x16x32_bf16 v[94:97], v[146:149], v[210:213], v[94:97]
	v_mfma_f32_16x16x32_bf16 v[90:93], v[158:161], v[210:213], v[90:93]
	v_mfma_f32_16x16x32_bf16 v[78:81], v[146:149], v[218:221], v[78:81]
	v_mfma_f32_16x16x32_bf16 v[74:77], v[158:161], v[218:221], v[74:77]
	s_setprio 0
	s_setprio 1
	v_mfma_f32_16x16x32_bf16 v[118:121], v[162:165], v[178:181], v[118:121]
	v_mfma_f32_16x16x32_bf16 v[114:117], v[170:173], v[178:181], v[114:117]
	v_mfma_f32_16x16x32_bf16 v[102:105], v[162:165], v[186:189], v[102:105]
	v_mfma_f32_16x16x32_bf16 v[98:101], v[170:173], v[186:189], v[98:101]
	v_mfma_f32_16x16x32_bf16 v[86:89], v[162:165], v[206:209], v[86:89]
	v_mfma_f32_16x16x32_bf16 v[82:85], v[170:173], v[206:209], v[82:85]
	v_mfma_f32_16x16x32_bf16 v[70:73], v[162:165], v[214:217], v[70:73]
	v_mfma_f32_16x16x32_bf16 v[66:69], v[170:173], v[214:217], v[66:69]
	v_mfma_f32_16x16x32_bf16 v[118:121], v[166:169], v[182:185], v[118:121]
	v_mfma_f32_16x16x32_bf16 v[114:117], v[174:177], v[182:185], v[114:117]
	v_mfma_f32_16x16x32_bf16 v[102:105], v[166:169], v[190:193], v[102:105]
	v_mfma_f32_16x16x32_bf16 v[98:101], v[174:177], v[190:193], v[98:101]
	v_mfma_f32_16x16x32_bf16 v[86:89], v[166:169], v[210:213], v[86:89]
	v_mfma_f32_16x16x32_bf16 v[82:85], v[174:177], v[210:213], v[82:85]
	v_mfma_f32_16x16x32_bf16 v[70:73], v[166:169], v[218:221], v[70:73]
	v_mfma_f32_16x16x32_bf16 v[66:69], v[174:177], v[218:221], v[66:69]
	s_setprio 0
	s_barrier
	s_add_i32 s6, s35, s18
	v_lshl_add_u64 v[194:195], v[194:195], 0, s[8:9]
	s_mov_b32 m0, s6
	ds_read_b128 v[178:181], v157 offset:49152
	ds_read_b128 v[182:185], v157 offset:50176
	ds_read_b128 v[186:189], v157 offset:51200
	ds_read_b128 v[190:193], v157 offset:52224
	ds_read_b128 v[206:209], v157 offset:53248
	ds_read_b128 v[210:213], v157 offset:54272
	ds_read_b128 v[214:217], v157 offset:55296
	ds_read_b128 v[218:221], v157 offset:56320
	global_load_lds_dwordx4 v[194:195], off
	s_add_i32 m0, s6, 0x2000
	s_add_u32 s6, s14, 0x40080
	v_lshl_add_u64 v[194:195], v[196:197], 0, s[8:9]
	s_addc_u32 s7, s15, 0
	s_add_i32 s14, s37, s18
	global_load_lds_dwordx4 v[194:195], off
	v_lshl_add_u64 v[194:195], s[6:7], 0, v[0:1]
	s_mov_b32 m0, s14
	s_nop 0
	global_load_lds_dwordx4 v[194:195], off
	v_lshl_add_u64 v[194:195], s[6:7], 0, v[130:131]
	s_add_i32 m0, s14, 0x2000
	s_nop 0
	global_load_lds_dwordx4 v[194:195], off
	v_lshl_add_u64 v[194:195], v[198:199], 0, s[8:9]
	s_mov_b32 m0, s23
	s_nop 0
	global_load_lds_dwordx4 v[194:195], off
	v_lshl_add_u64 v[194:195], v[200:201], 0, s[8:9]
	s_mov_b32 m0, s24
	s_nop 0
	global_load_lds_dwordx4 v[194:195], off
	s_waitcnt vmcnt(8)
	s_waitcnt lgkmcnt(0)
	s_barrier
	s_setprio 1
	s_waitcnt lgkmcnt(0)
	v_mfma_f32_16x16x32_bf16 v[62:65], v[142:145], v[178:181], v[62:65]
	v_mfma_f32_16x16x32_bf16 v[58:61], v[150:153], v[178:181], v[58:61]
	v_mfma_f32_16x16x32_bf16 v[46:49], v[142:145], v[186:189], v[46:49]
	v_mfma_f32_16x16x32_bf16 v[42:45], v[150:153], v[186:189], v[42:45]
	v_mfma_f32_16x16x32_bf16 v[30:33], v[142:145], v[206:209], v[30:33]
	v_mfma_f32_16x16x32_bf16 v[26:29], v[150:153], v[206:209], v[26:29]
	v_mfma_f32_16x16x32_bf16 v[14:17], v[142:145], v[214:217], v[14:17]
	v_mfma_f32_16x16x32_bf16 v[10:13], v[150:153], v[214:217], v[10:13]
	v_mfma_f32_16x16x32_bf16 v[62:65], v[146:149], v[182:185], v[62:65]
	v_mfma_f32_16x16x32_bf16 v[58:61], v[158:161], v[182:185], v[58:61]
	v_mfma_f32_16x16x32_bf16 v[46:49], v[146:149], v[190:193], v[46:49]
	v_mfma_f32_16x16x32_bf16 v[42:45], v[158:161], v[190:193], v[42:45]
	v_mfma_f32_16x16x32_bf16 v[30:33], v[146:149], v[210:213], v[30:33]
	v_mfma_f32_16x16x32_bf16 v[26:29], v[158:161], v[210:213], v[26:29]
	v_mfma_f32_16x16x32_bf16 v[14:17], v[146:149], v[218:221], v[14:17]
	v_mfma_f32_16x16x32_bf16 v[10:13], v[158:161], v[218:221], v[10:13]
	s_setprio 0
	s_setprio 1
	v_mfma_f32_16x16x32_bf16 v[54:57], v[162:165], v[178:181], v[54:57]
	v_mfma_f32_16x16x32_bf16 v[50:53], v[170:173], v[178:181], v[50:53]
	v_mfma_f32_16x16x32_bf16 v[38:41], v[162:165], v[186:189], v[38:41]
	v_mfma_f32_16x16x32_bf16 v[34:37], v[170:173], v[186:189], v[34:37]
	v_mfma_f32_16x16x32_bf16 v[22:25], v[162:165], v[206:209], v[22:25]
	v_mfma_f32_16x16x32_bf16 v[18:21], v[170:173], v[206:209], v[18:21]
	v_mfma_f32_16x16x32_bf16 v[6:9], v[162:165], v[214:217], v[6:9]
	v_mfma_f32_16x16x32_bf16 v[2:5], v[170:173], v[214:217], v[2:5]
	v_mfma_f32_16x16x32_bf16 v[54:57], v[166:169], v[182:185], v[54:57]
	v_mfma_f32_16x16x32_bf16 v[50:53], v[174:177], v[182:185], v[50:53]
	v_mfma_f32_16x16x32_bf16 v[38:41], v[166:169], v[190:193], v[38:41]
	v_mfma_f32_16x16x32_bf16 v[34:37], v[174:177], v[190:193], v[34:37]
	v_mfma_f32_16x16x32_bf16 v[22:25], v[166:169], v[210:213], v[22:25]
	v_mfma_f32_16x16x32_bf16 v[18:21], v[174:177], v[210:213], v[18:21]
	v_mfma_f32_16x16x32_bf16 v[6:9], v[166:169], v[218:221], v[6:9]
	v_mfma_f32_16x16x32_bf16 v[2:5], v[174:177], v[218:221], v[2:5]
	s_setprio 0
	s_barrier
	s_add_i32 s34, s34, 2
	s_add_u32 s12, s12, 0x100
	s_addc_u32 s13, s13, 0
	s_add_u32 s30, s30, 0x100
	s_addc_u32 s31, s31, 0
	s_cmp_gt_u32 s34, 13
	s_cbranch_scc0 .LBB0_1335
	s_and_b64 vcc, exec, s[38:39]
	s_cbranch_vccz .LBB0_1338
	s_barrier

; #define PG8_BAR __builtin_amdgcn_s_barrier()
; template <class Epi>
; __device__ __forceinline__ void gemm_phase(LAS unsigned char* lds, int wave_s, const Gemm g, const StaticOrder S, const Epi E) {
;     ...
;         if (!has_next) break;
; #pragma unroll
;         for (int a = 0; a < 2; ++a)
; #pragma unroll
;             for (int b = 0; b < 2; ++b)
; #pragma unroll
;                 for (int m = 0; m < 4; ++m)
; #pragma unroll
;                     for (int n = 0; n < 2; ++n) acc[a][b][m][n] = (f32x4){0.f, 0.f, 0.f, 0.f};
;         cur = nxt; cA = nA; cB = nB; ++ui;
;         if (wr == 1) PG8_BAR;
;     __device__ __forceinline__ void operator()(const f32x4 (&acc)[2][2][4][2], const Unit& u, int wr, int wc, int fr, int fq) const {
;     ...
;                 sq += __shfl_xor(sq, 16); sq += __shfl_xor(sq, 32);
;                 if (fq == 0) ssq_out[(size_t)row * 16 + 4 * u.pn + wc] = sq;
.LBB0_1354:
	s_or_b64 exec, exec, s[12:13]
	s_andn2_b64 vcc, exec, s[42:43]
	s_mov_b64 s[12:13], -1
	s_cbranch_vccnz .LBB0_1327
	v_readlane_b32 s6, v254, 18
	v_readlane_b32 s7, v254, 19
	s_andn2_b64 vcc, exec, s[6:7]
	s_cbranch_vccnz .LBB0_1326
	s_mov_b32 s99, 0x13579bdf
	s_branch .LBB0_1326
